# FFN1 epilogue: -log2e/-ln2 folded into staged conv parameters, 64 v_mul per lane-tile removed
# speedup vs baseline: 1.0040x; 1.0040x over previous
; #define LAS __attribute__((address_space(3)))
; __device__ __forceinline__ float sigmoidf_(float x) { return __builtin_amdgcn_rcpf(1.0f + __expf(-x)); }
;     __device__ __forceinline__ void operator()(AccRef acc, const Unit& u, int wr, int wc, int fr, int fq) const {
;     ...
;                 f32x4 h2v = (f32x4){0.f, 0.f, 0.f, 0.f}, h3v = h2v, h2g = h2v, h3g = h2v;
;                 const int pb = ai * 2 + wr - 1;
;                 if (pb >= 0 && fr == 0) { const LAS float* xp = xch + (pb * 2) * 256 + clb + 4 * n;
;                     h2v = *(const LAS f32x4*)(xp); h3v = *(const LAS f32x4*)(xp + 256); h2g = *(const LAS f32x4*)(xp + 128); h3g = *(const LAS f32x4*)(xp + 256 + 128); }
;                 float o[4][4];
; #pragma unroll
;                 for (int j = 0; j < 4; ++j) {
;                     const float v0 = acc[ai][0][0][n][j], v1 = acc[ai][0][1][n][j], v2 = acc[ai][0][2][n][j], v3 = acc[ai][0][3][n][j];
;                     const float g0 = acc[ai][1][0][n][j], g1 = acc[ai][1][1][n][j], g2 = acc[ai][1][2][n][j], g3 = acc[ai][1][3][n][j];
;                     const float pv3 = dpp_upd<0x111>(h3v[j], v3), pv2 = dpp_upd<0x111>(h2v[j], v2), pg3 = dpp_upd<0x111>(h3g[j], g3), pg2 = dpp_upd<0x111>(h2g[j], g2);
;                     const float hv0 = bvv[j] + w2v[j] * v0 + w1v[j] * pv3 + w0v[j] * pv2, hv1 = bvv[j] + w2v[j] * v1 + w1v[j] * v0 + w0v[j] * pv3;
;                     const float hv2 = bvv[j] + w2v[j] * v2 + w1v[j] * v1 + w0v[j] * v0, hv3 = bvv[j] + w2v[j] * v3 + w1v[j] * v2 + w0v[j] * v1;
;                     const float hg0 = bvg[j] + w2g[j] * g0 + w1g[j] * pg3 + w0g[j] * pg2, hg1 = bvg[j] + w2g[j] * g1 + w1g[j] * g0 + w0g[j] * pg3;
;                     const float hg2 = bvg[j] + w2g[j] * g2 + w1g[j] * g1 + w0g[j] * g0, hg3 = bvg[j] + w2g[j] * g3 + w1g[j] * g2 + w0g[j] * g1;
;                     o[0][j] = hg0 * sigmoidf_(hg0) * hv0; o[1][j] = hg1 * sigmoidf_(hg1) * hv1; o[2][j] = hg2 * sigmoidf_(hg2) * hv2; o[3][j] = hg3 * sigmoidf_(hg3) * hv3; }
; #pragma unroll
;                 for (int m = 0; m < 4; ++m) { u32x2 w; w.x = cvt_pk_bf16(o[m][0], o[m][1]); w.y = cvt_pk_bf16(o[m][2], o[m][3]);
;                     *(u32x2*)(Aout + (size_t)(row0 + ai * 128 + m) * FH + hc0 + 4 * n) = w; } } }
.LBB0_305:
	s_or_b64 exec, exec, s[34:35]
	s_waitcnt lgkmcnt(0)
	v_mov_b32_dpp v64, v8 row_shr:1 row_mask:0xf bank_mask:0xf
	v_mov_b32_dpp v65, v9 row_shr:1 row_mask:0xf bank_mask:0xf
	v_pk_fma_f32 v[44:45], v[24:25], v[120:121], v[124:125]
	v_mov_b32_dpp v40, v0 row_shr:1 row_mask:0xf bank_mask:0xf
	v_mov_b32_dpp v41, v1 row_shr:1 row_mask:0xf bank_mask:0xf
	v_pk_fma_f32 v[44:45], v[116:117], v[64:65], v[44:45]
	v_mov_b32_dpp v32, v20 row_shr:1 row_mask:0xf bank_mask:0xf
	v_pk_fma_f32 v[40:41], v[112:113], v[40:41], v[44:45]
	v_mov_b32_dpp v33, v21 row_shr:1 row_mask:0xf bank_mask:0xf
	v_exp_f32_e32 v44, v40
	v_exp_f32_e32 v45, v41
	v_pk_fma_f32 v[46:47], v[28:29], v[104:105], v[108:109]
	v_mov_b32_dpp v36, v12 row_shr:1 row_mask:0xf bank_mask:0xf
	v_add_f32_e32 v44, 1.0, v44
	v_add_f32_e32 v45, 1.0, v45
	v_rcp_f32_e32 v44, v44
	v_rcp_f32_e32 v45, v45
	v_mov_b32_dpp v37, v13 row_shr:1 row_mask:0xf bank_mask:0xf
	v_pk_fma_f32 v[46:47], v[100:101], v[32:33], v[46:47]
	v_mov_b32_dpp v66, v10 row_shr:1 row_mask:0xf bank_mask:0xf
	v_pk_fma_f32 v[36:37], v[96:97], v[36:37], v[46:47]
	v_pk_mul_f32 v[40:41], v[40:41], v[44:45]
	v_mov_b32_dpp v67, v11 row_shr:1 row_mask:0xf bank_mask:0xf
	v_pk_mul_f32 v[36:37], v[36:37], v[40:41]
	v_pk_fma_f32 v[40:41], v[26:27], v[122:123], v[126:127]
	v_mov_b32_dpp v42, v2 row_shr:1 row_mask:0xf bank_mask:0xf
	v_mov_b32_dpp v43, v3 row_shr:1 row_mask:0xf bank_mask:0xf
	v_pk_fma_f32 v[40:41], v[118:119], v[66:67], v[40:41]
	v_cvt_pk_bf16_f32 v36, v36, v37
	v_pk_fma_f32 v[40:41], v[114:115], v[42:43], v[40:41]
	v_mov_b32_dpp v34, v22 row_shr:1 row_mask:0xf bank_mask:0xf
	v_exp_f32_e32 v42, v40
	v_exp_f32_e32 v43, v41
	v_mov_b32_dpp v35, v23 row_shr:1 row_mask:0xf bank_mask:0xf
	v_add_f32_e32 v37, 1.0, v42
	v_rcp_f32_e32 v42, v37
	v_add_f32_e32 v37, 1.0, v43
	v_rcp_f32_e32 v43, v37
	v_pk_fma_f32 v[44:45], v[30:31], v[106:107], v[110:111]
	v_mov_b32_dpp v38, v14 row_shr:1 row_mask:0xf bank_mask:0xf
	v_mov_b32_dpp v39, v15 row_shr:1 row_mask:0xf bank_mask:0xf
	v_pk_fma_f32 v[44:45], v[102:103], v[34:35], v[44:45]
	v_pk_mul_f32 v[40:41], v[40:41], v[42:43]
	v_pk_fma_f32 v[38:39], v[98:99], v[38:39], v[44:45]
	v_pk_fma_f32 v[8:9], v[8:9], v[120:121], v[124:125]
	v_pk_mul_f32 v[38:39], v[38:39], v[40:41]
	v_pk_fma_f32 v[20:21], v[20:21], v[104:105], v[108:109]
	v_cvt_pk_bf16_f32 v37, v38, v39
	v_pk_fma_f32 v[38:39], v[4:5], v[120:121], v[124:125]
	v_mov_b32_e32 v146, v36
	v_mov_b32_e32 v147, v37
	global_store_dwordx4 v[132:133], v[144:147], off
	v_pk_fma_f32 v[38:39], v[24:25], v[116:117], v[38:39]
	s_and_b64 vcc, exec, s[12:13]
	v_pk_fma_f32 v[38:39], v[112:113], v[64:65], v[38:39]
	s_mov_b32 s35, s24
	v_exp_f32_e32 v40, v38
	v_exp_f32_e32 v41, v39
	s_mov_b32 s34, s26
	s_mov_b64 s[38:39], s[30:31]
	v_add_f32_e32 v36, 1.0, v40
	v_add_f32_e32 v37, 1.0, v41
	v_rcp_f32_e32 v36, v36
	v_rcp_f32_e32 v37, v37
	v_pk_fma_f32 v[40:41], v[16:17], v[104:105], v[108:109]
	s_mov_b64 s[36:37], s[28:29]
	v_pk_fma_f32 v[40:41], v[28:29], v[100:101], v[40:41]
	v_pk_mul_f32 v[36:37], v[38:39], v[36:37]
	v_pk_fma_f32 v[32:33], v[96:97], v[32:33], v[40:41]
	v_pk_fma_f32 v[40:41], v[18:19], v[106:107], v[110:111]
	v_pk_mul_f32 v[32:33], v[32:33], v[36:37]
	v_pk_fma_f32 v[36:37], v[6:7], v[122:123], v[126:127]
	v_cvt_pk_bf16_f32 v32, v32, v33
	v_pk_fma_f32 v[36:37], v[26:27], v[118:119], v[36:37]
	v_pk_fma_f32 v[40:41], v[30:31], v[102:103], v[40:41]
	v_pk_fma_f32 v[36:37], v[114:115], v[66:67], v[36:37]
	v_pk_fma_f32 v[34:35], v[98:99], v[34:35], v[40:41]
	v_exp_f32_e32 v38, v36
	v_exp_f32_e32 v39, v37
	v_add_f32_e32 v33, 1.0, v38
	v_rcp_f32_e32 v38, v33
	v_add_f32_e32 v33, 1.0, v39
	v_rcp_f32_e32 v39, v33
	s_nop 0
	v_pk_mul_f32 v[36:37], v[36:37], v[38:39]
	s_nop 0
	v_pk_mul_f32 v[34:35], v[34:35], v[36:37]
	s_nop 0
	v_cvt_pk_bf16_f32 v33, v34, v35
	v_pk_fma_f32 v[34:35], v[0:1], v[120:121], v[124:125]
	v_mov_b32_e32 v156, v32
	v_mov_b32_e32 v157, v33
	global_store_dwordx4 v[128:129], v[154:157], off
	v_pk_fma_f32 v[34:35], v[4:5], v[116:117], v[34:35]
	v_pk_fma_f32 v[0:1], v[0:1], v[116:117], v[8:9]
	v_pk_fma_f32 v[24:25], v[24:25], v[112:113], v[34:35]
	v_pk_fma_f32 v[0:1], v[4:5], v[112:113], v[0:1]
	v_exp_f32_e32 v34, v24
	v_exp_f32_e32 v35, v25
	v_exp_f32_e32 v8, v0
	v_add_f32_e32 v32, 1.0, v34
	v_add_f32_e32 v33, 1.0, v35
	v_rcp_f32_e32 v32, v32
	v_rcp_f32_e32 v33, v33
	v_pk_fma_f32 v[34:35], v[12:13], v[104:105], v[108:109]
	v_pk_fma_f32 v[4:5], v[10:11], v[122:123], v[126:127]
	v_pk_fma_f32 v[34:35], v[16:17], v[100:101], v[34:35]
	v_pk_mul_f32 v[24:25], v[24:25], v[32:33]
	v_pk_fma_f32 v[28:29], v[28:29], v[96:97], v[34:35]
	v_pk_mul_f32 v[24:25], v[28:29], v[24:25]
	v_pk_fma_f32 v[28:29], v[2:3], v[122:123], v[126:127]
	v_pk_fma_f32 v[2:3], v[2:3], v[118:119], v[4:5]
	v_pk_fma_f32 v[28:29], v[6:7], v[118:119], v[28:29]
	v_pk_fma_f32 v[2:3], v[6:7], v[114:115], v[2:3]
	v_pk_fma_f32 v[26:27], v[26:27], v[114:115], v[28:29]
	v_exp_f32_e32 v28, v26
	v_exp_f32_e32 v29, v27
	v_exp_f32_e32 v9, v1
	v_exp_f32_e32 v4, v2
	v_exp_f32_e32 v5, v3
	v_cvt_pk_bf16_f32 v24, v24, v25
	v_add_f32_e32 v25, 1.0, v28
	v_rcp_f32_e32 v28, v25
	v_add_f32_e32 v25, 1.0, v29
	v_add_f32_e32 v8, 1.0, v8
	v_add_f32_e32 v9, 1.0, v9
	v_add_f32_e32 v4, 1.0, v4
	v_add_f32_e32 v5, 1.0, v5
	v_rcp_f32_e32 v29, v25
	v_rcp_f32_e32 v8, v8
	v_rcp_f32_e32 v9, v9
	v_rcp_f32_e32 v4, v4
	v_rcp_f32_e32 v5, v5
	v_pk_fma_f32 v[32:33], v[14:15], v[106:107], v[110:111]
	v_pk_fma_f32 v[10:11], v[22:23], v[106:107], v[110:111]
	v_pk_fma_f32 v[32:33], v[18:19], v[102:103], v[32:33]
	v_pk_fma_f32 v[12:13], v[12:13], v[100:101], v[20:21]
	v_pk_fma_f32 v[6:7], v[14:15], v[102:103], v[10:11]
	v_pk_fma_f32 v[30:31], v[30:31], v[98:99], v[32:33]
	v_pk_mul_f32 v[26:27], v[26:27], v[28:29]
	v_pk_fma_f32 v[12:13], v[16:17], v[96:97], v[12:13]
	v_pk_mul_f32 v[0:1], v[0:1], v[8:9]
	v_pk_fma_f32 v[6:7], v[18:19], v[98:99], v[6:7]
	v_pk_mul_f32 v[2:3], v[2:3], v[4:5]
	v_pk_mul_f32 v[26:27], v[30:31], v[26:27]
	v_pk_mul_f32 v[0:1], v[12:13], v[0:1]
	v_pk_mul_f32 v[2:3], v[6:7], v[2:3]
	v_cvt_pk_bf16_f32 v25, v26, v27
	v_cvt_pk_bf16_f32 v0, v0, v1
	v_cvt_pk_bf16_f32 v1, v2, v3
	v_mov_b32_e32 v200, v24
	v_mov_b32_e32 v201, v25
	global_store_dwordx4 v[88:89], v[198:201], off
	v_mov_b32_e32 v150, v0
	v_mov_b32_e32 v151, v1
	global_store_dwordx4 v[82:83], v[148:151], off
	s_cbranch_vccnz .LBB0_324

;     __device__ __forceinline__ void operator()(AccRef acc, const Unit& u, int wr, int wc, int fr, int fq) const {
;     ...
;         { const float* cv = cw + 128 * u.pn + clb; const float* cg = cv + FH; const float* bp = cb + 128 * u.pn + clb;
;           cwv[0][0] = *(const f32x4*)(cv); cwv[0][1] = *(const f32x4*)(cv + F2); cwv[0][2] = *(const f32x4*)(cv + 2 * F2); cwv[0][3] = *(const f32x4*)(bp);
;           cwv[0][4] = *(const f32x4*)(cg); cwv[0][5] = *(const f32x4*)(cg + F2); cwv[0][6] = *(const f32x4*)(cg + 2 * F2); cwv[0][7] = *(const f32x4*)(bp + FH); }
;     ...
;                     const float* cv = cw + hc0 + 4; const float* cg = cv + FH; const float* bp = cb + hc0 + 4;
;                     cwv[1][0] = *(const f32x4*)(cv); cwv[1][1] = *(const f32x4*)(cv + F2); cwv[1][2] = *(const f32x4*)(cv + 2 * F2); cwv[1][3] = *(const f32x4*)(bp);
;                     cwv[1][4] = *(const f32x4*)(cg); cwv[1][5] = *(const f32x4*)(cg + F2); cwv[1][6] = *(const f32x4*)(cg + 2 * F2); cwv[1][7] = *(const f32x4*)(bp + FH);
.LBB0_318:
	s_or_b64 exec, exec, s[36:37]
	s_waitcnt lgkmcnt(0)
	v_mov_b32_dpp v198, v140 row_shr:1 row_mask:0xf bank_mask:0xf
	v_mov_b32_dpp v199, v141 row_shr:1 row_mask:0xf bank_mask:0xf
	s_waitcnt vmcnt(0)
	s_bitcmp1_b32 s99, 8
	s_cbranch_scc1 .Lcw309_nostage
	v_and_b32_e32 v107, 0xff, v219
	v_lshlrev_b32_e32 v107, 4, v107
	v_add_u32_e32 v107, 0x22000, v107
	v_and_b32_e32 v104, 4, v219
	v_cmp_ne_u32_e64 s[100:101], 0, v104
	v_mov_b32_e32 v104, 0xbf317218
	v_mov_b32_e32 v105, 0xbfb8aa3b
	s_nop 0
	v_cndmask_b32_e64 v104, v104, v105, s[100:101]
	v_mov_b32_e32 v105, v104
	v_pk_mul_f32 v[108:109], v[108:109], v[104:105]
	v_pk_mul_f32 v[110:111], v[110:111], v[104:105]
	ds_write_b128 v107, v[108:111]

; #define LAS __attribute__((address_space(3)))
; __device__ __forceinline__ float sigmoidf_(float x) { return __builtin_amdgcn_rcpf(1.0f + __expf(-x)); }
;     __device__ __forceinline__ void operator()(AccRef acc, const Unit& u, int wr, int wc, int fr, int fq) const {
;     ...
;                 f32x4 h2v = (f32x4){0.f, 0.f, 0.f, 0.f}, h3v = h2v, h2g = h2v, h3g = h2v;
;                 const int pb = ai * 2 + wr - 1;
;                 if (pb >= 0 && fr == 0) { const LAS float* xp = xch + (pb * 2) * 256 + clb + 4 * n;
;                     h2v = *(const LAS f32x4*)(xp); h3v = *(const LAS f32x4*)(xp + 256); h2g = *(const LAS f32x4*)(xp + 128); h3g = *(const LAS f32x4*)(xp + 256 + 128); }
;                 float o[4][4];
; #pragma unroll
;                 for (int j = 0; j < 4; ++j) {
;                     const float v0 = acc[ai][0][0][n][j], v1 = acc[ai][0][1][n][j], v2 = acc[ai][0][2][n][j], v3 = acc[ai][0][3][n][j];
;                     const float g0 = acc[ai][1][0][n][j], g1 = acc[ai][1][1][n][j], g2 = acc[ai][1][2][n][j], g3 = acc[ai][1][3][n][j];
;                     const float pv3 = dpp_upd<0x111>(h3v[j], v3), pv2 = dpp_upd<0x111>(h2v[j], v2), pg3 = dpp_upd<0x111>(h3g[j], g3), pg2 = dpp_upd<0x111>(h2g[j], g2);
;                     const float hv0 = bvv[j] + w2v[j] * v0 + w1v[j] * pv3 + w0v[j] * pv2, hv1 = bvv[j] + w2v[j] * v1 + w1v[j] * v0 + w0v[j] * pv3;
;                     const float hv2 = bvv[j] + w2v[j] * v2 + w1v[j] * v1 + w0v[j] * v0, hv3 = bvv[j] + w2v[j] * v3 + w1v[j] * v2 + w0v[j] * v1;
;                     const float hg0 = bvg[j] + w2g[j] * g0 + w1g[j] * pg3 + w0g[j] * pg2, hg1 = bvg[j] + w2g[j] * g1 + w1g[j] * g0 + w0g[j] * pg3;
;                     const float hg2 = bvg[j] + w2g[j] * g2 + w1g[j] * g1 + w0g[j] * g0, hg3 = bvg[j] + w2g[j] * g3 + w1g[j] * g2 + w0g[j] * g1;
;                     o[0][j] = hg0 * sigmoidf_(hg0) * hv0; o[1][j] = hg1 * sigmoidf_(hg1) * hv1; o[2][j] = hg2 * sigmoidf_(hg2) * hv2; o[3][j] = hg3 * sigmoidf_(hg3) * hv3; }
; #pragma unroll
;                 for (int m = 0; m < 4; ++m) { u32x2 w; w.x = cvt_pk_bf16(o[m][0], o[m][1]); w.y = cvt_pk_bf16(o[m][2], o[m][3]);
;                     *(u32x2*)(Aout + (size_t)(row0 + ai * 128 + m) * FH + hc0 + 4 * n) = w; } } }
.LBB0_316:
	s_or_b64 exec, exec, s[40:41]
	v_pk_fma_f32 v[248:249], v[152:153], v[184:185], v[188:189]
	v_mov_b32_dpp v206, v128 row_shr:1 row_mask:0xf bank_mask:0xf
	v_mov_b32_dpp v207, v129 row_shr:1 row_mask:0xf bank_mask:0xf
	v_pk_fma_f32 v[248:249], v[180:181], v[198:199], v[248:249]
	v_mov_b32_dpp v194, v148 row_shr:1 row_mask:0xf bank_mask:0xf
	v_pk_fma_f32 v[206:207], v[176:177], v[206:207], v[248:249]
	v_mov_b32_dpp v195, v149 row_shr:1 row_mask:0xf bank_mask:0xf
	v_exp_f32_e32 v193, v206
	v_exp_f32_e32 v247, v207
	v_pk_fma_f32 v[250:251], v[156:157], v[168:169], v[172:173]
	v_add_f32_e32 v193, 1.0, v193
	v_rcp_f32_e32 v248, v193
	v_add_f32_e32 v193, 1.0, v247
	v_rcp_f32_e32 v249, v193
	v_mov_b32_dpp v202, v136 row_shr:1 row_mask:0xf bank_mask:0xf
	v_mov_b32_dpp v203, v137 row_shr:1 row_mask:0xf bank_mask:0xf
	v_pk_fma_f32 v[250:251], v[164:165], v[194:195], v[250:251]
	v_pk_mul_f32 v[206:207], v[206:207], v[248:249]
	v_pk_fma_f32 v[202:203], v[160:161], v[202:203], v[250:251]
	v_mov_b32_dpp v200, v142 row_shr:1 row_mask:0xf bank_mask:0xf
	v_mov_b32_dpp v201, v143 row_shr:1 row_mask:0xf bank_mask:0xf
	v_pk_mul_f32 v[202:203], v[202:203], v[206:207]
	v_pk_fma_f32 v[206:207], v[154:155], v[186:187], v[190:191]
	v_mov_b32_dpp v208, v130 row_shr:1 row_mask:0xf bank_mask:0xf
	v_mov_b32_dpp v209, v131 row_shr:1 row_mask:0xf bank_mask:0xf
	v_pk_fma_f32 v[206:207], v[182:183], v[200:201], v[206:207]
	v_mov_b32_dpp v196, v150 row_shr:1 row_mask:0xf bank_mask:0xf
	v_pk_fma_f32 v[206:207], v[178:179], v[208:209], v[206:207]
	v_mov_b32_dpp v197, v151 row_shr:1 row_mask:0xf bank_mask:0xf
	v_exp_f32_e32 v193, v206
	v_exp_f32_e32 v209, v207
	v_cvt_pk_bf16_f32 v208, v202, v203
	v_add_f32_e32 v193, 1.0, v193
	v_rcp_f32_e32 v202, v193
	v_add_f32_e32 v193, 1.0, v209
	v_rcp_f32_e32 v203, v193
	v_pk_fma_f32 v[248:249], v[158:159], v[170:171], v[174:175]
	v_mov_b32_dpp v204, v138 row_shr:1 row_mask:0xf bank_mask:0xf
	v_mov_b32_dpp v205, v139 row_shr:1 row_mask:0xf bank_mask:0xf
	v_pk_fma_f32 v[248:249], v[166:167], v[196:197], v[248:249]
	v_pk_mul_f32 v[202:203], v[206:207], v[202:203]
	v_pk_fma_f32 v[204:205], v[162:163], v[204:205], v[248:249]
	v_lshl_add_u32 v246, s34, 8, v236
	v_pk_mul_f32 v[202:203], v[204:205], v[202:203]
	v_lshlrev_b64 v[204:205], 1, v[232:233]
	v_pk_fma_f32 v[232:233], v[132:133], v[184:185], v[188:189]
	v_mov_b64_e32 v[206:207], s[60:61]
	v_pk_fma_f32 v[232:233], v[152:153], v[180:181], v[232:233]
	v_cvt_pk_bf16_f32 v209, v202, v203
	v_pk_fma_f32 v[198:199], v[176:177], v[198:199], v[232:233]
	v_mad_i64_i32 v[202:203], s[34:35], v246, s74, v[206:207]
	v_exp_f32_e32 v193, v198
	v_exp_f32_e32 v232, v199
	v_lshl_add_u64 v[202:203], v[202:203], 0, v[204:205]
	v_add_f32_e32 v193, 1.0, v193
	v_mov_b32_e32 v247, v208
	v_mov_b32_e32 v248, v209
	v_rcp_f32_e32 v208, v193
	v_add_f32_e32 v193, 1.0, v232
	v_rcp_f32_e32 v209, v193
	v_pk_fma_f32 v[232:233], v[144:145], v[168:169], v[172:173]
	v_pk_fma_f32 v[140:141], v[140:141], v[184:185], v[188:189]
	v_pk_fma_f32 v[232:233], v[156:157], v[164:165], v[232:233]
	v_pk_mul_f32 v[198:199], v[198:199], v[208:209]
	v_pk_fma_f32 v[194:195], v[160:161], v[194:195], v[232:233]
	v_pk_fma_f32 v[208:209], v[146:147], v[170:171], v[174:175]
	v_pk_mul_f32 v[194:195], v[194:195], v[198:199]
	v_pk_fma_f32 v[198:199], v[134:135], v[186:187], v[190:191]
	v_pk_fma_f32 v[208:209], v[158:159], v[166:167], v[208:209]
	v_pk_fma_f32 v[198:199], v[154:155], v[182:183], v[198:199]
	v_pk_fma_f32 v[196:197], v[162:163], v[196:197], v[208:209]
	v_pk_fma_f32 v[198:199], v[178:179], v[200:201], v[198:199]
	v_cvt_pk_bf16_f32 v194, v194, v195
	v_exp_f32_e32 v193, v198
	v_exp_f32_e32 v201, v199
	v_pk_fma_f32 v[148:149], v[148:149], v[168:169], v[172:173]
	v_add_f32_e32 v193, 1.0, v193
	v_rcp_f32_e32 v200, v193
	v_add_f32_e32 v193, 1.0, v201
	v_rcp_f32_e32 v201, v193
	v_or_b32_e32 v193, 1, v246
	v_pk_mul_f32 v[198:199], v[198:199], v[200:201]
	s_nop 0
	v_pk_mul_f32 v[196:197], v[196:197], v[198:199]
	v_pk_fma_f32 v[198:199], v[128:129], v[184:185], v[188:189]
	v_cvt_pk_bf16_f32 v195, v196, v197
	v_pk_fma_f32 v[198:199], v[132:133], v[180:181], v[198:199]
	v_mad_i64_i32 v[196:197], s[34:35], v193, s74, v[206:207]
	v_pk_fma_f32 v[152:153], v[152:153], v[176:177], v[198:199]
	v_lshl_add_u64 v[196:197], v[196:197], 0, v[204:205]
	v_exp_f32_e32 v193, v152
	v_exp_f32_e32 v198, v153
	v_mov_b32_e32 v249, v194
	v_mov_b32_e32 v250, v195
	v_add_f32_e32 v193, 1.0, v193
	v_rcp_f32_e32 v194, v193
	v_add_f32_e32 v193, 1.0, v198
	v_rcp_f32_e32 v195, v193
	v_pk_fma_f32 v[198:199], v[136:137], v[168:169], v[172:173]
	v_pk_fma_f32 v[128:129], v[128:129], v[180:181], v[140:141]
	v_pk_fma_f32 v[198:199], v[144:145], v[164:165], v[198:199]
	v_pk_fma_f32 v[128:129], v[132:133], v[176:177], v[128:129]
	v_pk_fma_f32 v[156:157], v[156:157], v[160:161], v[198:199]
	v_pk_mul_f32 v[152:153], v[152:153], v[194:195]
	v_pk_mul_f32 v[152:153], v[156:157], v[152:153]
	v_pk_fma_f32 v[156:157], v[130:131], v[186:187], v[190:191]
	v_exp_f32_e32 v140, v128
	v_pk_fma_f32 v[132:133], v[142:143], v[186:187], v[190:191]
	v_pk_fma_f32 v[156:157], v[134:135], v[182:183], v[156:157]
	v_pk_fma_f32 v[130:131], v[130:131], v[182:183], v[132:133]
	v_pk_fma_f32 v[154:155], v[154:155], v[178:179], v[156:157]
	v_pk_fma_f32 v[130:131], v[134:135], v[178:179], v[130:131]
	v_exp_f32_e32 v157, v154
	v_exp_f32_e32 v141, v129
	v_exp_f32_e32 v132, v130
	v_exp_f32_e32 v133, v131
	v_exp_f32_e32 v193, v155
	v_add_f32_e32 v140, 1.0, v140
	v_add_f32_e32 v141, 1.0, v141
	v_add_f32_e32 v132, 1.0, v132
	v_add_f32_e32 v133, 1.0, v133
	v_cvt_pk_bf16_f32 v156, v152, v153
	v_add_f32_e32 v152, 1.0, v157
; #define LAS __attribute__((address_space(3)))
; __device__ __forceinline__ float sigmoidf_(float x) { return __builtin_amdgcn_rcpf(1.0f + __expf(-x)); }
;     __device__ __forceinline__ void operator()(AccRef acc, const Unit& u, int wr, int wc, int fr, int fq) const {
;     ...
;                 f32x4 h2v = (f32x4){0.f, 0.f, 0.f, 0.f}, h3v = h2v, h2g = h2v, h3g = h2v;
;                 const int pb = ai * 2 + wr - 1;
;                 if (pb >= 0 && fr == 0) { const LAS float* xp = xch + (pb * 2) * 256 + clb + 4 * n;
;                     h2v = *(const LAS f32x4*)(xp); h3v = *(const LAS f32x4*)(xp + 256); h2g = *(const LAS f32x4*)(xp + 128); h3g = *(const LAS f32x4*)(xp + 256 + 128); }
;                 float o[4][4];
; #pragma unroll
;                 for (int j = 0; j < 4; ++j) {
;                     const float v0 = acc[ai][0][0][n][j], v1 = acc[ai][0][1][n][j], v2 = acc[ai][0][2][n][j], v3 = acc[ai][0][3][n][j];
;                     const float g0 = acc[ai][1][0][n][j], g1 = acc[ai][1][1][n][j], g2 = acc[ai][1][2][n][j], g3 = acc[ai][1][3][n][j];
;                     const float pv3 = dpp_upd<0x111>(h3v[j], v3), pv2 = dpp_upd<0x111>(h2v[j], v2), pg3 = dpp_upd<0x111>(h3g[j], g3), pg2 = dpp_upd<0x111>(h2g[j], g2);
;                     const float hv0 = bvv[j] + w2v[j] * v0 + w1v[j] * pv3 + w0v[j] * pv2, hv1 = bvv[j] + w2v[j] * v1 + w1v[j] * v0 + w0v[j] * pv3;
;                     const float hv2 = bvv[j] + w2v[j] * v2 + w1v[j] * v1 + w0v[j] * v0, hv3 = bvv[j] + w2v[j] * v3 + w1v[j] * v2 + w0v[j] * v1;
;                     const float hg0 = bvg[j] + w2g[j] * g0 + w1g[j] * pg3 + w0g[j] * pg2, hg1 = bvg[j] + w2g[j] * g1 + w1g[j] * g0 + w0g[j] * pg3;
;                     const float hg2 = bvg[j] + w2g[j] * g2 + w1g[j] * g1 + w0g[j] * g0, hg3 = bvg[j] + w2g[j] * g3 + w1g[j] * g2 + w0g[j] * g1;
;                     o[0][j] = hg0 * sigmoidf_(hg0) * hv0; o[1][j] = hg1 * sigmoidf_(hg1) * hv1; o[2][j] = hg2 * sigmoidf_(hg2) * hv2; o[3][j] = hg3 * sigmoidf_(hg3) * hv3; }
; #pragma unroll
;                 for (int m = 0; m < 4; ++m) { u32x2 w; w.x = cvt_pk_bf16(o[m][0], o[m][1]); w.y = cvt_pk_bf16(o[m][2], o[m][3]);
;                     *(u32x2*)(Aout + (size_t)(row0 + ai * 128 + m) * FH + hc0 + 4 * n) = w; } } }
	v_add_f32_e32 v153, 1.0, v193
	v_rcp_f32_e32 v140, v140
	v_rcp_f32_e32 v141, v141
	v_rcp_f32_e32 v132, v132
	v_rcp_f32_e32 v133, v133
	v_rcp_f32_e32 v152, v152
	v_rcp_f32_e32 v153, v153
	v_pk_fma_f32 v[142:143], v[150:151], v[170:171], v[174:175]
	v_pk_fma_f32 v[194:195], v[138:139], v[170:171], v[174:175]
	v_pk_fma_f32 v[136:137], v[136:137], v[164:165], v[148:149]
	v_pk_fma_f32 v[134:135], v[138:139], v[166:167], v[142:143]
	v_pk_fma_f32 v[194:195], v[146:147], v[166:167], v[194:195]
	v_pk_fma_f32 v[136:137], v[144:145], v[160:161], v[136:137]
	v_pk_mul_f32 v[128:129], v[128:129], v[140:141]
	v_pk_fma_f32 v[134:135], v[146:147], v[162:163], v[134:135]
	v_pk_mul_f32 v[130:131], v[130:131], v[132:133]
	v_pk_fma_f32 v[158:159], v[158:159], v[162:163], v[194:195]
	v_pk_mul_f32 v[152:153], v[154:155], v[152:153]
	v_pk_mul_f32 v[128:129], v[136:137], v[128:129]
	v_pk_mul_f32 v[130:131], v[134:135], v[130:131]
	v_pk_mul_f32 v[152:153], v[158:159], v[152:153]
	v_cvt_pk_bf16_f32 v128, v128, v129
	v_cvt_pk_bf16_f32 v129, v130, v131
	v_or_b32_e32 v130, 3, v246
	v_cvt_pk_bf16_f32 v157, v152, v153
	v_or_b32_e32 v152, 2, v246
	v_mad_i64_i32 v[130:131], s[34:35], v130, s74, v[206:207]
	v_mad_i64_i32 v[152:153], s[34:35], v152, s74, v[206:207]
	v_lshl_add_u64 v[140:141], v[130:131], 0, v[204:205]
	v_lshl_add_u64 v[152:153], v[152:153], 0, v[204:205]
	v_mov_b32_e32 v251, v128
	v_mov_b32_e32 v253, v129
	v_mov_b32_e32 v193, 0
	v_mov_b32_e32 v194, 0
	v_mov_b32_e32 v195, 0
	v_mov_b32_e32 v136, 0
	v_mov_b32_e32 v137, 0
	v_mov_b32_e32 v138, 0
	v_mov_b32_e32 v139, 0
	v_mov_b32_e32 v128, 0
	v_mov_b32_e32 v129, 0
	v_mov_b32_e32 v130, 0
	v_mov_b32_e32 v131, 0
	v_mov_b32_e32 v132, 0
	v_mov_b32_e32 v133, 0
	v_mov_b32_e32 v134, 0
	v_mov_b32_e32 v135, 0
	v_mov_b32_e32 v254, v156
	v_mov_b32_e32 v255, v157
	s_and_saveexec_b64 s[34:35], s[22:23]
	s_cbranch_execz .LBB0_320
	ds_read_b128 v[132:135], v237 offset:2048
	ds_read_b128 v[136:139], v237 offset:2560
	ds_read_b128 v[128:131], v237 offset:3072
	ds_read_b128 v[192:195], v237 offset:3584
.LBB0_320:
	s_or_b64 exec, exec, s[34:35]
	s_waitcnt lgkmcnt(0)
	v_mov_b32_dpp v192, v72 row_shr:1 row_mask:0xf bank_mask:0xf
	v_mov_b32_dpp v193, v73 row_shr:1 row_mask:0xf bank_mask:0xf
	v_pk_fma_f32 v[142:143], v[88:89], v[184:185], v[188:189]
	v_mov_b32_dpp v136, v64 row_shr:1 row_mask:0xf bank_mask:0xf
	v_mov_b32_dpp v137, v65 row_shr:1 row_mask:0xf bank_mask:0xf
	v_pk_fma_f32 v[142:143], v[180:181], v[192:193], v[142:143]
	v_mov_b32_dpp v128, v84 row_shr:1 row_mask:0xf bank_mask:0xf
	v_pk_fma_f32 v[136:137], v[176:177], v[136:137], v[142:143]
	v_mov_b32_dpp v129, v85 row_shr:1 row_mask:0xf bank_mask:0xf
	v_exp_f32_e32 v142, v136
	v_exp_f32_e32 v143, v137
	v_pk_fma_f32 v[144:145], v[92:93], v[168:169], v[172:173]
	v_mov_b32_dpp v132, v76 row_shr:1 row_mask:0xf bank_mask:0xf
	v_add_f32_e32 v142, 1.0, v142
	v_add_f32_e32 v143, 1.0, v143
	v_rcp_f32_e32 v142, v142
	v_rcp_f32_e32 v143, v143
	v_mov_b32_dpp v133, v77 row_shr:1 row_mask:0xf bank_mask:0xf
	v_pk_fma_f32 v[144:145], v[164:165], v[128:129], v[144:145]
	v_mov_b32_dpp v194, v74 row_shr:1 row_mask:0xf bank_mask:0xf
	v_pk_fma_f32 v[132:133], v[160:161], v[132:133], v[144:145]
	v_pk_mul_f32 v[136:137], v[136:137], v[142:143]
	v_mov_b32_dpp v195, v75 row_shr:1 row_mask:0xf bank_mask:0xf
	v_pk_mul_f32 v[132:133], v[132:133], v[136:137]
	v_pk_fma_f32 v[136:137], v[90:91], v[186:187], v[190:191]
	v_mov_b32_dpp v138, v66 row_shr:1 row_mask:0xf bank_mask:0xf
	v_mov_b32_dpp v139, v67 row_shr:1 row_mask:0xf bank_mask:0xf
	v_pk_fma_f32 v[136:137], v[182:183], v[194:195], v[136:137]
	v_mov_b32_dpp v130, v86 row_shr:1 row_mask:0xf bank_mask:0xf
	v_pk_fma_f32 v[136:137], v[178:179], v[138:139], v[136:137]
	v_mov_b32_dpp v131, v87 row_shr:1 row_mask:0xf bank_mask:0xf
	v_exp_f32_e32 v139, v136
	v_exp_f32_e32 v142, v137
	v_cvt_pk_bf16_f32 v138, v132, v133
	v_add_f32_e32 v132, 1.0, v139
	v_rcp_f32_e32 v132, v132
	v_add_f32_e32 v133, 1.0, v142
	v_rcp_f32_e32 v133, v133
	v_pk_fma_f32 v[142:143], v[94:95], v[170:171], v[174:175]
	v_mov_b32_dpp v134, v78 row_shr:1 row_mask:0xf bank_mask:0xf
	v_mov_b32_dpp v135, v79 row_shr:1 row_mask:0xf bank_mask:0xf
	v_pk_mul_f32 v[132:133], v[136:137], v[132:133]
	v_pk_fma_f32 v[136:137], v[68:69], v[184:185], v[188:189]
	v_pk_fma_f32 v[142:143], v[166:167], v[130:131], v[142:143]
	v_pk_fma_f32 v[136:137], v[88:89], v[180:181], v[136:137]
	v_pk_fma_f32 v[134:135], v[162:163], v[134:135], v[142:143]
	v_pk_fma_f32 v[136:137], v[176:177], v[192:193], v[136:137]
	v_add_u32_e32 v146, 0x80, v246
	v_exp_f32_e32 v142, v136
	v_exp_f32_e32 v143, v137
	v_pk_mul_f32 v[132:133], v[134:135], v[132:133]
	v_mov_b64_e32 v[134:135], s[60:61]
	v_cvt_pk_bf16_f32 v139, v132, v133
	v_mad_i64_i32 v[132:133], s[34:35], v146, s74, v[134:135]
	v_lshl_add_u64 v[132:133], v[132:133], 0, v[204:205]
	v_mov_b32_e32 v144, v138
	v_mov_b32_e32 v145, v139
	v_add_f32_e32 v138, 1.0, v142
	v_add_f32_e32 v139, 1.0, v143
	v_rcp_f32_e32 v138, v138
	v_rcp_f32_e32 v139, v139
	v_pk_fma_f32 v[142:143], v[80:81], v[168:169], v[172:173]
	v_pk_fma_f32 v[72:73], v[72:73], v[184:185], v[188:189]
	v_pk_fma_f32 v[142:143], v[92:93], v[164:165], v[142:143]
	v_pk_mul_f32 v[136:137], v[136:137], v[138:139]
	v_pk_fma_f32 v[128:129], v[160:161], v[128:129], v[142:143]
	v_pk_fma_f32 v[84:85], v[84:85], v[168:169], v[172:173]
	v_pk_mul_f32 v[128:129], v[128:129], v[136:137]
	v_pk_fma_f32 v[136:137], v[70:71], v[186:187], v[190:191]
	s_nop 0
	v_pk_fma_f32 v[136:137], v[90:91], v[182:183], v[136:137]
	s_nop 0
	v_pk_fma_f32 v[136:137], v[178:179], v[194:195], v[136:137]
	s_nop 0
	v_exp_f32_e32 v139, v136
; #define LAS __attribute__((address_space(3)))
; __device__ __forceinline__ float sigmoidf_(float x) { return __builtin_amdgcn_rcpf(1.0f + __expf(-x)); }
;     __device__ __forceinline__ void operator()(AccRef acc, const Unit& u, int wr, int wc, int fr, int fq) const {
;     ...
;                 f32x4 h2v = (f32x4){0.f, 0.f, 0.f, 0.f}, h3v = h2v, h2g = h2v, h3g = h2v;
;                 const int pb = ai * 2 + wr - 1;
;                 if (pb >= 0 && fr == 0) { const LAS float* xp = xch + (pb * 2) * 256 + clb + 4 * n;
;                     h2v = *(const LAS f32x4*)(xp); h3v = *(const LAS f32x4*)(xp + 256); h2g = *(const LAS f32x4*)(xp + 128); h3g = *(const LAS f32x4*)(xp + 256 + 128); }
;                 float o[4][4];
; #pragma unroll
;                 for (int j = 0; j < 4; ++j) {
;                     const float v0 = acc[ai][0][0][n][j], v1 = acc[ai][0][1][n][j], v2 = acc[ai][0][2][n][j], v3 = acc[ai][0][3][n][j];
;                     const float g0 = acc[ai][1][0][n][j], g1 = acc[ai][1][1][n][j], g2 = acc[ai][1][2][n][j], g3 = acc[ai][1][3][n][j];
;                     const float pv3 = dpp_upd<0x111>(h3v[j], v3), pv2 = dpp_upd<0x111>(h2v[j], v2), pg3 = dpp_upd<0x111>(h3g[j], g3), pg2 = dpp_upd<0x111>(h2g[j], g2);
;                     const float hv0 = bvv[j] + w2v[j] * v0 + w1v[j] * pv3 + w0v[j] * pv2, hv1 = bvv[j] + w2v[j] * v1 + w1v[j] * v0 + w0v[j] * pv3;
;                     const float hv2 = bvv[j] + w2v[j] * v2 + w1v[j] * v1 + w0v[j] * v0, hv3 = bvv[j] + w2v[j] * v3 + w1v[j] * v2 + w0v[j] * v1;
;                     const float hg0 = bvg[j] + w2g[j] * g0 + w1g[j] * pg3 + w0g[j] * pg2, hg1 = bvg[j] + w2g[j] * g1 + w1g[j] * g0 + w0g[j] * pg3;
;                     const float hg2 = bvg[j] + w2g[j] * g2 + w1g[j] * g1 + w0g[j] * g0, hg3 = bvg[j] + w2g[j] * g3 + w1g[j] * g2 + w0g[j] * g1;
;                     o[0][j] = hg0 * sigmoidf_(hg0) * hv0; o[1][j] = hg1 * sigmoidf_(hg1) * hv1; o[2][j] = hg2 * sigmoidf_(hg2) * hv2; o[3][j] = hg3 * sigmoidf_(hg3) * hv3; }
; #pragma unroll
;                 for (int m = 0; m < 4; ++m) { u32x2 w; w.x = cvt_pk_bf16(o[m][0], o[m][1]); w.y = cvt_pk_bf16(o[m][2], o[m][3]);
;                     *(u32x2*)(Aout + (size_t)(row0 + ai * 128 + m) * FH + hc0 + 4 * n) = w; } } }
	v_exp_f32_e32 v142, v137
	v_cvt_pk_bf16_f32 v138, v128, v129
	v_add_f32_e32 v128, 1.0, v139
	v_rcp_f32_e32 v128, v128
	v_add_f32_e32 v129, 1.0, v142
	v_rcp_f32_e32 v129, v129
	v_pk_fma_f32 v[142:143], v[82:83], v[170:171], v[174:175]
	v_pk_mul_f32 v[128:129], v[136:137], v[128:129]
	v_pk_fma_f32 v[142:143], v[94:95], v[166:167], v[142:143]
	v_pk_fma_f32 v[136:137], v[76:77], v[168:169], v[172:173]
	v_pk_fma_f32 v[130:131], v[162:163], v[130:131], v[142:143]
	v_pk_fma_f32 v[136:137], v[80:81], v[164:165], v[136:137]
	v_pk_mul_f32 v[128:129], v[130:131], v[128:129]
	v_pk_fma_f32 v[130:131], v[64:65], v[184:185], v[188:189]
	v_pk_fma_f32 v[64:65], v[64:65], v[180:181], v[72:73]
	v_pk_fma_f32 v[130:131], v[68:69], v[180:181], v[130:131]
	v_pk_fma_f32 v[64:65], v[68:69], v[176:177], v[64:65]
	v_pk_fma_f32 v[88:89], v[88:89], v[176:177], v[130:131]
	v_pk_fma_f32 v[92:93], v[92:93], v[160:161], v[136:137]
	v_exp_f32_e32 v130, v88
	v_exp_f32_e32 v131, v89
	v_exp_f32_e32 v72, v64
	v_add_f32_e32 v130, 1.0, v130
	v_add_f32_e32 v131, 1.0, v131
	v_rcp_f32_e32 v130, v130
	v_rcp_f32_e32 v131, v131
	v_pk_fma_f32 v[68:69], v[74:75], v[186:187], v[190:191]
	v_exp_f32_e32 v73, v65
	v_pk_mul_f32 v[88:89], v[88:89], v[130:131]
	v_add_f32_e32 v72, 1.0, v72
	v_pk_mul_f32 v[88:89], v[92:93], v[88:89]
	v_pk_fma_f32 v[92:93], v[66:67], v[186:187], v[190:191]
	v_pk_fma_f32 v[66:67], v[66:67], v[182:183], v[68:69]
	v_pk_fma_f32 v[92:93], v[70:71], v[182:183], v[92:93]
	v_pk_fma_f32 v[66:67], v[70:71], v[178:179], v[66:67]
	v_pk_fma_f32 v[90:91], v[90:91], v[178:179], v[92:93]
	v_exp_f32_e32 v93, v90
	v_exp_f32_e32 v68, v66
	v_exp_f32_e32 v69, v67
	v_exp_f32_e32 v130, v91
	v_add_f32_e32 v73, 1.0, v73
	v_add_f32_e32 v68, 1.0, v68
	v_add_f32_e32 v69, 1.0, v69
	v_cvt_pk_bf16_f32 v92, v88, v89
	v_add_f32_e32 v88, 1.0, v93
	v_add_f32_e32 v89, 1.0, v130
	v_rcp_f32_e32 v72, v72
	v_rcp_f32_e32 v73, v73
	v_rcp_f32_e32 v68, v68
	v_rcp_f32_e32 v69, v69
	v_rcp_f32_e32 v88, v88
	v_rcp_f32_e32 v89, v89
	v_pk_fma_f32 v[74:75], v[86:87], v[170:171], v[174:175]
	v_pk_fma_f32 v[130:131], v[78:79], v[170:171], v[174:175]
	v_pk_fma_f32 v[76:77], v[76:77], v[164:165], v[84:85]
	v_pk_fma_f32 v[70:71], v[78:79], v[166:167], v[74:75]
	v_pk_fma_f32 v[130:131], v[82:83], v[166:167], v[130:131]
	v_pk_fma_f32 v[76:77], v[80:81], v[160:161], v[76:77]
	v_pk_mul_f32 v[64:65], v[64:65], v[72:73]
	v_pk_fma_f32 v[70:71], v[82:83], v[162:163], v[70:71]
	v_pk_mul_f32 v[66:67], v[66:67], v[68:69]
	v_pk_fma_f32 v[94:95], v[94:95], v[162:163], v[130:131]
	v_pk_mul_f32 v[88:89], v[90:91], v[88:89]
	v_pk_mul_f32 v[64:65], v[76:77], v[64:65]
	v_pk_mul_f32 v[66:67], v[70:71], v[66:67]
	v_pk_mul_f32 v[88:89], v[94:95], v[88:89]
	v_cvt_pk_bf16_f32 v64, v64, v65
	v_cvt_pk_bf16_f32 v65, v66, v67
	v_add_u32_e32 v66, 0x83, v246
	v_cvt_pk_bf16_f32 v139, v128, v129
	v_add_u32_e32 v128, 0x81, v246
	v_cvt_pk_bf16_f32 v93, v88, v89
	v_add_u32_e32 v88, 0x82, v246
	v_mad_i64_i32 v[66:67], s[34:35], v66, s74, v[134:135]
	v_mad_i64_i32 v[128:129], s[34:35], v128, s74, v[134:135]
	v_mad_i64_i32 v[88:89], s[34:35], v88, s74, v[134:135]
	v_lshl_add_u64 v[82:83], v[66:67], 0, v[204:205]
	v_lshl_add_u64 v[128:129], v[128:129], 0, v[204:205]
	v_lshl_add_u64 v[88:89], v[88:89], 0, v[204:205]
	v_mov_b32_e32 v148, v64
	v_mov_b32_e32 v149, v65
	v_mov_b32_e32 v64, 0
	v_mov_b32_e32 v70, 0
	v_mov_b32_e32 v71, 0
	v_mov_b32_e32 v72, 0
	v_mov_b32_e32 v73, 0
	v_mov_b32_e32 v78, 0
	v_mov_b32_e32 v79, 0
	v_mov_b32_e32 v80, 0
	v_mov_b32_e32 v81, 0
	v_mov_b32_e32 v66, 0
	v_mov_b32_e32 v67, 0
	v_mov_b32_e32 v68, 0
	v_mov_b32_e32 v69, 0
	v_mov_b32_e32 v74, 0
	v_mov_b32_e32 v75, 0
	v_mov_b32_e32 v76, 0
	v_mov_b32_e32 v77, 0
	v_mov_b32_e32 v154, v138
	v_mov_b32_e32 v155, v139
	v_mov_b32_e32 v198, v92
	v_mov_b32_e32 v199, v93
	s_and_saveexec_b64 s[34:35], s[18:19]
	s_cbranch_execz .LBB0_322
	ds_read_b128 v[74:77], v242
	ds_read_b128 v[66:69], v241
	ds_read_b128 v[78:81], v240
	ds_read_b128 v[70:73], v239
.LBB0_322:
	s_or_b64 exec, exec, s[34:35]
	s_waitcnt lgkmcnt(0)
	v_mov_b32_dpp v70, v44 row_shr:1 row_mask:0xf bank_mask:0xf
	v_mov_b32_dpp v71, v45 row_shr:1 row_mask:0xf bank_mask:0xf
	s_waitcnt vmcnt(0)
; #define LAS __attribute__((address_space(3)))
; __device__ __forceinline__ float sigmoidf_(float x) { return __builtin_amdgcn_rcpf(1.0f + __expf(-x)); }
;     __device__ __forceinline__ void operator()(AccRef acc, const Unit& u, int wr, int wc, int fr, int fq) const {
;     ...
;                 f32x4 h2v = (f32x4){0.f, 0.f, 0.f, 0.f}, h3v = h2v, h2g = h2v, h3g = h2v;
;                 const int pb = ai * 2 + wr - 1;
;                 if (pb >= 0 && fr == 0) { const LAS float* xp = xch + (pb * 2) * 256 + clb + 4 * n;
;                     h2v = *(const LAS f32x4*)(xp); h3v = *(const LAS f32x4*)(xp + 256); h2g = *(const LAS f32x4*)(xp + 128); h3g = *(const LAS f32x4*)(xp + 256 + 128); }
;                 float o[4][4];
; #pragma unroll
;                 for (int j = 0; j < 4; ++j) {
;                     const float v0 = acc[ai][0][0][n][j], v1 = acc[ai][0][1][n][j], v2 = acc[ai][0][2][n][j], v3 = acc[ai][0][3][n][j];
;                     const float g0 = acc[ai][1][0][n][j], g1 = acc[ai][1][1][n][j], g2 = acc[ai][1][2][n][j], g3 = acc[ai][1][3][n][j];
;                     const float pv3 = dpp_upd<0x111>(h3v[j], v3), pv2 = dpp_upd<0x111>(h2v[j], v2), pg3 = dpp_upd<0x111>(h3g[j], g3), pg2 = dpp_upd<0x111>(h2g[j], g2);
;                     const float hv0 = bvv[j] + w2v[j] * v0 + w1v[j] * pv3 + w0v[j] * pv2, hv1 = bvv[j] + w2v[j] * v1 + w1v[j] * v0 + w0v[j] * pv3;
;                     const float hv2 = bvv[j] + w2v[j] * v2 + w1v[j] * v1 + w0v[j] * v0, hv3 = bvv[j] + w2v[j] * v3 + w1v[j] * v2 + w0v[j] * v1;
;                     const float hg0 = bvg[j] + w2g[j] * g0 + w1g[j] * pg3 + w0g[j] * pg2, hg1 = bvg[j] + w2g[j] * g1 + w1g[j] * g0 + w0g[j] * pg3;
;                     const float hg2 = bvg[j] + w2g[j] * g2 + w1g[j] * g1 + w0g[j] * g0, hg3 = bvg[j] + w2g[j] * g3 + w1g[j] * g2 + w0g[j] * g1;
;                     o[0][j] = hg0 * sigmoidf_(hg0) * hv0; o[1][j] = hg1 * sigmoidf_(hg1) * hv1; o[2][j] = hg2 * sigmoidf_(hg2) * hv2; o[3][j] = hg3 * sigmoidf_(hg3) * hv3; }
; #pragma unroll
;                 for (int m = 0; m < 4; ++m) { u32x2 w; w.x = cvt_pk_bf16(o[m][0], o[m][1]); w.y = cvt_pk_bf16(o[m][2], o[m][3]);
;                     *(u32x2*)(Aout + (size_t)(row0 + ai * 128 + m) * FH + hc0 + 4 * n) = w; } } }
	v_pk_fma_f32 v[84:85], v[56:57], v[120:121], v[124:125]
	v_mov_b32_dpp v78, v32 row_shr:1 row_mask:0xf bank_mask:0xf
	v_mov_b32_dpp v79, v33 row_shr:1 row_mask:0xf bank_mask:0xf
	v_pk_fma_f32 v[84:85], v[116:117], v[70:71], v[84:85]
	v_mov_b32_dpp v66, v52 row_shr:1 row_mask:0xf bank_mask:0xf
	v_pk_fma_f32 v[78:79], v[112:113], v[78:79], v[84:85]
	v_mov_b32_dpp v67, v53 row_shr:1 row_mask:0xf bank_mask:0xf
	v_exp_f32_e32 v65, v78
	v_exp_f32_e32 v85, v79
	v_pk_fma_f32 v[86:87], v[60:61], v[104:105], v[108:109]
	v_add_f32_e32 v65, 1.0, v65
	v_rcp_f32_e32 v84, v65
	v_add_f32_e32 v65, 1.0, v85
	v_rcp_f32_e32 v85, v65
	v_mov_b32_dpp v74, v40 row_shr:1 row_mask:0xf bank_mask:0xf
	v_mov_b32_dpp v75, v41 row_shr:1 row_mask:0xf bank_mask:0xf
	v_pk_fma_f32 v[86:87], v[100:101], v[66:67], v[86:87]
	v_pk_mul_f32 v[78:79], v[78:79], v[84:85]
	v_pk_fma_f32 v[74:75], v[96:97], v[74:75], v[86:87]
	v_mov_b32_dpp v72, v46 row_shr:1 row_mask:0xf bank_mask:0xf
	v_mov_b32_dpp v73, v47 row_shr:1 row_mask:0xf bank_mask:0xf
	v_pk_mul_f32 v[74:75], v[74:75], v[78:79]
	v_pk_fma_f32 v[78:79], v[58:59], v[122:123], v[126:127]
	v_mov_b32_dpp v80, v34 row_shr:1 row_mask:0xf bank_mask:0xf
	v_mov_b32_dpp v81, v35 row_shr:1 row_mask:0xf bank_mask:0xf
	v_pk_fma_f32 v[78:79], v[118:119], v[72:73], v[78:79]
	v_mov_b32_dpp v68, v54 row_shr:1 row_mask:0xf bank_mask:0xf
	v_pk_fma_f32 v[78:79], v[114:115], v[80:81], v[78:79]
	v_mov_b32_dpp v69, v55 row_shr:1 row_mask:0xf bank_mask:0xf
	v_exp_f32_e32 v65, v78
	v_exp_f32_e32 v81, v79
	v_pk_fma_f32 v[84:85], v[62:63], v[106:107], v[110:111]
	v_add_f32_e32 v65, 1.0, v65
	v_rcp_f32_e32 v80, v65
	v_add_f32_e32 v65, 1.0, v81
	v_rcp_f32_e32 v81, v65
	v_mov_b32_dpp v76, v42 row_shr:1 row_mask:0xf bank_mask:0xf
	v_mov_b32_dpp v77, v43 row_shr:1 row_mask:0xf bank_mask:0xf
	v_pk_fma_f32 v[84:85], v[102:103], v[68:69], v[84:85]
	v_pk_mul_f32 v[78:79], v[78:79], v[80:81]
	v_pk_fma_f32 v[76:77], v[98:99], v[76:77], v[84:85]
	v_cvt_pk_bf16_f32 v74, v74, v75
	v_pk_mul_f32 v[76:77], v[76:77], v[78:79]
	v_pk_fma_f32 v[44:45], v[44:45], v[120:121], v[124:125]
	v_cvt_pk_bf16_f32 v75, v76, v77
	v_pk_fma_f32 v[76:77], v[36:37], v[120:121], v[124:125]
	v_mov_b32_e32 v90, v247
	v_mov_b32_e32 v91, v248
	v_mov_b32_e32 v92, v74
	v_mov_b32_e32 v93, v75
	global_store_dwordx4 v[202:203], v[90:93], off
	v_pk_fma_f32 v[76:77], v[56:57], v[116:117], v[76:77]
	v_pk_fma_f32 v[52:53], v[52:53], v[104:105], v[108:109]
	v_pk_fma_f32 v[70:71], v[112:113], v[70:71], v[76:77]
	s_nop 0
	v_exp_f32_e32 v65, v70
	v_exp_f32_e32 v76, v71
	v_add_f32_e32 v65, 1.0, v65
	v_rcp_f32_e32 v74, v65
	v_add_f32_e32 v65, 1.0, v76
	v_rcp_f32_e32 v75, v65
	v_pk_fma_f32 v[76:77], v[48:49], v[104:105], v[108:109]
	v_pk_mul_f32 v[70:71], v[70:71], v[74:75]
	v_pk_fma_f32 v[76:77], v[60:61], v[100:101], v[76:77]
	v_pk_fma_f32 v[74:75], v[50:51], v[106:107], v[110:111]
	v_pk_fma_f32 v[66:67], v[96:97], v[66:67], v[76:77]
	v_pk_fma_f32 v[74:75], v[62:63], v[102:103], v[74:75]
	v_pk_mul_f32 v[66:67], v[66:67], v[70:71]
	v_pk_fma_f32 v[70:71], v[38:39], v[122:123], v[126:127]
	v_pk_fma_f32 v[68:69], v[98:99], v[68:69], v[74:75]
	v_pk_fma_f32 v[70:71], v[58:59], v[118:119], v[70:71]
	v_cvt_pk_bf16_f32 v66, v66, v67
	v_pk_fma_f32 v[70:71], v[114:115], v[72:73], v[70:71]
	s_nop 0
	v_exp_f32_e32 v65, v70
	v_exp_f32_e32 v73, v71
	v_add_f32_e32 v65, 1.0, v65
	v_rcp_f32_e32 v72, v65
	v_add_f32_e32 v65, 1.0, v73
	v_rcp_f32_e32 v73, v65
	s_nop 0
	v_pk_mul_f32 v[70:71], v[70:71], v[72:73]
	s_nop 0
	v_pk_mul_f32 v[68:69], v[68:69], v[70:71]
	s_nop 0
	v_cvt_pk_bf16_f32 v67, v68, v69
	v_pk_fma_f32 v[68:69], v[32:33], v[120:121], v[124:125]
	v_mov_b32_e32 v134, v249
	v_mov_b32_e32 v135, v250
	v_mov_b32_e32 v136, v66
	v_mov_b32_e32 v137, v67
	global_store_dwordx4 v[196:197], v[134:137], off
	v_pk_fma_f32 v[68:69], v[36:37], v[116:117], v[68:69]
	v_pk_fma_f32 v[32:33], v[32:33], v[116:117], v[44:45]
	v_pk_fma_f32 v[56:57], v[56:57], v[112:113], v[68:69]
	v_pk_fma_f32 v[32:33], v[36:37], v[112:113], v[32:33]
	v_exp_f32_e32 v65, v56
	v_exp_f32_e32 v68, v57
	v_add_f32_e32 v65, 1.0, v65
	v_rcp_f32_e32 v66, v65
	v_add_f32_e32 v65, 1.0, v68
	v_rcp_f32_e32 v67, v65
	v_pk_fma_f32 v[68:69], v[40:41], v[104:105], v[108:109]
	v_exp_f32_e32 v44, v32
	v_pk_fma_f32 v[68:69], v[48:49], v[100:101], v[68:69]
	v_pk_mul_f32 v[56:57], v[56:57], v[66:67]
	v_pk_fma_f32 v[60:61], v[60:61], v[96:97], v[68:69]
	v_pk_fma_f32 v[36:37], v[46:47], v[122:123], v[126:127]
	v_pk_mul_f32 v[56:57], v[60:61], v[56:57]
	v_pk_fma_f32 v[60:61], v[34:35], v[122:123], v[126:127]
	v_pk_fma_f32 v[34:35], v[34:35], v[118:119], v[36:37]
	v_pk_fma_f32 v[60:61], v[38:39], v[118:119], v[60:61]
	v_pk_fma_f32 v[34:35], v[38:39], v[114:115], v[34:35]
	v_pk_fma_f32 v[58:59], v[58:59], v[114:115], v[60:61]
	v_exp_f32_e32 v60, v58
	v_exp_f32_e32 v45, v33
	v_exp_f32_e32 v36, v34
	v_exp_f32_e32 v37, v35
	v_exp_f32_e32 v61, v59
	v_cvt_pk_bf16_f32 v56, v56, v57
	v_add_f32_e32 v57, 1.0, v60
	v_add_f32_e32 v44, 1.0, v44
	v_add_f32_e32 v45, 1.0, v45
	v_add_f32_e32 v36, 1.0, v36
	v_add_f32_e32 v37, 1.0, v37
	v_rcp_f32_e32 v60, v57
	v_add_f32_e32 v57, 1.0, v61
	v_rcp_f32_e32 v44, v44
	v_rcp_f32_e32 v45, v45
	v_rcp_f32_e32 v36, v36
	v_rcp_f32_e32 v37, v37
	v_rcp_f32_e32 v61, v57
	v_pk_fma_f32 v[46:47], v[54:55], v[106:107], v[110:111]
	v_pk_fma_f32 v[66:67], v[42:43], v[106:107], v[110:111]
	v_pk_fma_f32 v[40:41], v[40:41], v[100:101], v[52:53]
	v_pk_fma_f32 v[38:39], v[42:43], v[102:103], v[46:47]
	v_pk_fma_f32 v[66:67], v[50:51], v[102:103], v[66:67]
	v_pk_fma_f32 v[40:41], v[48:49], v[96:97], v[40:41]
	v_pk_mul_f32 v[32:33], v[32:33], v[44:45]
	v_pk_fma_f32 v[38:39], v[50:51], v[98:99], v[38:39]
	v_pk_mul_f32 v[34:35], v[34:35], v[36:37]
	v_pk_fma_f32 v[62:63], v[62:63], v[98:99], v[66:67]
	v_pk_mul_f32 v[58:59], v[58:59], v[60:61]
	v_pk_mul_f32 v[32:33], v[40:41], v[32:33]
	v_pk_mul_f32 v[34:35], v[38:39], v[34:35]
	v_pk_mul_f32 v[58:59], v[62:63], v[58:59]
	v_cvt_pk_bf16_f32 v32, v32, v33
	v_cvt_pk_bf16_f32 v33, v34, v35
	v_cvt_pk_bf16_f32 v57, v58, v59
	v_mov_b32_e32 v158, v251
	v_mov_b32_e32 v159, v253
	v_mov_b32_e32 v160, v32
	v_mov_b32_e32 v161, v33
	global_store_dwordx4 v[140:141], v[158:161], off
	v_mov_b32_e32 v65, 0
	v_mov_b32_e32 v66, 0
	v_mov_b32_e32 v67, 0
	v_mov_b32_e32 v40, 0
	v_mov_b32_e32 v41, 0
	v_mov_b32_e32 v42, 0
	v_mov_b32_e32 v43, 0
	v_mov_b32_e32 v32, 0
	v_mov_b32_e32 v33, 0
	v_mov_b32_e32 v34, 0
	v_mov_b32_e32 v35, 0
	v_mov_b32_e32 v36, 0
	v_mov_b32_e32 v37, 0
	v_mov_b32_e32 v38, 0
	v_mov_b32_e32 v39, 0
	v_mov_b32_e32 v162, v254
	v_mov_b32_e32 v163, v255
	v_mov_b32_e32 v164, v56
	v_mov_b32_e32 v165, v57
	global_store_dwordx4 v[152:153], v[162:165], off
	s_and_saveexec_b64 s[34:35], s[22:23]
	s_cbranch_execz .LBB0_305
	ds_read_b128 v[36:39], v237 offset:2064
	ds_read_b128 v[40:43], v237 offset:2576
	ds_read_b128 v[32:35], v237 offset:3088
	ds_read_b128 v[64:67], v237 offset:3600
	s_branch .LBB0_305

; #define LAS __attribute__((address_space(3)))
; __device__ __forceinline__ float sigmoidf_(float x) { return __builtin_amdgcn_rcpf(1.0f + __expf(-x)); }
;     __device__ __forceinline__ void operator()(AccRef acc, const Unit& u, int wr, int wc, int fr, int fq) const {
;     ...
;                 f32x4 h2v = (f32x4){0.f, 0.f, 0.f, 0.f}, h3v = h2v, h2g = h2v, h3g = h2v;
;                 const int pb = ai * 2 + wr - 1;
;                 if (pb >= 0 && fr == 0) { const LAS float* xp = xch + (pb * 2) * 256 + clb + 4 * n;
;                     h2v = *(const LAS f32x4*)(xp); h3v = *(const LAS f32x4*)(xp + 256); h2g = *(const LAS f32x4*)(xp + 128); h3g = *(const LAS f32x4*)(xp + 256 + 128); }
;                 float o[4][4];
; #pragma unroll
;                 for (int j = 0; j < 4; ++j) {
;                     const float v0 = acc[ai][0][0][n][j], v1 = acc[ai][0][1][n][j], v2 = acc[ai][0][2][n][j], v3 = acc[ai][0][3][n][j];
;                     const float g0 = acc[ai][1][0][n][j], g1 = acc[ai][1][1][n][j], g2 = acc[ai][1][2][n][j], g3 = acc[ai][1][3][n][j];
;                     const float pv3 = dpp_upd<0x111>(h3v[j], v3), pv2 = dpp_upd<0x111>(h2v[j], v2), pg3 = dpp_upd<0x111>(h3g[j], g3), pg2 = dpp_upd<0x111>(h2g[j], g2);
;                     const float hv0 = bvv[j] + w2v[j] * v0 + w1v[j] * pv3 + w0v[j] * pv2, hv1 = bvv[j] + w2v[j] * v1 + w1v[j] * v0 + w0v[j] * pv3;
;                     const float hv2 = bvv[j] + w2v[j] * v2 + w1v[j] * v1 + w0v[j] * v0, hv3 = bvv[j] + w2v[j] * v3 + w1v[j] * v2 + w0v[j] * v1;
;                     const float hg0 = bvg[j] + w2g[j] * g0 + w1g[j] * pg3 + w0g[j] * pg2, hg1 = bvg[j] + w2g[j] * g1 + w1g[j] * g0 + w0g[j] * pg3;
;                     const float hg2 = bvg[j] + w2g[j] * g2 + w1g[j] * g1 + w0g[j] * g0, hg3 = bvg[j] + w2g[j] * g3 + w1g[j] * g2 + w0g[j] * g1;
;                     o[0][j] = hg0 * sigmoidf_(hg0) * hv0; o[1][j] = hg1 * sigmoidf_(hg1) * hv1; o[2][j] = hg2 * sigmoidf_(hg2) * hv2; o[3][j] = hg3 * sigmoidf_(hg3) * hv3; }
; #pragma unroll
;                 for (int m = 0; m < 4; ++m) { u32x2 w; w.x = cvt_pk_bf16(o[m][0], o[m][1]); w.y = cvt_pk_bf16(o[m][2], o[m][3]);
;                     *(u32x2*)(Aout + (size_t)(row0 + ai * 128 + m) * FH + hc0 + 4 * n) = w; } } }
.LBB0_754:
	s_or_b64 exec, exec, s[40:41]
	s_waitcnt lgkmcnt(0)
	v_mov_b32_dpp v64, v8 row_shr:1 row_mask:0xf bank_mask:0xf
	v_mov_b32_dpp v65, v9 row_shr:1 row_mask:0xf bank_mask:0xf
	v_pk_fma_f32 v[44:45], v[24:25], v[120:121], v[124:125]
	v_mov_b32_dpp v40, v0 row_shr:1 row_mask:0xf bank_mask:0xf
	v_mov_b32_dpp v41, v1 row_shr:1 row_mask:0xf bank_mask:0xf
	v_pk_fma_f32 v[44:45], v[116:117], v[64:65], v[44:45]
	v_mov_b32_dpp v32, v20 row_shr:1 row_mask:0xf bank_mask:0xf
	v_pk_fma_f32 v[40:41], v[112:113], v[40:41], v[44:45]
	v_mov_b32_dpp v33, v21 row_shr:1 row_mask:0xf bank_mask:0xf
	v_exp_f32_e32 v44, v40
	v_exp_f32_e32 v45, v41
	v_pk_fma_f32 v[46:47], v[28:29], v[104:105], v[108:109]
	v_mov_b32_dpp v36, v12 row_shr:1 row_mask:0xf bank_mask:0xf
	v_add_f32_e32 v44, 1.0, v44
	v_add_f32_e32 v45, 1.0, v45
	v_rcp_f32_e32 v44, v44
	v_rcp_f32_e32 v45, v45
	v_mov_b32_dpp v37, v13 row_shr:1 row_mask:0xf bank_mask:0xf
	v_pk_fma_f32 v[46:47], v[100:101], v[32:33], v[46:47]
	v_mov_b32_dpp v66, v10 row_shr:1 row_mask:0xf bank_mask:0xf
	v_pk_fma_f32 v[36:37], v[96:97], v[36:37], v[46:47]
	v_pk_mul_f32 v[40:41], v[40:41], v[44:45]
	v_mov_b32_dpp v67, v11 row_shr:1 row_mask:0xf bank_mask:0xf
	v_pk_mul_f32 v[36:37], v[36:37], v[40:41]
	v_pk_fma_f32 v[40:41], v[26:27], v[122:123], v[126:127]
	v_mov_b32_dpp v42, v2 row_shr:1 row_mask:0xf bank_mask:0xf
	v_mov_b32_dpp v43, v3 row_shr:1 row_mask:0xf bank_mask:0xf
	v_pk_fma_f32 v[40:41], v[118:119], v[66:67], v[40:41]
	v_cvt_pk_bf16_f32 v36, v36, v37
	v_pk_fma_f32 v[40:41], v[114:115], v[42:43], v[40:41]
	v_mov_b32_dpp v34, v22 row_shr:1 row_mask:0xf bank_mask:0xf
	v_exp_f32_e32 v42, v40
	v_exp_f32_e32 v43, v41
	v_mov_b32_dpp v35, v23 row_shr:1 row_mask:0xf bank_mask:0xf
	v_add_f32_e32 v37, 1.0, v42
	v_rcp_f32_e32 v42, v37
	v_add_f32_e32 v37, 1.0, v43
	v_rcp_f32_e32 v43, v37
	v_pk_fma_f32 v[44:45], v[30:31], v[106:107], v[110:111]
	v_mov_b32_dpp v38, v14 row_shr:1 row_mask:0xf bank_mask:0xf
	v_mov_b32_dpp v39, v15 row_shr:1 row_mask:0xf bank_mask:0xf
	v_pk_fma_f32 v[44:45], v[102:103], v[34:35], v[44:45]
	v_pk_mul_f32 v[40:41], v[40:41], v[42:43]
	v_pk_fma_f32 v[38:39], v[98:99], v[38:39], v[44:45]
	v_pk_fma_f32 v[8:9], v[8:9], v[120:121], v[124:125]
	v_pk_mul_f32 v[38:39], v[38:39], v[40:41]
	v_pk_fma_f32 v[20:21], v[20:21], v[104:105], v[108:109]
	v_cvt_pk_bf16_f32 v37, v38, v39
	v_pk_fma_f32 v[38:39], v[4:5], v[120:121], v[124:125]
	v_mov_b32_e32 v146, v36
	v_mov_b32_e32 v147, v37
	global_store_dwordx4 v[132:133], v[144:147], off
	v_pk_fma_f32 v[38:39], v[24:25], v[116:117], v[38:39]
	s_and_b64 vcc, exec, s[14:15]
	v_pk_fma_f32 v[38:39], v[112:113], v[64:65], v[38:39]
	s_mov_b32 s41, s30
	v_exp_f32_e32 v40, v38
	v_exp_f32_e32 v41, v39
	s_mov_b32 s40, s34
	s_mov_b64 s[44:45], s[38:39]
	v_add_f32_e32 v36, 1.0, v40
	v_add_f32_e32 v37, 1.0, v41
	v_rcp_f32_e32 v36, v36
	v_rcp_f32_e32 v37, v37
	v_pk_fma_f32 v[40:41], v[16:17], v[104:105], v[108:109]
	s_mov_b64 s[42:43], s[36:37]
	v_pk_fma_f32 v[40:41], v[28:29], v[100:101], v[40:41]
	v_pk_mul_f32 v[36:37], v[38:39], v[36:37]
	v_pk_fma_f32 v[32:33], v[96:97], v[32:33], v[40:41]
	v_pk_fma_f32 v[40:41], v[18:19], v[106:107], v[110:111]
	v_pk_mul_f32 v[32:33], v[32:33], v[36:37]
	v_pk_fma_f32 v[36:37], v[6:7], v[122:123], v[126:127]
	v_cvt_pk_bf16_f32 v32, v32, v33
	v_pk_fma_f32 v[36:37], v[26:27], v[118:119], v[36:37]
	v_pk_fma_f32 v[40:41], v[30:31], v[102:103], v[40:41]
	v_pk_fma_f32 v[36:37], v[114:115], v[66:67], v[36:37]
	v_pk_fma_f32 v[34:35], v[98:99], v[34:35], v[40:41]
	v_exp_f32_e32 v38, v36
	v_exp_f32_e32 v39, v37
	v_add_f32_e32 v33, 1.0, v38
	v_rcp_f32_e32 v38, v33
	v_add_f32_e32 v33, 1.0, v39
	v_rcp_f32_e32 v39, v33
	s_nop 0
	v_pk_mul_f32 v[36:37], v[36:37], v[38:39]
	s_nop 0
	v_pk_mul_f32 v[34:35], v[34:35], v[36:37]
	s_nop 0
	v_cvt_pk_bf16_f32 v33, v34, v35
	v_pk_fma_f32 v[34:35], v[0:1], v[120:121], v[124:125]
	v_mov_b32_e32 v156, v32
	v_mov_b32_e32 v157, v33
	global_store_dwordx4 v[128:129], v[154:157], off
	v_pk_fma_f32 v[34:35], v[4:5], v[116:117], v[34:35]
	v_pk_fma_f32 v[0:1], v[0:1], v[116:117], v[8:9]
	v_pk_fma_f32 v[24:25], v[24:25], v[112:113], v[34:35]
	v_pk_fma_f32 v[0:1], v[4:5], v[112:113], v[0:1]
	v_exp_f32_e32 v34, v24
	v_exp_f32_e32 v35, v25
	v_exp_f32_e32 v8, v0
	v_add_f32_e32 v32, 1.0, v34
	v_add_f32_e32 v33, 1.0, v35
	v_rcp_f32_e32 v32, v32
	v_rcp_f32_e32 v33, v33
	v_pk_fma_f32 v[34:35], v[12:13], v[104:105], v[108:109]
	v_pk_fma_f32 v[4:5], v[10:11], v[122:123], v[126:127]
	v_pk_fma_f32 v[34:35], v[16:17], v[100:101], v[34:35]
	v_pk_mul_f32 v[24:25], v[24:25], v[32:33]
	v_pk_fma_f32 v[28:29], v[28:29], v[96:97], v[34:35]
	v_pk_mul_f32 v[24:25], v[28:29], v[24:25]
	v_pk_fma_f32 v[28:29], v[2:3], v[122:123], v[126:127]
	v_pk_fma_f32 v[2:3], v[2:3], v[118:119], v[4:5]
	v_pk_fma_f32 v[28:29], v[6:7], v[118:119], v[28:29]
	v_pk_fma_f32 v[2:3], v[6:7], v[114:115], v[2:3]
	v_pk_fma_f32 v[26:27], v[26:27], v[114:115], v[28:29]
	v_exp_f32_e32 v28, v26
	v_exp_f32_e32 v29, v27
	v_exp_f32_e32 v9, v1
	v_exp_f32_e32 v4, v2
	v_exp_f32_e32 v5, v3
	v_cvt_pk_bf16_f32 v24, v24, v25
	v_add_f32_e32 v25, 1.0, v28
	v_rcp_f32_e32 v28, v25
	v_add_f32_e32 v25, 1.0, v29
	v_add_f32_e32 v8, 1.0, v8
	v_add_f32_e32 v9, 1.0, v9
	v_add_f32_e32 v4, 1.0, v4
	v_add_f32_e32 v5, 1.0, v5
	v_rcp_f32_e32 v29, v25
	v_rcp_f32_e32 v8, v8
	v_rcp_f32_e32 v9, v9
	v_rcp_f32_e32 v4, v4
	v_rcp_f32_e32 v5, v5
	v_pk_fma_f32 v[32:33], v[14:15], v[106:107], v[110:111]
	v_pk_fma_f32 v[10:11], v[22:23], v[106:107], v[110:111]
	v_pk_fma_f32 v[32:33], v[18:19], v[102:103], v[32:33]
	v_pk_fma_f32 v[12:13], v[12:13], v[100:101], v[20:21]
	v_pk_fma_f32 v[6:7], v[14:15], v[102:103], v[10:11]
	v_pk_fma_f32 v[30:31], v[30:31], v[98:99], v[32:33]
	v_pk_mul_f32 v[26:27], v[26:27], v[28:29]
	v_pk_fma_f32 v[12:13], v[16:17], v[96:97], v[12:13]
	v_pk_mul_f32 v[0:1], v[0:1], v[8:9]
	v_pk_fma_f32 v[6:7], v[18:19], v[98:99], v[6:7]
	v_pk_mul_f32 v[2:3], v[2:3], v[4:5]
	v_pk_mul_f32 v[26:27], v[30:31], v[26:27]
	v_pk_mul_f32 v[0:1], v[12:13], v[0:1]
	v_pk_mul_f32 v[2:3], v[6:7], v[2:3]
	v_cvt_pk_bf16_f32 v25, v26, v27
	v_cvt_pk_bf16_f32 v0, v0, v1
	v_cvt_pk_bf16_f32 v1, v2, v3
	v_mov_b32_e32 v200, v24
	v_mov_b32_e32 v201, v25
	global_store_dwordx4 v[88:89], v[198:201], off
	v_mov_b32_e32 v150, v0
	v_mov_b32_e32 v151, v1
	global_store_dwordx4 v[82:83], v[148:151], off
	s_cbranch_vccnz .LBB0_773

;     __device__ __forceinline__ void operator()(AccRef acc, const Unit& u, int wr, int wc, int fr, int fq) const {
;     ...
;         { const float* cv = cw + 128 * u.pn + clb; const float* cg = cv + FH; const float* bp = cb + 128 * u.pn + clb;
;           cwv[0][0] = *(const f32x4*)(cv); cwv[0][1] = *(const f32x4*)(cv + F2); cwv[0][2] = *(const f32x4*)(cv + 2 * F2); cwv[0][3] = *(const f32x4*)(bp);
;           cwv[0][4] = *(const f32x4*)(cg); cwv[0][5] = *(const f32x4*)(cg + F2); cwv[0][6] = *(const f32x4*)(cg + 2 * F2); cwv[0][7] = *(const f32x4*)(bp + FH); }
;     ...
;                     const float* cv = cw + hc0 + 4; const float* cg = cv + FH; const float* bp = cb + hc0 + 4;
;                     cwv[1][0] = *(const f32x4*)(cv); cwv[1][1] = *(const f32x4*)(cv + F2); cwv[1][2] = *(const f32x4*)(cv + 2 * F2); cwv[1][3] = *(const f32x4*)(bp);
;                     cwv[1][4] = *(const f32x4*)(cg); cwv[1][5] = *(const f32x4*)(cg + F2); cwv[1][6] = *(const f32x4*)(cg + 2 * F2); cwv[1][7] = *(const f32x4*)(bp + FH);
.LBB0_767:
	s_or_b64 exec, exec, s[42:43]
	s_waitcnt lgkmcnt(0)
	v_mov_b32_dpp v198, v140 row_shr:1 row_mask:0xf bank_mask:0xf
	v_mov_b32_dpp v199, v141 row_shr:1 row_mask:0xf bank_mask:0xf
	s_waitcnt vmcnt(0)
	s_bitcmp1_b32 s99, 8
	s_cbranch_scc1 .Lcw758_nostage
	v_and_b32_e32 v107, 0xff, v219
	v_lshlrev_b32_e32 v107, 4, v107
	v_add_u32_e32 v107, 0x22000, v107
	v_and_b32_e32 v104, 4, v219
	v_cmp_ne_u32_e64 s[100:101], 0, v104
	v_mov_b32_e32 v104, 0xbf317218
	v_mov_b32_e32 v105, 0xbfb8aa3b
	s_nop 0
	v_cndmask_b32_e64 v104, v104, v105, s[100:101]
	v_mov_b32_e32 v105, v104
	v_pk_mul_f32 v[108:109], v[108:109], v[104:105]
	v_pk_mul_f32 v[110:111], v[110:111], v[104:105]
	ds_write_b128 v107, v[108:111]

; #define LAS __attribute__((address_space(3)))
; __device__ __forceinline__ float sigmoidf_(float x) { return __builtin_amdgcn_rcpf(1.0f + __expf(-x)); }
;     __device__ __forceinline__ void operator()(AccRef acc, const Unit& u, int wr, int wc, int fr, int fq) const {
;     ...
;                 f32x4 h2v = (f32x4){0.f, 0.f, 0.f, 0.f}, h3v = h2v, h2g = h2v, h3g = h2v;
;                 const int pb = ai * 2 + wr - 1;
;                 if (pb >= 0 && fr == 0) { const LAS float* xp = xch + (pb * 2) * 256 + clb + 4 * n;
;                     h2v = *(const LAS f32x4*)(xp); h3v = *(const LAS f32x4*)(xp + 256); h2g = *(const LAS f32x4*)(xp + 128); h3g = *(const LAS f32x4*)(xp + 256 + 128); }
;                 float o[4][4];
; #pragma unroll
;                 for (int j = 0; j < 4; ++j) {
;                     const float v0 = acc[ai][0][0][n][j], v1 = acc[ai][0][1][n][j], v2 = acc[ai][0][2][n][j], v3 = acc[ai][0][3][n][j];
;                     const float g0 = acc[ai][1][0][n][j], g1 = acc[ai][1][1][n][j], g2 = acc[ai][1][2][n][j], g3 = acc[ai][1][3][n][j];
;                     const float pv3 = dpp_upd<0x111>(h3v[j], v3), pv2 = dpp_upd<0x111>(h2v[j], v2), pg3 = dpp_upd<0x111>(h3g[j], g3), pg2 = dpp_upd<0x111>(h2g[j], g2);
;                     const float hv0 = bvv[j] + w2v[j] * v0 + w1v[j] * pv3 + w0v[j] * pv2, hv1 = bvv[j] + w2v[j] * v1 + w1v[j] * v0 + w0v[j] * pv3;
;                     const float hv2 = bvv[j] + w2v[j] * v2 + w1v[j] * v1 + w0v[j] * v0, hv3 = bvv[j] + w2v[j] * v3 + w1v[j] * v2 + w0v[j] * v1;
;                     const float hg0 = bvg[j] + w2g[j] * g0 + w1g[j] * pg3 + w0g[j] * pg2, hg1 = bvg[j] + w2g[j] * g1 + w1g[j] * g0 + w0g[j] * pg3;
;                     const float hg2 = bvg[j] + w2g[j] * g2 + w1g[j] * g1 + w0g[j] * g0, hg3 = bvg[j] + w2g[j] * g3 + w1g[j] * g2 + w0g[j] * g1;
;                     o[0][j] = hg0 * sigmoidf_(hg0) * hv0; o[1][j] = hg1 * sigmoidf_(hg1) * hv1; o[2][j] = hg2 * sigmoidf_(hg2) * hv2; o[3][j] = hg3 * sigmoidf_(hg3) * hv3; }
; #pragma unroll
;                 for (int m = 0; m < 4; ++m) { u32x2 w; w.x = cvt_pk_bf16(o[m][0], o[m][1]); w.y = cvt_pk_bf16(o[m][2], o[m][3]);
;                     *(u32x2*)(Aout + (size_t)(row0 + ai * 128 + m) * FH + hc0 + 4 * n) = w; } } }
.LBB0_765:
	s_or_b64 exec, exec, s[46:47]
	v_pk_fma_f32 v[248:249], v[152:153], v[184:185], v[188:189]
	v_mov_b32_dpp v206, v128 row_shr:1 row_mask:0xf bank_mask:0xf
	v_mov_b32_dpp v207, v129 row_shr:1 row_mask:0xf bank_mask:0xf
	v_pk_fma_f32 v[248:249], v[180:181], v[198:199], v[248:249]
	v_mov_b32_dpp v194, v148 row_shr:1 row_mask:0xf bank_mask:0xf
	v_pk_fma_f32 v[206:207], v[176:177], v[206:207], v[248:249]
	v_mov_b32_dpp v195, v149 row_shr:1 row_mask:0xf bank_mask:0xf
	v_exp_f32_e32 v193, v206
	v_exp_f32_e32 v247, v207
	v_pk_fma_f32 v[250:251], v[156:157], v[168:169], v[172:173]
	v_add_f32_e32 v193, 1.0, v193
	v_rcp_f32_e32 v248, v193
	v_add_f32_e32 v193, 1.0, v247
	v_rcp_f32_e32 v249, v193
	v_mov_b32_dpp v202, v136 row_shr:1 row_mask:0xf bank_mask:0xf
	v_mov_b32_dpp v203, v137 row_shr:1 row_mask:0xf bank_mask:0xf
	v_pk_fma_f32 v[250:251], v[164:165], v[194:195], v[250:251]
	v_pk_mul_f32 v[206:207], v[206:207], v[248:249]
	v_pk_fma_f32 v[202:203], v[160:161], v[202:203], v[250:251]
	v_mov_b32_dpp v200, v142 row_shr:1 row_mask:0xf bank_mask:0xf
	v_mov_b32_dpp v201, v143 row_shr:1 row_mask:0xf bank_mask:0xf
	v_pk_mul_f32 v[202:203], v[202:203], v[206:207]
	v_pk_fma_f32 v[206:207], v[154:155], v[186:187], v[190:191]
	v_mov_b32_dpp v208, v130 row_shr:1 row_mask:0xf bank_mask:0xf
	v_mov_b32_dpp v209, v131 row_shr:1 row_mask:0xf bank_mask:0xf
	v_pk_fma_f32 v[206:207], v[182:183], v[200:201], v[206:207]
	v_mov_b32_dpp v196, v150 row_shr:1 row_mask:0xf bank_mask:0xf
	v_pk_fma_f32 v[206:207], v[178:179], v[208:209], v[206:207]
	v_mov_b32_dpp v197, v151 row_shr:1 row_mask:0xf bank_mask:0xf
	v_exp_f32_e32 v193, v206
	v_exp_f32_e32 v209, v207
	v_cvt_pk_bf16_f32 v208, v202, v203
	v_add_f32_e32 v193, 1.0, v193
	v_rcp_f32_e32 v202, v193
	v_add_f32_e32 v193, 1.0, v209
	v_rcp_f32_e32 v203, v193
	v_pk_fma_f32 v[248:249], v[158:159], v[170:171], v[174:175]
	v_mov_b32_dpp v204, v138 row_shr:1 row_mask:0xf bank_mask:0xf
	v_mov_b32_dpp v205, v139 row_shr:1 row_mask:0xf bank_mask:0xf
	v_pk_fma_f32 v[248:249], v[166:167], v[196:197], v[248:249]
	v_pk_mul_f32 v[202:203], v[206:207], v[202:203]
	v_pk_fma_f32 v[204:205], v[162:163], v[204:205], v[248:249]
	v_lshl_add_u32 v246, s40, 8, v236
	v_pk_mul_f32 v[202:203], v[204:205], v[202:203]
	v_lshlrev_b64 v[204:205], 1, v[232:233]
	v_pk_fma_f32 v[232:233], v[132:133], v[184:185], v[188:189]
	v_mov_b64_e32 v[206:207], s[60:61]
	v_pk_fma_f32 v[232:233], v[152:153], v[180:181], v[232:233]
	v_cvt_pk_bf16_f32 v209, v202, v203
	v_pk_fma_f32 v[198:199], v[176:177], v[198:199], v[232:233]
	v_mad_i64_i32 v[202:203], s[40:41], v246, s76, v[206:207]
	v_exp_f32_e32 v193, v198
	v_exp_f32_e32 v232, v199
	v_lshl_add_u64 v[202:203], v[202:203], 0, v[204:205]
	v_add_f32_e32 v193, 1.0, v193
	v_mov_b32_e32 v247, v208
	v_mov_b32_e32 v248, v209
	v_rcp_f32_e32 v208, v193
	v_add_f32_e32 v193, 1.0, v232
	v_rcp_f32_e32 v209, v193
	v_pk_fma_f32 v[232:233], v[144:145], v[168:169], v[172:173]
	v_pk_fma_f32 v[140:141], v[140:141], v[184:185], v[188:189]
	v_pk_fma_f32 v[232:233], v[156:157], v[164:165], v[232:233]
	v_pk_mul_f32 v[198:199], v[198:199], v[208:209]
	v_pk_fma_f32 v[194:195], v[160:161], v[194:195], v[232:233]
	v_pk_fma_f32 v[208:209], v[146:147], v[170:171], v[174:175]
	v_pk_mul_f32 v[194:195], v[194:195], v[198:199]
	v_pk_fma_f32 v[198:199], v[134:135], v[186:187], v[190:191]
	v_pk_fma_f32 v[208:209], v[158:159], v[166:167], v[208:209]
	v_pk_fma_f32 v[198:199], v[154:155], v[182:183], v[198:199]
	v_pk_fma_f32 v[196:197], v[162:163], v[196:197], v[208:209]
	v_pk_fma_f32 v[198:199], v[178:179], v[200:201], v[198:199]
	v_cvt_pk_bf16_f32 v194, v194, v195
	v_exp_f32_e32 v193, v198
	v_exp_f32_e32 v201, v199
	v_pk_fma_f32 v[148:149], v[148:149], v[168:169], v[172:173]
	v_add_f32_e32 v193, 1.0, v193
	v_rcp_f32_e32 v200, v193
	v_add_f32_e32 v193, 1.0, v201
	v_rcp_f32_e32 v201, v193
	v_or_b32_e32 v193, 1, v246
	v_pk_mul_f32 v[198:199], v[198:199], v[200:201]
	s_nop 0
	v_pk_mul_f32 v[196:197], v[196:197], v[198:199]
	v_pk_fma_f32 v[198:199], v[128:129], v[184:185], v[188:189]
	v_cvt_pk_bf16_f32 v195, v196, v197
	v_pk_fma_f32 v[198:199], v[132:133], v[180:181], v[198:199]
	v_mad_i64_i32 v[196:197], s[40:41], v193, s76, v[206:207]
	v_pk_fma_f32 v[152:153], v[152:153], v[176:177], v[198:199]
	v_lshl_add_u64 v[196:197], v[196:197], 0, v[204:205]
	v_exp_f32_e32 v193, v152
	v_exp_f32_e32 v198, v153
	v_mov_b32_e32 v249, v194
	v_mov_b32_e32 v250, v195
	v_add_f32_e32 v193, 1.0, v193
	v_rcp_f32_e32 v194, v193
	v_add_f32_e32 v193, 1.0, v198
	v_rcp_f32_e32 v195, v193
	v_pk_fma_f32 v[198:199], v[136:137], v[168:169], v[172:173]
	v_pk_fma_f32 v[128:129], v[128:129], v[180:181], v[140:141]
	v_pk_fma_f32 v[198:199], v[144:145], v[164:165], v[198:199]
	v_pk_fma_f32 v[128:129], v[132:133], v[176:177], v[128:129]
	v_pk_fma_f32 v[156:157], v[156:157], v[160:161], v[198:199]
	v_pk_mul_f32 v[152:153], v[152:153], v[194:195]
	v_pk_mul_f32 v[152:153], v[156:157], v[152:153]
	v_pk_fma_f32 v[156:157], v[130:131], v[186:187], v[190:191]
	v_exp_f32_e32 v140, v128
	v_pk_fma_f32 v[132:133], v[142:143], v[186:187], v[190:191]
	v_pk_fma_f32 v[156:157], v[134:135], v[182:183], v[156:157]
	v_pk_fma_f32 v[130:131], v[130:131], v[182:183], v[132:133]
	v_pk_fma_f32 v[154:155], v[154:155], v[178:179], v[156:157]
	v_pk_fma_f32 v[130:131], v[134:135], v[178:179], v[130:131]
	v_exp_f32_e32 v157, v154
	v_exp_f32_e32 v141, v129
	v_exp_f32_e32 v132, v130
	v_exp_f32_e32 v133, v131
	v_exp_f32_e32 v193, v155
	v_add_f32_e32 v140, 1.0, v140
	v_add_f32_e32 v141, 1.0, v141
	v_add_f32_e32 v132, 1.0, v132
	v_add_f32_e32 v133, 1.0, v133
	v_cvt_pk_bf16_f32 v156, v152, v153
	v_add_f32_e32 v152, 1.0, v157
; #define LAS __attribute__((address_space(3)))
; __device__ __forceinline__ float sigmoidf_(float x) { return __builtin_amdgcn_rcpf(1.0f + __expf(-x)); }
;     __device__ __forceinline__ void operator()(AccRef acc, const Unit& u, int wr, int wc, int fr, int fq) const {
;     ...
;                 f32x4 h2v = (f32x4){0.f, 0.f, 0.f, 0.f}, h3v = h2v, h2g = h2v, h3g = h2v;
;                 const int pb = ai * 2 + wr - 1;
;                 if (pb >= 0 && fr == 0) { const LAS float* xp = xch + (pb * 2) * 256 + clb + 4 * n;
;                     h2v = *(const LAS f32x4*)(xp); h3v = *(const LAS f32x4*)(xp + 256); h2g = *(const LAS f32x4*)(xp + 128); h3g = *(const LAS f32x4*)(xp + 256 + 128); }
;                 float o[4][4];
; #pragma unroll
;                 for (int j = 0; j < 4; ++j) {
;                     const float v0 = acc[ai][0][0][n][j], v1 = acc[ai][0][1][n][j], v2 = acc[ai][0][2][n][j], v3 = acc[ai][0][3][n][j];
;                     const float g0 = acc[ai][1][0][n][j], g1 = acc[ai][1][1][n][j], g2 = acc[ai][1][2][n][j], g3 = acc[ai][1][3][n][j];
;                     const float pv3 = dpp_upd<0x111>(h3v[j], v3), pv2 = dpp_upd<0x111>(h2v[j], v2), pg3 = dpp_upd<0x111>(h3g[j], g3), pg2 = dpp_upd<0x111>(h2g[j], g2);
;                     const float hv0 = bvv[j] + w2v[j] * v0 + w1v[j] * pv3 + w0v[j] * pv2, hv1 = bvv[j] + w2v[j] * v1 + w1v[j] * v0 + w0v[j] * pv3;
;                     const float hv2 = bvv[j] + w2v[j] * v2 + w1v[j] * v1 + w0v[j] * v0, hv3 = bvv[j] + w2v[j] * v3 + w1v[j] * v2 + w0v[j] * v1;
;                     const float hg0 = bvg[j] + w2g[j] * g0 + w1g[j] * pg3 + w0g[j] * pg2, hg1 = bvg[j] + w2g[j] * g1 + w1g[j] * g0 + w0g[j] * pg3;
;                     const float hg2 = bvg[j] + w2g[j] * g2 + w1g[j] * g1 + w0g[j] * g0, hg3 = bvg[j] + w2g[j] * g3 + w1g[j] * g2 + w0g[j] * g1;
;                     o[0][j] = hg0 * sigmoidf_(hg0) * hv0; o[1][j] = hg1 * sigmoidf_(hg1) * hv1; o[2][j] = hg2 * sigmoidf_(hg2) * hv2; o[3][j] = hg3 * sigmoidf_(hg3) * hv3; }
; #pragma unroll
;                 for (int m = 0; m < 4; ++m) { u32x2 w; w.x = cvt_pk_bf16(o[m][0], o[m][1]); w.y = cvt_pk_bf16(o[m][2], o[m][3]);
;                     *(u32x2*)(Aout + (size_t)(row0 + ai * 128 + m) * FH + hc0 + 4 * n) = w; } } }
	v_add_f32_e32 v153, 1.0, v193
	v_rcp_f32_e32 v140, v140
	v_rcp_f32_e32 v141, v141
	v_rcp_f32_e32 v132, v132
	v_rcp_f32_e32 v133, v133
	v_rcp_f32_e32 v152, v152
	v_rcp_f32_e32 v153, v153
	v_pk_fma_f32 v[142:143], v[150:151], v[170:171], v[174:175]
	v_pk_fma_f32 v[194:195], v[138:139], v[170:171], v[174:175]
	v_pk_fma_f32 v[136:137], v[136:137], v[164:165], v[148:149]
	v_pk_fma_f32 v[134:135], v[138:139], v[166:167], v[142:143]
	v_pk_fma_f32 v[194:195], v[146:147], v[166:167], v[194:195]
	v_pk_fma_f32 v[136:137], v[144:145], v[160:161], v[136:137]
	v_pk_mul_f32 v[128:129], v[128:129], v[140:141]
	v_pk_fma_f32 v[134:135], v[146:147], v[162:163], v[134:135]
	v_pk_mul_f32 v[130:131], v[130:131], v[132:133]
	v_pk_fma_f32 v[158:159], v[158:159], v[162:163], v[194:195]
	v_pk_mul_f32 v[152:153], v[154:155], v[152:153]
	v_pk_mul_f32 v[128:129], v[136:137], v[128:129]
	v_pk_mul_f32 v[130:131], v[134:135], v[130:131]
	v_pk_mul_f32 v[152:153], v[158:159], v[152:153]
	v_cvt_pk_bf16_f32 v128, v128, v129
	v_cvt_pk_bf16_f32 v129, v130, v131
	v_or_b32_e32 v130, 3, v246
	v_cvt_pk_bf16_f32 v157, v152, v153
	v_or_b32_e32 v152, 2, v246
	v_mad_i64_i32 v[130:131], s[40:41], v130, s76, v[206:207]
	v_mad_i64_i32 v[152:153], s[40:41], v152, s76, v[206:207]
	v_lshl_add_u64 v[140:141], v[130:131], 0, v[204:205]
	v_lshl_add_u64 v[152:153], v[152:153], 0, v[204:205]
	v_mov_b32_e32 v251, v128
	v_mov_b32_e32 v253, v129
	v_mov_b32_e32 v193, 0
	v_mov_b32_e32 v194, 0
	v_mov_b32_e32 v195, 0
	v_mov_b32_e32 v136, 0
	v_mov_b32_e32 v137, 0
	v_mov_b32_e32 v138, 0
	v_mov_b32_e32 v139, 0
	v_mov_b32_e32 v128, 0
	v_mov_b32_e32 v129, 0
	v_mov_b32_e32 v130, 0
	v_mov_b32_e32 v131, 0
	v_mov_b32_e32 v132, 0
	v_mov_b32_e32 v133, 0
	v_mov_b32_e32 v134, 0
	v_mov_b32_e32 v135, 0
	v_mov_b32_e32 v254, v156
	v_mov_b32_e32 v255, v157
	s_and_saveexec_b64 s[40:41], s[28:29]
	s_cbranch_execz .LBB0_769
	ds_read_b128 v[132:135], v237 offset:2048
	ds_read_b128 v[136:139], v237 offset:2560
	ds_read_b128 v[128:131], v237 offset:3072
	ds_read_b128 v[192:195], v237 offset:3584
.LBB0_769:
	s_or_b64 exec, exec, s[40:41]
	s_waitcnt lgkmcnt(0)
	v_mov_b32_dpp v192, v72 row_shr:1 row_mask:0xf bank_mask:0xf
	v_mov_b32_dpp v193, v73 row_shr:1 row_mask:0xf bank_mask:0xf
	v_pk_fma_f32 v[142:143], v[88:89], v[184:185], v[188:189]
	v_mov_b32_dpp v136, v64 row_shr:1 row_mask:0xf bank_mask:0xf
	v_mov_b32_dpp v137, v65 row_shr:1 row_mask:0xf bank_mask:0xf
	v_pk_fma_f32 v[142:143], v[180:181], v[192:193], v[142:143]
	v_mov_b32_dpp v128, v84 row_shr:1 row_mask:0xf bank_mask:0xf
	v_pk_fma_f32 v[136:137], v[176:177], v[136:137], v[142:143]
	v_mov_b32_dpp v129, v85 row_shr:1 row_mask:0xf bank_mask:0xf
	v_exp_f32_e32 v142, v136
	v_exp_f32_e32 v143, v137
	v_pk_fma_f32 v[144:145], v[92:93], v[168:169], v[172:173]
	v_mov_b32_dpp v132, v76 row_shr:1 row_mask:0xf bank_mask:0xf
	v_add_f32_e32 v142, 1.0, v142
	v_add_f32_e32 v143, 1.0, v143
	v_rcp_f32_e32 v142, v142
	v_rcp_f32_e32 v143, v143
	v_mov_b32_dpp v133, v77 row_shr:1 row_mask:0xf bank_mask:0xf
	v_pk_fma_f32 v[144:145], v[164:165], v[128:129], v[144:145]
	v_mov_b32_dpp v194, v74 row_shr:1 row_mask:0xf bank_mask:0xf
	v_pk_fma_f32 v[132:133], v[160:161], v[132:133], v[144:145]
	v_pk_mul_f32 v[136:137], v[136:137], v[142:143]
	v_mov_b32_dpp v195, v75 row_shr:1 row_mask:0xf bank_mask:0xf
	v_pk_mul_f32 v[132:133], v[132:133], v[136:137]
	v_pk_fma_f32 v[136:137], v[90:91], v[186:187], v[190:191]
	v_mov_b32_dpp v138, v66 row_shr:1 row_mask:0xf bank_mask:0xf
	v_mov_b32_dpp v139, v67 row_shr:1 row_mask:0xf bank_mask:0xf
	v_pk_fma_f32 v[136:137], v[182:183], v[194:195], v[136:137]
	v_mov_b32_dpp v130, v86 row_shr:1 row_mask:0xf bank_mask:0xf
	v_pk_fma_f32 v[136:137], v[178:179], v[138:139], v[136:137]
	v_mov_b32_dpp v131, v87 row_shr:1 row_mask:0xf bank_mask:0xf
	v_exp_f32_e32 v139, v136
	v_exp_f32_e32 v142, v137
	v_cvt_pk_bf16_f32 v138, v132, v133
	v_add_f32_e32 v132, 1.0, v139
	v_rcp_f32_e32 v132, v132
	v_add_f32_e32 v133, 1.0, v142
	v_rcp_f32_e32 v133, v133
	v_pk_fma_f32 v[142:143], v[94:95], v[170:171], v[174:175]
	v_mov_b32_dpp v134, v78 row_shr:1 row_mask:0xf bank_mask:0xf
	v_mov_b32_dpp v135, v79 row_shr:1 row_mask:0xf bank_mask:0xf
	v_pk_mul_f32 v[132:133], v[136:137], v[132:133]
	v_pk_fma_f32 v[136:137], v[68:69], v[184:185], v[188:189]
	v_pk_fma_f32 v[142:143], v[166:167], v[130:131], v[142:143]
	v_pk_fma_f32 v[136:137], v[88:89], v[180:181], v[136:137]
	v_pk_fma_f32 v[134:135], v[162:163], v[134:135], v[142:143]
	v_pk_fma_f32 v[136:137], v[176:177], v[192:193], v[136:137]
	v_add_u32_e32 v146, 0x80, v246
	v_exp_f32_e32 v142, v136
	v_exp_f32_e32 v143, v137
	v_pk_mul_f32 v[132:133], v[134:135], v[132:133]
	v_mov_b64_e32 v[134:135], s[60:61]
	v_cvt_pk_bf16_f32 v139, v132, v133
	v_mad_i64_i32 v[132:133], s[40:41], v146, s76, v[134:135]
	v_lshl_add_u64 v[132:133], v[132:133], 0, v[204:205]
	v_mov_b32_e32 v144, v138
	v_mov_b32_e32 v145, v139
	v_add_f32_e32 v138, 1.0, v142
	v_add_f32_e32 v139, 1.0, v143
	v_rcp_f32_e32 v138, v138
	v_rcp_f32_e32 v139, v139
	v_pk_fma_f32 v[142:143], v[80:81], v[168:169], v[172:173]
	v_pk_fma_f32 v[72:73], v[72:73], v[184:185], v[188:189]
	v_pk_fma_f32 v[142:143], v[92:93], v[164:165], v[142:143]
	v_pk_mul_f32 v[136:137], v[136:137], v[138:139]
	v_pk_fma_f32 v[128:129], v[160:161], v[128:129], v[142:143]
	v_pk_fma_f32 v[84:85], v[84:85], v[168:169], v[172:173]
	v_pk_mul_f32 v[128:129], v[128:129], v[136:137]
	v_pk_fma_f32 v[136:137], v[70:71], v[186:187], v[190:191]
	s_nop 0
	v_pk_fma_f32 v[136:137], v[90:91], v[182:183], v[136:137]
	s_nop 0
	v_pk_fma_f32 v[136:137], v[178:179], v[194:195], v[136:137]
	s_nop 0
	v_exp_f32_e32 v139, v136
; #define LAS __attribute__((address_space(3)))
; __device__ __forceinline__ float sigmoidf_(float x) { return __builtin_amdgcn_rcpf(1.0f + __expf(-x)); }
;     __device__ __forceinline__ void operator()(AccRef acc, const Unit& u, int wr, int wc, int fr, int fq) const {
;     ...
;                 f32x4 h2v = (f32x4){0.f, 0.f, 0.f, 0.f}, h3v = h2v, h2g = h2v, h3g = h2v;
;                 const int pb = ai * 2 + wr - 1;
;                 if (pb >= 0 && fr == 0) { const LAS float* xp = xch + (pb * 2) * 256 + clb + 4 * n;
;                     h2v = *(const LAS f32x4*)(xp); h3v = *(const LAS f32x4*)(xp + 256); h2g = *(const LAS f32x4*)(xp + 128); h3g = *(const LAS f32x4*)(xp + 256 + 128); }
;                 float o[4][4];
; #pragma unroll
;                 for (int j = 0; j < 4; ++j) {
;                     const float v0 = acc[ai][0][0][n][j], v1 = acc[ai][0][1][n][j], v2 = acc[ai][0][2][n][j], v3 = acc[ai][0][3][n][j];
;                     const float g0 = acc[ai][1][0][n][j], g1 = acc[ai][1][1][n][j], g2 = acc[ai][1][2][n][j], g3 = acc[ai][1][3][n][j];
;                     const float pv3 = dpp_upd<0x111>(h3v[j], v3), pv2 = dpp_upd<0x111>(h2v[j], v2), pg3 = dpp_upd<0x111>(h3g[j], g3), pg2 = dpp_upd<0x111>(h2g[j], g2);
;                     const float hv0 = bvv[j] + w2v[j] * v0 + w1v[j] * pv3 + w0v[j] * pv2, hv1 = bvv[j] + w2v[j] * v1 + w1v[j] * v0 + w0v[j] * pv3;
;                     const float hv2 = bvv[j] + w2v[j] * v2 + w1v[j] * v1 + w0v[j] * v0, hv3 = bvv[j] + w2v[j] * v3 + w1v[j] * v2 + w0v[j] * v1;
;                     const float hg0 = bvg[j] + w2g[j] * g0 + w1g[j] * pg3 + w0g[j] * pg2, hg1 = bvg[j] + w2g[j] * g1 + w1g[j] * g0 + w0g[j] * pg3;
;                     const float hg2 = bvg[j] + w2g[j] * g2 + w1g[j] * g1 + w0g[j] * g0, hg3 = bvg[j] + w2g[j] * g3 + w1g[j] * g2 + w0g[j] * g1;
;                     o[0][j] = hg0 * sigmoidf_(hg0) * hv0; o[1][j] = hg1 * sigmoidf_(hg1) * hv1; o[2][j] = hg2 * sigmoidf_(hg2) * hv2; o[3][j] = hg3 * sigmoidf_(hg3) * hv3; }
; #pragma unroll
;                 for (int m = 0; m < 4; ++m) { u32x2 w; w.x = cvt_pk_bf16(o[m][0], o[m][1]); w.y = cvt_pk_bf16(o[m][2], o[m][3]);
;                     *(u32x2*)(Aout + (size_t)(row0 + ai * 128 + m) * FH + hc0 + 4 * n) = w; } } }
	v_exp_f32_e32 v142, v137
	v_cvt_pk_bf16_f32 v138, v128, v129
	v_add_f32_e32 v128, 1.0, v139
	v_rcp_f32_e32 v128, v128
	v_add_f32_e32 v129, 1.0, v142
	v_rcp_f32_e32 v129, v129
	v_pk_fma_f32 v[142:143], v[82:83], v[170:171], v[174:175]
	v_pk_mul_f32 v[128:129], v[136:137], v[128:129]
	v_pk_fma_f32 v[142:143], v[94:95], v[166:167], v[142:143]
	v_pk_fma_f32 v[136:137], v[76:77], v[168:169], v[172:173]
	v_pk_fma_f32 v[130:131], v[162:163], v[130:131], v[142:143]
	v_pk_fma_f32 v[136:137], v[80:81], v[164:165], v[136:137]
	v_pk_mul_f32 v[128:129], v[130:131], v[128:129]
	v_pk_fma_f32 v[130:131], v[64:65], v[184:185], v[188:189]
	v_pk_fma_f32 v[64:65], v[64:65], v[180:181], v[72:73]
	v_pk_fma_f32 v[130:131], v[68:69], v[180:181], v[130:131]
	v_pk_fma_f32 v[64:65], v[68:69], v[176:177], v[64:65]
	v_pk_fma_f32 v[88:89], v[88:89], v[176:177], v[130:131]
	v_pk_fma_f32 v[92:93], v[92:93], v[160:161], v[136:137]
	v_exp_f32_e32 v130, v88
	v_exp_f32_e32 v131, v89
	v_exp_f32_e32 v72, v64
	v_add_f32_e32 v130, 1.0, v130
	v_add_f32_e32 v131, 1.0, v131
	v_rcp_f32_e32 v130, v130
	v_rcp_f32_e32 v131, v131
	v_pk_fma_f32 v[68:69], v[74:75], v[186:187], v[190:191]
	v_exp_f32_e32 v73, v65
	v_pk_mul_f32 v[88:89], v[88:89], v[130:131]
	v_add_f32_e32 v72, 1.0, v72
	v_pk_mul_f32 v[88:89], v[92:93], v[88:89]
	v_pk_fma_f32 v[92:93], v[66:67], v[186:187], v[190:191]
	v_pk_fma_f32 v[66:67], v[66:67], v[182:183], v[68:69]
	v_pk_fma_f32 v[92:93], v[70:71], v[182:183], v[92:93]
	v_pk_fma_f32 v[66:67], v[70:71], v[178:179], v[66:67]
	v_pk_fma_f32 v[90:91], v[90:91], v[178:179], v[92:93]
	v_exp_f32_e32 v93, v90
	v_exp_f32_e32 v68, v66
	v_exp_f32_e32 v69, v67
	v_exp_f32_e32 v130, v91
	v_add_f32_e32 v73, 1.0, v73
	v_add_f32_e32 v68, 1.0, v68
	v_add_f32_e32 v69, 1.0, v69
	v_cvt_pk_bf16_f32 v92, v88, v89
	v_add_f32_e32 v88, 1.0, v93
	v_add_f32_e32 v89, 1.0, v130
	v_rcp_f32_e32 v72, v72
	v_rcp_f32_e32 v73, v73
	v_rcp_f32_e32 v68, v68
	v_rcp_f32_e32 v69, v69
	v_rcp_f32_e32 v88, v88
	v_rcp_f32_e32 v89, v89
	v_pk_fma_f32 v[74:75], v[86:87], v[170:171], v[174:175]
	v_pk_fma_f32 v[130:131], v[78:79], v[170:171], v[174:175]
	v_pk_fma_f32 v[76:77], v[76:77], v[164:165], v[84:85]
	v_pk_fma_f32 v[70:71], v[78:79], v[166:167], v[74:75]
	v_pk_fma_f32 v[130:131], v[82:83], v[166:167], v[130:131]
	v_pk_fma_f32 v[76:77], v[80:81], v[160:161], v[76:77]
	v_pk_mul_f32 v[64:65], v[64:65], v[72:73]
	v_pk_fma_f32 v[70:71], v[82:83], v[162:163], v[70:71]
	v_pk_mul_f32 v[66:67], v[66:67], v[68:69]
	v_pk_fma_f32 v[94:95], v[94:95], v[162:163], v[130:131]
	v_pk_mul_f32 v[88:89], v[90:91], v[88:89]
	v_pk_mul_f32 v[64:65], v[76:77], v[64:65]
	v_pk_mul_f32 v[66:67], v[70:71], v[66:67]
	v_pk_mul_f32 v[88:89], v[94:95], v[88:89]
	v_cvt_pk_bf16_f32 v64, v64, v65
	v_cvt_pk_bf16_f32 v65, v66, v67
	v_add_u32_e32 v66, 0x83, v246
	v_cvt_pk_bf16_f32 v139, v128, v129
	v_add_u32_e32 v128, 0x81, v246
	v_cvt_pk_bf16_f32 v93, v88, v89
	v_add_u32_e32 v88, 0x82, v246
	v_mad_i64_i32 v[66:67], s[40:41], v66, s76, v[134:135]
	v_mad_i64_i32 v[128:129], s[40:41], v128, s76, v[134:135]
	v_mad_i64_i32 v[88:89], s[40:41], v88, s76, v[134:135]
	v_lshl_add_u64 v[82:83], v[66:67], 0, v[204:205]
	v_lshl_add_u64 v[128:129], v[128:129], 0, v[204:205]
	v_lshl_add_u64 v[88:89], v[88:89], 0, v[204:205]
	v_mov_b32_e32 v148, v64
	v_mov_b32_e32 v149, v65
	v_mov_b32_e32 v64, 0
	v_mov_b32_e32 v70, 0
	v_mov_b32_e32 v71, 0
	v_mov_b32_e32 v72, 0
	v_mov_b32_e32 v73, 0
	v_mov_b32_e32 v78, 0
	v_mov_b32_e32 v79, 0
	v_mov_b32_e32 v80, 0
	v_mov_b32_e32 v81, 0
	v_mov_b32_e32 v66, 0
	v_mov_b32_e32 v67, 0
	v_mov_b32_e32 v68, 0
	v_mov_b32_e32 v69, 0
	v_mov_b32_e32 v74, 0
	v_mov_b32_e32 v75, 0
	v_mov_b32_e32 v76, 0
	v_mov_b32_e32 v77, 0
	v_mov_b32_e32 v154, v138
	v_mov_b32_e32 v155, v139
	v_mov_b32_e32 v198, v92
	v_mov_b32_e32 v199, v93
	s_and_saveexec_b64 s[40:41], s[26:27]
	s_cbranch_execz .LBB0_771
	ds_read_b128 v[74:77], v242
	ds_read_b128 v[66:69], v241
	ds_read_b128 v[78:81], v240
	ds_read_b128 v[70:73], v239
.LBB0_771:
	s_or_b64 exec, exec, s[40:41]
	s_waitcnt lgkmcnt(0)
	v_mov_b32_dpp v70, v44 row_shr:1 row_mask:0xf bank_mask:0xf
	v_mov_b32_dpp v71, v45 row_shr:1 row_mask:0xf bank_mask:0xf
	s_waitcnt vmcnt(0)
; #define LAS __attribute__((address_space(3)))
; __device__ __forceinline__ float sigmoidf_(float x) { return __builtin_amdgcn_rcpf(1.0f + __expf(-x)); }
;     __device__ __forceinline__ void operator()(AccRef acc, const Unit& u, int wr, int wc, int fr, int fq) const {
;     ...
;                 f32x4 h2v = (f32x4){0.f, 0.f, 0.f, 0.f}, h3v = h2v, h2g = h2v, h3g = h2v;
;                 const int pb = ai * 2 + wr - 1;
;                 if (pb >= 0 && fr == 0) { const LAS float* xp = xch + (pb * 2) * 256 + clb + 4 * n;
;                     h2v = *(const LAS f32x4*)(xp); h3v = *(const LAS f32x4*)(xp + 256); h2g = *(const LAS f32x4*)(xp + 128); h3g = *(const LAS f32x4*)(xp + 256 + 128); }
;                 float o[4][4];
; #pragma unroll
;                 for (int j = 0; j < 4; ++j) {
;                     const float v0 = acc[ai][0][0][n][j], v1 = acc[ai][0][1][n][j], v2 = acc[ai][0][2][n][j], v3 = acc[ai][0][3][n][j];
;                     const float g0 = acc[ai][1][0][n][j], g1 = acc[ai][1][1][n][j], g2 = acc[ai][1][2][n][j], g3 = acc[ai][1][3][n][j];
;                     const float pv3 = dpp_upd<0x111>(h3v[j], v3), pv2 = dpp_upd<0x111>(h2v[j], v2), pg3 = dpp_upd<0x111>(h3g[j], g3), pg2 = dpp_upd<0x111>(h2g[j], g2);
;                     const float hv0 = bvv[j] + w2v[j] * v0 + w1v[j] * pv3 + w0v[j] * pv2, hv1 = bvv[j] + w2v[j] * v1 + w1v[j] * v0 + w0v[j] * pv3;
;                     const float hv2 = bvv[j] + w2v[j] * v2 + w1v[j] * v1 + w0v[j] * v0, hv3 = bvv[j] + w2v[j] * v3 + w1v[j] * v2 + w0v[j] * v1;
;                     const float hg0 = bvg[j] + w2g[j] * g0 + w1g[j] * pg3 + w0g[j] * pg2, hg1 = bvg[j] + w2g[j] * g1 + w1g[j] * g0 + w0g[j] * pg3;
;                     const float hg2 = bvg[j] + w2g[j] * g2 + w1g[j] * g1 + w0g[j] * g0, hg3 = bvg[j] + w2g[j] * g3 + w1g[j] * g2 + w0g[j] * g1;
;                     o[0][j] = hg0 * sigmoidf_(hg0) * hv0; o[1][j] = hg1 * sigmoidf_(hg1) * hv1; o[2][j] = hg2 * sigmoidf_(hg2) * hv2; o[3][j] = hg3 * sigmoidf_(hg3) * hv3; }
; #pragma unroll
;                 for (int m = 0; m < 4; ++m) { u32x2 w; w.x = cvt_pk_bf16(o[m][0], o[m][1]); w.y = cvt_pk_bf16(o[m][2], o[m][3]);
;                     *(u32x2*)(Aout + (size_t)(row0 + ai * 128 + m) * FH + hc0 + 4 * n) = w; } } }
	v_pk_fma_f32 v[84:85], v[56:57], v[120:121], v[124:125]
	v_mov_b32_dpp v78, v32 row_shr:1 row_mask:0xf bank_mask:0xf
	v_mov_b32_dpp v79, v33 row_shr:1 row_mask:0xf bank_mask:0xf
	v_pk_fma_f32 v[84:85], v[116:117], v[70:71], v[84:85]
	v_mov_b32_dpp v66, v52 row_shr:1 row_mask:0xf bank_mask:0xf
	v_pk_fma_f32 v[78:79], v[112:113], v[78:79], v[84:85]
	v_mov_b32_dpp v67, v53 row_shr:1 row_mask:0xf bank_mask:0xf
	v_exp_f32_e32 v65, v78
	v_exp_f32_e32 v85, v79
	v_pk_fma_f32 v[86:87], v[60:61], v[104:105], v[108:109]
	v_add_f32_e32 v65, 1.0, v65
	v_rcp_f32_e32 v84, v65
	v_add_f32_e32 v65, 1.0, v85
	v_rcp_f32_e32 v85, v65
	v_mov_b32_dpp v74, v40 row_shr:1 row_mask:0xf bank_mask:0xf
	v_mov_b32_dpp v75, v41 row_shr:1 row_mask:0xf bank_mask:0xf
	v_pk_fma_f32 v[86:87], v[100:101], v[66:67], v[86:87]
	v_pk_mul_f32 v[78:79], v[78:79], v[84:85]
	v_pk_fma_f32 v[74:75], v[96:97], v[74:75], v[86:87]
	v_mov_b32_dpp v72, v46 row_shr:1 row_mask:0xf bank_mask:0xf
	v_mov_b32_dpp v73, v47 row_shr:1 row_mask:0xf bank_mask:0xf
	v_pk_mul_f32 v[74:75], v[74:75], v[78:79]
	v_pk_fma_f32 v[78:79], v[58:59], v[122:123], v[126:127]
	v_mov_b32_dpp v80, v34 row_shr:1 row_mask:0xf bank_mask:0xf
	v_mov_b32_dpp v81, v35 row_shr:1 row_mask:0xf bank_mask:0xf
	v_pk_fma_f32 v[78:79], v[118:119], v[72:73], v[78:79]
	v_mov_b32_dpp v68, v54 row_shr:1 row_mask:0xf bank_mask:0xf
	v_pk_fma_f32 v[78:79], v[114:115], v[80:81], v[78:79]
	v_mov_b32_dpp v69, v55 row_shr:1 row_mask:0xf bank_mask:0xf
	v_exp_f32_e32 v65, v78
	v_exp_f32_e32 v81, v79
	v_pk_fma_f32 v[84:85], v[62:63], v[106:107], v[110:111]
	v_add_f32_e32 v65, 1.0, v65
	v_rcp_f32_e32 v80, v65
	v_add_f32_e32 v65, 1.0, v81
	v_rcp_f32_e32 v81, v65
	v_mov_b32_dpp v76, v42 row_shr:1 row_mask:0xf bank_mask:0xf
	v_mov_b32_dpp v77, v43 row_shr:1 row_mask:0xf bank_mask:0xf
	v_pk_fma_f32 v[84:85], v[102:103], v[68:69], v[84:85]
	v_pk_mul_f32 v[78:79], v[78:79], v[80:81]
	v_pk_fma_f32 v[76:77], v[98:99], v[76:77], v[84:85]
	v_cvt_pk_bf16_f32 v74, v74, v75
	v_pk_mul_f32 v[76:77], v[76:77], v[78:79]
	v_pk_fma_f32 v[44:45], v[44:45], v[120:121], v[124:125]
	v_cvt_pk_bf16_f32 v75, v76, v77
	v_pk_fma_f32 v[76:77], v[36:37], v[120:121], v[124:125]
	v_mov_b32_e32 v90, v247
	v_mov_b32_e32 v91, v248
	v_mov_b32_e32 v92, v74
	v_mov_b32_e32 v93, v75
	global_store_dwordx4 v[202:203], v[90:93], off
	v_pk_fma_f32 v[76:77], v[56:57], v[116:117], v[76:77]
	v_pk_fma_f32 v[52:53], v[52:53], v[104:105], v[108:109]
	v_pk_fma_f32 v[70:71], v[112:113], v[70:71], v[76:77]
	s_nop 0
	v_exp_f32_e32 v65, v70
	v_exp_f32_e32 v76, v71
	v_add_f32_e32 v65, 1.0, v65
	v_rcp_f32_e32 v74, v65
	v_add_f32_e32 v65, 1.0, v76
	v_rcp_f32_e32 v75, v65
	v_pk_fma_f32 v[76:77], v[48:49], v[104:105], v[108:109]
	v_pk_mul_f32 v[70:71], v[70:71], v[74:75]
	v_pk_fma_f32 v[76:77], v[60:61], v[100:101], v[76:77]
	v_pk_fma_f32 v[74:75], v[50:51], v[106:107], v[110:111]
	v_pk_fma_f32 v[66:67], v[96:97], v[66:67], v[76:77]
	v_pk_fma_f32 v[74:75], v[62:63], v[102:103], v[74:75]
	v_pk_mul_f32 v[66:67], v[66:67], v[70:71]
	v_pk_fma_f32 v[70:71], v[38:39], v[122:123], v[126:127]
	v_pk_fma_f32 v[68:69], v[98:99], v[68:69], v[74:75]
	v_pk_fma_f32 v[70:71], v[58:59], v[118:119], v[70:71]
	v_cvt_pk_bf16_f32 v66, v66, v67
	v_pk_fma_f32 v[70:71], v[114:115], v[72:73], v[70:71]
	s_nop 0
	v_exp_f32_e32 v65, v70
	v_exp_f32_e32 v73, v71
	v_add_f32_e32 v65, 1.0, v65
	v_rcp_f32_e32 v72, v65
	v_add_f32_e32 v65, 1.0, v73
	v_rcp_f32_e32 v73, v65
	s_nop 0
	v_pk_mul_f32 v[70:71], v[70:71], v[72:73]
	s_nop 0
	v_pk_mul_f32 v[68:69], v[68:69], v[70:71]
	s_nop 0
	v_cvt_pk_bf16_f32 v67, v68, v69
	v_pk_fma_f32 v[68:69], v[32:33], v[120:121], v[124:125]
	v_mov_b32_e32 v134, v249
	v_mov_b32_e32 v135, v250
	v_mov_b32_e32 v136, v66
	v_mov_b32_e32 v137, v67
	global_store_dwordx4 v[196:197], v[134:137], off
	v_pk_fma_f32 v[68:69], v[36:37], v[116:117], v[68:69]
	v_pk_fma_f32 v[32:33], v[32:33], v[116:117], v[44:45]
	v_pk_fma_f32 v[56:57], v[56:57], v[112:113], v[68:69]
	v_pk_fma_f32 v[32:33], v[36:37], v[112:113], v[32:33]
	v_exp_f32_e32 v65, v56
	v_exp_f32_e32 v68, v57
	v_add_f32_e32 v65, 1.0, v65
	v_rcp_f32_e32 v66, v65
	v_add_f32_e32 v65, 1.0, v68
	v_rcp_f32_e32 v67, v65
	v_pk_fma_f32 v[68:69], v[40:41], v[104:105], v[108:109]
	v_exp_f32_e32 v44, v32
	v_pk_fma_f32 v[68:69], v[48:49], v[100:101], v[68:69]
	v_pk_mul_f32 v[56:57], v[56:57], v[66:67]
	v_pk_fma_f32 v[60:61], v[60:61], v[96:97], v[68:69]
	v_pk_fma_f32 v[36:37], v[46:47], v[122:123], v[126:127]
	v_pk_mul_f32 v[56:57], v[60:61], v[56:57]
	v_pk_fma_f32 v[60:61], v[34:35], v[122:123], v[126:127]
	v_pk_fma_f32 v[34:35], v[34:35], v[118:119], v[36:37]
	v_pk_fma_f32 v[60:61], v[38:39], v[118:119], v[60:61]
	v_pk_fma_f32 v[34:35], v[38:39], v[114:115], v[34:35]
	v_pk_fma_f32 v[58:59], v[58:59], v[114:115], v[60:61]
	v_exp_f32_e32 v60, v58
	v_exp_f32_e32 v45, v33
	v_exp_f32_e32 v36, v34
	v_exp_f32_e32 v37, v35
	v_exp_f32_e32 v61, v59
	v_cvt_pk_bf16_f32 v56, v56, v57
	v_add_f32_e32 v57, 1.0, v60
	v_add_f32_e32 v44, 1.0, v44
	v_add_f32_e32 v45, 1.0, v45
	v_add_f32_e32 v36, 1.0, v36
	v_add_f32_e32 v37, 1.0, v37
	v_rcp_f32_e32 v60, v57
	v_add_f32_e32 v57, 1.0, v61
	v_rcp_f32_e32 v44, v44
	v_rcp_f32_e32 v45, v45
	v_rcp_f32_e32 v36, v36
	v_rcp_f32_e32 v37, v37
	v_rcp_f32_e32 v61, v57
	v_pk_fma_f32 v[46:47], v[54:55], v[106:107], v[110:111]
	v_pk_fma_f32 v[66:67], v[42:43], v[106:107], v[110:111]
	v_pk_fma_f32 v[40:41], v[40:41], v[100:101], v[52:53]
	v_pk_fma_f32 v[38:39], v[42:43], v[102:103], v[46:47]
	v_pk_fma_f32 v[66:67], v[50:51], v[102:103], v[66:67]
	v_pk_fma_f32 v[40:41], v[48:49], v[96:97], v[40:41]
	v_pk_mul_f32 v[32:33], v[32:33], v[44:45]
	v_pk_fma_f32 v[38:39], v[50:51], v[98:99], v[38:39]
	v_pk_mul_f32 v[34:35], v[34:35], v[36:37]
	v_pk_fma_f32 v[62:63], v[62:63], v[98:99], v[66:67]
	v_pk_mul_f32 v[58:59], v[58:59], v[60:61]
	v_pk_mul_f32 v[32:33], v[40:41], v[32:33]
	v_pk_mul_f32 v[34:35], v[38:39], v[34:35]
	v_pk_mul_f32 v[58:59], v[62:63], v[58:59]
	v_cvt_pk_bf16_f32 v32, v32, v33
	v_cvt_pk_bf16_f32 v33, v34, v35
	v_cvt_pk_bf16_f32 v57, v58, v59
	v_mov_b32_e32 v158, v251
	v_mov_b32_e32 v159, v253
	v_mov_b32_e32 v160, v32
	v_mov_b32_e32 v161, v33
	global_store_dwordx4 v[140:141], v[158:161], off
	v_mov_b32_e32 v65, 0
	v_mov_b32_e32 v66, 0
	v_mov_b32_e32 v67, 0
	v_mov_b32_e32 v40, 0
	v_mov_b32_e32 v41, 0
	v_mov_b32_e32 v42, 0
	v_mov_b32_e32 v43, 0
	v_mov_b32_e32 v32, 0
	v_mov_b32_e32 v33, 0
	v_mov_b32_e32 v34, 0
	v_mov_b32_e32 v35, 0
	v_mov_b32_e32 v36, 0
	v_mov_b32_e32 v37, 0
	v_mov_b32_e32 v38, 0
	v_mov_b32_e32 v39, 0
	v_mov_b32_e32 v162, v254
	v_mov_b32_e32 v163, v255
	v_mov_b32_e32 v164, v56
	v_mov_b32_e32 v165, v57
	global_store_dwordx4 v[152:153], v[162:165], off
	s_and_saveexec_b64 s[40:41], s[28:29]
	s_cbranch_execz .LBB0_754
	ds_read_b128 v[36:39], v237 offset:2064
	ds_read_b128 v[40:43], v237 offset:2576
	ds_read_b128 v[32:35], v237 offset:3088
	ds_read_b128 v[64:67], v237 offset:3600
	s_branch .LBB0_754

; #define LAS __attribute__((address_space(3)))
; __device__ __forceinline__ float sigmoidf_(float x) { return __builtin_amdgcn_rcpf(1.0f + __expf(-x)); }
;     __device__ __forceinline__ void operator()(AccRef acc, const Unit& u, int wr, int wc, int fr, int fq) const {
;     ...
;                 f32x4 h2v = (f32x4){0.f, 0.f, 0.f, 0.f}, h3v = h2v, h2g = h2v, h3g = h2v;
;                 const int pb = ai * 2 + wr - 1;
;                 if (pb >= 0 && fr == 0) { const LAS float* xp = xch + (pb * 2) * 256 + clb + 4 * n;
;                     h2v = *(const LAS f32x4*)(xp); h3v = *(const LAS f32x4*)(xp + 256); h2g = *(const LAS f32x4*)(xp + 128); h3g = *(const LAS f32x4*)(xp + 256 + 128); }
;                 float o[4][4];
; #pragma unroll
;                 for (int j = 0; j < 4; ++j) {
;                     const float v0 = acc[ai][0][0][n][j], v1 = acc[ai][0][1][n][j], v2 = acc[ai][0][2][n][j], v3 = acc[ai][0][3][n][j];
;                     const float g0 = acc[ai][1][0][n][j], g1 = acc[ai][1][1][n][j], g2 = acc[ai][1][2][n][j], g3 = acc[ai][1][3][n][j];
;                     const float pv3 = dpp_upd<0x111>(h3v[j], v3), pv2 = dpp_upd<0x111>(h2v[j], v2), pg3 = dpp_upd<0x111>(h3g[j], g3), pg2 = dpp_upd<0x111>(h2g[j], g2);
;                     const float hv0 = bvv[j] + w2v[j] * v0 + w1v[j] * pv3 + w0v[j] * pv2, hv1 = bvv[j] + w2v[j] * v1 + w1v[j] * v0 + w0v[j] * pv3;
;                     const float hv2 = bvv[j] + w2v[j] * v2 + w1v[j] * v1 + w0v[j] * v0, hv3 = bvv[j] + w2v[j] * v3 + w1v[j] * v2 + w0v[j] * v1;
;                     const float hg0 = bvg[j] + w2g[j] * g0 + w1g[j] * pg3 + w0g[j] * pg2, hg1 = bvg[j] + w2g[j] * g1 + w1g[j] * g0 + w0g[j] * pg3;
;                     const float hg2 = bvg[j] + w2g[j] * g2 + w1g[j] * g1 + w0g[j] * g0, hg3 = bvg[j] + w2g[j] * g3 + w1g[j] * g2 + w0g[j] * g1;
;                     o[0][j] = hg0 * sigmoidf_(hg0) * hv0; o[1][j] = hg1 * sigmoidf_(hg1) * hv1; o[2][j] = hg2 * sigmoidf_(hg2) * hv2; o[3][j] = hg3 * sigmoidf_(hg3) * hv3; }
; #pragma unroll
;                 for (int m = 0; m < 4; ++m) { u32x2 w; w.x = cvt_pk_bf16(o[m][0], o[m][1]); w.y = cvt_pk_bf16(o[m][2], o[m][3]);
;                     *(u32x2*)(Aout + (size_t)(row0 + ai * 128 + m) * FH + hc0 + 4 * n) = w; } } }
.LBB0_1355:
	s_or_b64 exec, exec, s[42:43]
	s_waitcnt lgkmcnt(0)
	v_mov_b32_dpp v64, v8 row_shr:1 row_mask:0xf bank_mask:0xf
	v_mov_b32_dpp v65, v9 row_shr:1 row_mask:0xf bank_mask:0xf
	v_pk_fma_f32 v[44:45], v[24:25], v[120:121], v[124:125]
	v_mov_b32_dpp v40, v0 row_shr:1 row_mask:0xf bank_mask:0xf
	v_mov_b32_dpp v41, v1 row_shr:1 row_mask:0xf bank_mask:0xf
	v_pk_fma_f32 v[44:45], v[116:117], v[64:65], v[44:45]
	v_mov_b32_dpp v32, v20 row_shr:1 row_mask:0xf bank_mask:0xf
	v_pk_fma_f32 v[40:41], v[112:113], v[40:41], v[44:45]
	v_mov_b32_dpp v33, v21 row_shr:1 row_mask:0xf bank_mask:0xf
	v_exp_f32_e32 v44, v40
	v_exp_f32_e32 v45, v41
	v_pk_fma_f32 v[46:47], v[28:29], v[104:105], v[108:109]
	v_mov_b32_dpp v36, v12 row_shr:1 row_mask:0xf bank_mask:0xf
	v_add_f32_e32 v44, 1.0, v44
	v_add_f32_e32 v45, 1.0, v45
	v_rcp_f32_e32 v44, v44
	v_rcp_f32_e32 v45, v45
	v_mov_b32_dpp v37, v13 row_shr:1 row_mask:0xf bank_mask:0xf
	v_pk_fma_f32 v[46:47], v[100:101], v[32:33], v[46:47]
	v_mov_b32_dpp v66, v10 row_shr:1 row_mask:0xf bank_mask:0xf
	v_pk_fma_f32 v[36:37], v[96:97], v[36:37], v[46:47]
	v_pk_mul_f32 v[40:41], v[40:41], v[44:45]
	v_mov_b32_dpp v67, v11 row_shr:1 row_mask:0xf bank_mask:0xf
	v_pk_mul_f32 v[36:37], v[36:37], v[40:41]
	v_pk_fma_f32 v[40:41], v[26:27], v[122:123], v[126:127]
	v_mov_b32_dpp v42, v2 row_shr:1 row_mask:0xf bank_mask:0xf
	v_mov_b32_dpp v43, v3 row_shr:1 row_mask:0xf bank_mask:0xf
	v_pk_fma_f32 v[40:41], v[118:119], v[66:67], v[40:41]
	v_cvt_pk_bf16_f32 v36, v36, v37
	v_pk_fma_f32 v[40:41], v[114:115], v[42:43], v[40:41]
	v_mov_b32_dpp v34, v22 row_shr:1 row_mask:0xf bank_mask:0xf
	v_exp_f32_e32 v42, v40
	v_exp_f32_e32 v43, v41
	v_mov_b32_dpp v35, v23 row_shr:1 row_mask:0xf bank_mask:0xf
	v_add_f32_e32 v37, 1.0, v42
	v_rcp_f32_e32 v42, v37
	v_add_f32_e32 v37, 1.0, v43
	v_rcp_f32_e32 v43, v37
	v_pk_fma_f32 v[44:45], v[30:31], v[106:107], v[110:111]
	v_mov_b32_dpp v38, v14 row_shr:1 row_mask:0xf bank_mask:0xf
	v_mov_b32_dpp v39, v15 row_shr:1 row_mask:0xf bank_mask:0xf
	v_pk_fma_f32 v[44:45], v[102:103], v[34:35], v[44:45]
	v_pk_mul_f32 v[40:41], v[40:41], v[42:43]
	v_pk_fma_f32 v[38:39], v[98:99], v[38:39], v[44:45]
	v_pk_fma_f32 v[8:9], v[8:9], v[120:121], v[124:125]
	v_pk_mul_f32 v[38:39], v[38:39], v[40:41]
	v_pk_fma_f32 v[20:21], v[20:21], v[104:105], v[108:109]
	v_cvt_pk_bf16_f32 v37, v38, v39
	v_pk_fma_f32 v[38:39], v[4:5], v[120:121], v[124:125]
	v_mov_b32_e32 v146, v36
	v_mov_b32_e32 v147, v37
	global_store_dwordx4 v[132:133], v[144:147], off
	v_pk_fma_f32 v[38:39], v[24:25], v[116:117], v[38:39]
	s_and_b64 vcc, exec, s[14:15]
	v_pk_fma_f32 v[38:39], v[112:113], v[64:65], v[38:39]
	s_mov_b32 s43, s34
	v_exp_f32_e32 v40, v38
	v_exp_f32_e32 v41, v39
	s_mov_b32 s42, s36
	s_mov_b64 s[46:47], s[40:41]
	v_add_f32_e32 v36, 1.0, v40
	v_add_f32_e32 v37, 1.0, v41
	v_rcp_f32_e32 v36, v36
	v_rcp_f32_e32 v37, v37
	v_pk_fma_f32 v[40:41], v[16:17], v[104:105], v[108:109]
	s_mov_b64 s[44:45], s[38:39]
	v_pk_fma_f32 v[40:41], v[28:29], v[100:101], v[40:41]
	v_pk_mul_f32 v[36:37], v[38:39], v[36:37]
	v_pk_fma_f32 v[32:33], v[96:97], v[32:33], v[40:41]
	v_pk_fma_f32 v[40:41], v[18:19], v[106:107], v[110:111]
	v_pk_mul_f32 v[32:33], v[32:33], v[36:37]
	v_pk_fma_f32 v[36:37], v[6:7], v[122:123], v[126:127]
	v_cvt_pk_bf16_f32 v32, v32, v33
	v_pk_fma_f32 v[36:37], v[26:27], v[118:119], v[36:37]
	v_pk_fma_f32 v[40:41], v[30:31], v[102:103], v[40:41]
	v_pk_fma_f32 v[36:37], v[114:115], v[66:67], v[36:37]
	v_pk_fma_f32 v[34:35], v[98:99], v[34:35], v[40:41]
	v_exp_f32_e32 v38, v36
	v_exp_f32_e32 v39, v37
	v_add_f32_e32 v33, 1.0, v38
	v_rcp_f32_e32 v38, v33
	v_add_f32_e32 v33, 1.0, v39
	v_rcp_f32_e32 v39, v33
	s_nop 0
	v_pk_mul_f32 v[36:37], v[36:37], v[38:39]
	s_nop 0
	v_pk_mul_f32 v[34:35], v[34:35], v[36:37]
	s_nop 0
	v_cvt_pk_bf16_f32 v33, v34, v35
	v_pk_fma_f32 v[34:35], v[0:1], v[120:121], v[124:125]
	v_mov_b32_e32 v156, v32
	v_mov_b32_e32 v157, v33
	global_store_dwordx4 v[128:129], v[154:157], off
	v_pk_fma_f32 v[34:35], v[4:5], v[116:117], v[34:35]
	v_pk_fma_f32 v[0:1], v[0:1], v[116:117], v[8:9]
	v_pk_fma_f32 v[24:25], v[24:25], v[112:113], v[34:35]
	v_pk_fma_f32 v[0:1], v[4:5], v[112:113], v[0:1]
	v_exp_f32_e32 v34, v24
	v_exp_f32_e32 v35, v25
	v_exp_f32_e32 v8, v0
	v_add_f32_e32 v32, 1.0, v34
	v_add_f32_e32 v33, 1.0, v35
	v_rcp_f32_e32 v32, v32
	v_rcp_f32_e32 v33, v33
	v_pk_fma_f32 v[34:35], v[12:13], v[104:105], v[108:109]
	v_pk_fma_f32 v[4:5], v[10:11], v[122:123], v[126:127]
	v_pk_fma_f32 v[34:35], v[16:17], v[100:101], v[34:35]
	v_pk_mul_f32 v[24:25], v[24:25], v[32:33]
	v_pk_fma_f32 v[28:29], v[28:29], v[96:97], v[34:35]
	v_pk_mul_f32 v[24:25], v[28:29], v[24:25]
	v_pk_fma_f32 v[28:29], v[2:3], v[122:123], v[126:127]
	v_pk_fma_f32 v[2:3], v[2:3], v[118:119], v[4:5]
	v_pk_fma_f32 v[28:29], v[6:7], v[118:119], v[28:29]
	v_pk_fma_f32 v[2:3], v[6:7], v[114:115], v[2:3]
	v_pk_fma_f32 v[26:27], v[26:27], v[114:115], v[28:29]
	v_exp_f32_e32 v28, v26
	v_exp_f32_e32 v29, v27
	v_exp_f32_e32 v9, v1
	v_exp_f32_e32 v4, v2
	v_exp_f32_e32 v5, v3
	v_cvt_pk_bf16_f32 v24, v24, v25
	v_add_f32_e32 v25, 1.0, v28
	v_rcp_f32_e32 v28, v25
	v_add_f32_e32 v25, 1.0, v29
	v_add_f32_e32 v8, 1.0, v8
	v_add_f32_e32 v9, 1.0, v9
	v_add_f32_e32 v4, 1.0, v4
	v_add_f32_e32 v5, 1.0, v5
	v_rcp_f32_e32 v29, v25
	v_rcp_f32_e32 v8, v8
	v_rcp_f32_e32 v9, v9
	v_rcp_f32_e32 v4, v4
	v_rcp_f32_e32 v5, v5
	v_pk_fma_f32 v[32:33], v[14:15], v[106:107], v[110:111]
	v_pk_fma_f32 v[10:11], v[22:23], v[106:107], v[110:111]
	v_pk_fma_f32 v[32:33], v[18:19], v[102:103], v[32:33]
	v_pk_fma_f32 v[12:13], v[12:13], v[100:101], v[20:21]
	v_pk_fma_f32 v[6:7], v[14:15], v[102:103], v[10:11]
	v_pk_fma_f32 v[30:31], v[30:31], v[98:99], v[32:33]
	v_pk_mul_f32 v[26:27], v[26:27], v[28:29]
	v_pk_fma_f32 v[12:13], v[16:17], v[96:97], v[12:13]
	v_pk_mul_f32 v[0:1], v[0:1], v[8:9]
	v_pk_fma_f32 v[6:7], v[18:19], v[98:99], v[6:7]
	v_pk_mul_f32 v[2:3], v[2:3], v[4:5]
	v_pk_mul_f32 v[26:27], v[30:31], v[26:27]
	v_pk_mul_f32 v[0:1], v[12:13], v[0:1]
	v_pk_mul_f32 v[2:3], v[6:7], v[2:3]
	v_cvt_pk_bf16_f32 v25, v26, v27
	v_cvt_pk_bf16_f32 v0, v0, v1
	v_cvt_pk_bf16_f32 v1, v2, v3
	v_mov_b32_e32 v200, v24
	v_mov_b32_e32 v201, v25
	global_store_dwordx4 v[88:89], v[198:201], off
	v_mov_b32_e32 v150, v0
	v_mov_b32_e32 v151, v1
	global_store_dwordx4 v[82:83], v[148:151], off
	s_cbranch_vccnz .LBB0_1374

;     __device__ __forceinline__ void operator()(AccRef acc, const Unit& u, int wr, int wc, int fr, int fq) const {
;     ...
;         { const float* cv = cw + 128 * u.pn + clb; const float* cg = cv + FH; const float* bp = cb + 128 * u.pn + clb;
;           cwv[0][0] = *(const f32x4*)(cv); cwv[0][1] = *(const f32x4*)(cv + F2); cwv[0][2] = *(const f32x4*)(cv + 2 * F2); cwv[0][3] = *(const f32x4*)(bp);
;           cwv[0][4] = *(const f32x4*)(cg); cwv[0][5] = *(const f32x4*)(cg + F2); cwv[0][6] = *(const f32x4*)(cg + 2 * F2); cwv[0][7] = *(const f32x4*)(bp + FH); }
;     ...
;                     const float* cv = cw + hc0 + 4; const float* cg = cv + FH; const float* bp = cb + hc0 + 4;
;                     cwv[1][0] = *(const f32x4*)(cv); cwv[1][1] = *(const f32x4*)(cv + F2); cwv[1][2] = *(const f32x4*)(cv + 2 * F2); cwv[1][3] = *(const f32x4*)(bp);
;                     cwv[1][4] = *(const f32x4*)(cg); cwv[1][5] = *(const f32x4*)(cg + F2); cwv[1][6] = *(const f32x4*)(cg + 2 * F2); cwv[1][7] = *(const f32x4*)(bp + FH);
.LBB0_1368:
	s_or_b64 exec, exec, s[44:45]
	s_waitcnt lgkmcnt(0)
	v_mov_b32_dpp v198, v140 row_shr:1 row_mask:0xf bank_mask:0xf
	v_mov_b32_dpp v199, v141 row_shr:1 row_mask:0xf bank_mask:0xf
	s_waitcnt vmcnt(0)
	s_bitcmp1_b32 s99, 8
	s_cbranch_scc1 .Lcw1359_nostage
	v_and_b32_e32 v107, 0xff, v219
	v_lshlrev_b32_e32 v107, 4, v107
	v_add_u32_e32 v107, 0x22000, v107
	v_and_b32_e32 v104, 4, v219
	v_cmp_ne_u32_e64 s[100:101], 0, v104
	v_mov_b32_e32 v104, 0xbf317218
	v_mov_b32_e32 v105, 0xbfb8aa3b
	s_nop 0
	v_cndmask_b32_e64 v104, v104, v105, s[100:101]
	v_mov_b32_e32 v105, v104
	v_pk_mul_f32 v[108:109], v[108:109], v[104:105]
	v_pk_mul_f32 v[110:111], v[110:111], v[104:105]
	ds_write_b128 v107, v[108:111]

; #define LAS __attribute__((address_space(3)))
; __device__ __forceinline__ float sigmoidf_(float x) { return __builtin_amdgcn_rcpf(1.0f + __expf(-x)); }
;     __device__ __forceinline__ void operator()(AccRef acc, const Unit& u, int wr, int wc, int fr, int fq) const {
;     ...
;                 f32x4 h2v = (f32x4){0.f, 0.f, 0.f, 0.f}, h3v = h2v, h2g = h2v, h3g = h2v;
;                 const int pb = ai * 2 + wr - 1;
;                 if (pb >= 0 && fr == 0) { const LAS float* xp = xch + (pb * 2) * 256 + clb + 4 * n;
;                     h2v = *(const LAS f32x4*)(xp); h3v = *(const LAS f32x4*)(xp + 256); h2g = *(const LAS f32x4*)(xp + 128); h3g = *(const LAS f32x4*)(xp + 256 + 128); }
;                 float o[4][4];
; #pragma unroll
;                 for (int j = 0; j < 4; ++j) {
;                     const float v0 = acc[ai][0][0][n][j], v1 = acc[ai][0][1][n][j], v2 = acc[ai][0][2][n][j], v3 = acc[ai][0][3][n][j];
;                     const float g0 = acc[ai][1][0][n][j], g1 = acc[ai][1][1][n][j], g2 = acc[ai][1][2][n][j], g3 = acc[ai][1][3][n][j];
;                     const float pv3 = dpp_upd<0x111>(h3v[j], v3), pv2 = dpp_upd<0x111>(h2v[j], v2), pg3 = dpp_upd<0x111>(h3g[j], g3), pg2 = dpp_upd<0x111>(h2g[j], g2);
;                     const float hv0 = bvv[j] + w2v[j] * v0 + w1v[j] * pv3 + w0v[j] * pv2, hv1 = bvv[j] + w2v[j] * v1 + w1v[j] * v0 + w0v[j] * pv3;
;                     const float hv2 = bvv[j] + w2v[j] * v2 + w1v[j] * v1 + w0v[j] * v0, hv3 = bvv[j] + w2v[j] * v3 + w1v[j] * v2 + w0v[j] * v1;
;                     const float hg0 = bvg[j] + w2g[j] * g0 + w1g[j] * pg3 + w0g[j] * pg2, hg1 = bvg[j] + w2g[j] * g1 + w1g[j] * g0 + w0g[j] * pg3;
;                     const float hg2 = bvg[j] + w2g[j] * g2 + w1g[j] * g1 + w0g[j] * g0, hg3 = bvg[j] + w2g[j] * g3 + w1g[j] * g2 + w0g[j] * g1;
;                     o[0][j] = hg0 * sigmoidf_(hg0) * hv0; o[1][j] = hg1 * sigmoidf_(hg1) * hv1; o[2][j] = hg2 * sigmoidf_(hg2) * hv2; o[3][j] = hg3 * sigmoidf_(hg3) * hv3; }
; #pragma unroll
;                 for (int m = 0; m < 4; ++m) { u32x2 w; w.x = cvt_pk_bf16(o[m][0], o[m][1]); w.y = cvt_pk_bf16(o[m][2], o[m][3]);
;                     *(u32x2*)(Aout + (size_t)(row0 + ai * 128 + m) * FH + hc0 + 4 * n) = w; } } }
.LBB0_1366:
	s_or_b64 exec, exec, s[48:49]
	v_pk_fma_f32 v[248:249], v[152:153], v[184:185], v[188:189]
	v_mov_b32_dpp v206, v128 row_shr:1 row_mask:0xf bank_mask:0xf
	v_mov_b32_dpp v207, v129 row_shr:1 row_mask:0xf bank_mask:0xf
	v_pk_fma_f32 v[248:249], v[180:181], v[198:199], v[248:249]
	v_mov_b32_dpp v194, v148 row_shr:1 row_mask:0xf bank_mask:0xf
	v_pk_fma_f32 v[206:207], v[176:177], v[206:207], v[248:249]
	v_mov_b32_dpp v195, v149 row_shr:1 row_mask:0xf bank_mask:0xf
	v_exp_f32_e32 v193, v206
	v_exp_f32_e32 v247, v207
	v_pk_fma_f32 v[250:251], v[156:157], v[168:169], v[172:173]
	v_add_f32_e32 v193, 1.0, v193
	v_rcp_f32_e32 v248, v193
	v_add_f32_e32 v193, 1.0, v247
	v_rcp_f32_e32 v249, v193
	v_mov_b32_dpp v202, v136 row_shr:1 row_mask:0xf bank_mask:0xf
	v_mov_b32_dpp v203, v137 row_shr:1 row_mask:0xf bank_mask:0xf
	v_pk_fma_f32 v[250:251], v[164:165], v[194:195], v[250:251]
	v_pk_mul_f32 v[206:207], v[206:207], v[248:249]
	v_pk_fma_f32 v[202:203], v[160:161], v[202:203], v[250:251]
	v_mov_b32_dpp v200, v142 row_shr:1 row_mask:0xf bank_mask:0xf
	v_mov_b32_dpp v201, v143 row_shr:1 row_mask:0xf bank_mask:0xf
	v_pk_mul_f32 v[202:203], v[202:203], v[206:207]
	v_pk_fma_f32 v[206:207], v[154:155], v[186:187], v[190:191]
	v_mov_b32_dpp v208, v130 row_shr:1 row_mask:0xf bank_mask:0xf
	v_mov_b32_dpp v209, v131 row_shr:1 row_mask:0xf bank_mask:0xf
	v_pk_fma_f32 v[206:207], v[182:183], v[200:201], v[206:207]
	v_mov_b32_dpp v196, v150 row_shr:1 row_mask:0xf bank_mask:0xf
	v_pk_fma_f32 v[206:207], v[178:179], v[208:209], v[206:207]
	v_mov_b32_dpp v197, v151 row_shr:1 row_mask:0xf bank_mask:0xf
	v_exp_f32_e32 v193, v206
	v_exp_f32_e32 v209, v207
	v_cvt_pk_bf16_f32 v208, v202, v203
	v_add_f32_e32 v193, 1.0, v193
	v_rcp_f32_e32 v202, v193
	v_add_f32_e32 v193, 1.0, v209
	v_rcp_f32_e32 v203, v193
	v_pk_fma_f32 v[248:249], v[158:159], v[170:171], v[174:175]
	v_mov_b32_dpp v204, v138 row_shr:1 row_mask:0xf bank_mask:0xf
	v_mov_b32_dpp v205, v139 row_shr:1 row_mask:0xf bank_mask:0xf
	v_pk_fma_f32 v[248:249], v[166:167], v[196:197], v[248:249]
	v_pk_mul_f32 v[202:203], v[206:207], v[202:203]
	v_pk_fma_f32 v[204:205], v[162:163], v[204:205], v[248:249]
	v_lshl_add_u32 v246, s42, 8, v236
	v_pk_mul_f32 v[202:203], v[204:205], v[202:203]
	v_lshlrev_b64 v[204:205], 1, v[232:233]
	v_pk_fma_f32 v[232:233], v[132:133], v[184:185], v[188:189]
	v_mov_b64_e32 v[206:207], s[60:61]
	v_pk_fma_f32 v[232:233], v[152:153], v[180:181], v[232:233]
	v_cvt_pk_bf16_f32 v209, v202, v203
	v_pk_fma_f32 v[198:199], v[176:177], v[198:199], v[232:233]
	v_mad_i64_i32 v[202:203], s[42:43], v246, s82, v[206:207]
	v_exp_f32_e32 v193, v198
	v_exp_f32_e32 v232, v199
	v_lshl_add_u64 v[202:203], v[202:203], 0, v[204:205]
	v_add_f32_e32 v193, 1.0, v193
	v_mov_b32_e32 v247, v208
	v_mov_b32_e32 v248, v209
	v_rcp_f32_e32 v208, v193
	v_add_f32_e32 v193, 1.0, v232
	v_rcp_f32_e32 v209, v193
	v_pk_fma_f32 v[232:233], v[144:145], v[168:169], v[172:173]
	v_pk_fma_f32 v[140:141], v[140:141], v[184:185], v[188:189]
	v_pk_fma_f32 v[232:233], v[156:157], v[164:165], v[232:233]
	v_pk_mul_f32 v[198:199], v[198:199], v[208:209]
	v_pk_fma_f32 v[194:195], v[160:161], v[194:195], v[232:233]
	v_pk_fma_f32 v[208:209], v[146:147], v[170:171], v[174:175]
	v_pk_mul_f32 v[194:195], v[194:195], v[198:199]
	v_pk_fma_f32 v[198:199], v[134:135], v[186:187], v[190:191]
	v_pk_fma_f32 v[208:209], v[158:159], v[166:167], v[208:209]
	v_pk_fma_f32 v[198:199], v[154:155], v[182:183], v[198:199]
	v_pk_fma_f32 v[196:197], v[162:163], v[196:197], v[208:209]
	v_pk_fma_f32 v[198:199], v[178:179], v[200:201], v[198:199]
	v_cvt_pk_bf16_f32 v194, v194, v195
	v_exp_f32_e32 v193, v198
	v_exp_f32_e32 v201, v199
	v_pk_fma_f32 v[148:149], v[148:149], v[168:169], v[172:173]
	v_add_f32_e32 v193, 1.0, v193
	v_rcp_f32_e32 v200, v193
	v_add_f32_e32 v193, 1.0, v201
	v_rcp_f32_e32 v201, v193
	v_or_b32_e32 v193, 1, v246
	v_pk_mul_f32 v[198:199], v[198:199], v[200:201]
	s_nop 0
	v_pk_mul_f32 v[196:197], v[196:197], v[198:199]
	v_pk_fma_f32 v[198:199], v[128:129], v[184:185], v[188:189]
	v_cvt_pk_bf16_f32 v195, v196, v197
	v_pk_fma_f32 v[198:199], v[132:133], v[180:181], v[198:199]
	v_mad_i64_i32 v[196:197], s[42:43], v193, s82, v[206:207]
	v_pk_fma_f32 v[152:153], v[152:153], v[176:177], v[198:199]
	v_lshl_add_u64 v[196:197], v[196:197], 0, v[204:205]
	v_exp_f32_e32 v193, v152
	v_exp_f32_e32 v198, v153
	v_mov_b32_e32 v249, v194
	v_mov_b32_e32 v250, v195
	v_add_f32_e32 v193, 1.0, v193
	v_rcp_f32_e32 v194, v193
	v_add_f32_e32 v193, 1.0, v198
	v_rcp_f32_e32 v195, v193
	v_pk_fma_f32 v[198:199], v[136:137], v[168:169], v[172:173]
	v_pk_fma_f32 v[128:129], v[128:129], v[180:181], v[140:141]
	v_pk_fma_f32 v[198:199], v[144:145], v[164:165], v[198:199]
	v_pk_fma_f32 v[128:129], v[132:133], v[176:177], v[128:129]
	v_pk_fma_f32 v[156:157], v[156:157], v[160:161], v[198:199]
	v_pk_mul_f32 v[152:153], v[152:153], v[194:195]
	v_pk_mul_f32 v[152:153], v[156:157], v[152:153]
	v_pk_fma_f32 v[156:157], v[130:131], v[186:187], v[190:191]
	v_exp_f32_e32 v140, v128
	v_pk_fma_f32 v[132:133], v[142:143], v[186:187], v[190:191]
	v_pk_fma_f32 v[156:157], v[134:135], v[182:183], v[156:157]
	v_pk_fma_f32 v[130:131], v[130:131], v[182:183], v[132:133]
	v_pk_fma_f32 v[154:155], v[154:155], v[178:179], v[156:157]
	v_pk_fma_f32 v[130:131], v[134:135], v[178:179], v[130:131]
	v_exp_f32_e32 v157, v154
	v_exp_f32_e32 v141, v129
	v_exp_f32_e32 v132, v130
	v_exp_f32_e32 v133, v131
	v_exp_f32_e32 v193, v155
	v_add_f32_e32 v140, 1.0, v140
	v_add_f32_e32 v141, 1.0, v141
	v_add_f32_e32 v132, 1.0, v132
	v_add_f32_e32 v133, 1.0, v133
	v_cvt_pk_bf16_f32 v156, v152, v153
	v_add_f32_e32 v152, 1.0, v157
; #define LAS __attribute__((address_space(3)))
; __device__ __forceinline__ float sigmoidf_(float x) { return __builtin_amdgcn_rcpf(1.0f + __expf(-x)); }
;     __device__ __forceinline__ void operator()(AccRef acc, const Unit& u, int wr, int wc, int fr, int fq) const {
;     ...
;                 f32x4 h2v = (f32x4){0.f, 0.f, 0.f, 0.f}, h3v = h2v, h2g = h2v, h3g = h2v;
;                 const int pb = ai * 2 + wr - 1;
;                 if (pb >= 0 && fr == 0) { const LAS float* xp = xch + (pb * 2) * 256 + clb + 4 * n;
;                     h2v = *(const LAS f32x4*)(xp); h3v = *(const LAS f32x4*)(xp + 256); h2g = *(const LAS f32x4*)(xp + 128); h3g = *(const LAS f32x4*)(xp + 256 + 128); }
;                 float o[4][4];
; #pragma unroll
;                 for (int j = 0; j < 4; ++j) {
;                     const float v0 = acc[ai][0][0][n][j], v1 = acc[ai][0][1][n][j], v2 = acc[ai][0][2][n][j], v3 = acc[ai][0][3][n][j];
;                     const float g0 = acc[ai][1][0][n][j], g1 = acc[ai][1][1][n][j], g2 = acc[ai][1][2][n][j], g3 = acc[ai][1][3][n][j];
;                     const float pv3 = dpp_upd<0x111>(h3v[j], v3), pv2 = dpp_upd<0x111>(h2v[j], v2), pg3 = dpp_upd<0x111>(h3g[j], g3), pg2 = dpp_upd<0x111>(h2g[j], g2);
;                     const float hv0 = bvv[j] + w2v[j] * v0 + w1v[j] * pv3 + w0v[j] * pv2, hv1 = bvv[j] + w2v[j] * v1 + w1v[j] * v0 + w0v[j] * pv3;
;                     const float hv2 = bvv[j] + w2v[j] * v2 + w1v[j] * v1 + w0v[j] * v0, hv3 = bvv[j] + w2v[j] * v3 + w1v[j] * v2 + w0v[j] * v1;
;                     const float hg0 = bvg[j] + w2g[j] * g0 + w1g[j] * pg3 + w0g[j] * pg2, hg1 = bvg[j] + w2g[j] * g1 + w1g[j] * g0 + w0g[j] * pg3;
;                     const float hg2 = bvg[j] + w2g[j] * g2 + w1g[j] * g1 + w0g[j] * g0, hg3 = bvg[j] + w2g[j] * g3 + w1g[j] * g2 + w0g[j] * g1;
;                     o[0][j] = hg0 * sigmoidf_(hg0) * hv0; o[1][j] = hg1 * sigmoidf_(hg1) * hv1; o[2][j] = hg2 * sigmoidf_(hg2) * hv2; o[3][j] = hg3 * sigmoidf_(hg3) * hv3; }
; #pragma unroll
;                 for (int m = 0; m < 4; ++m) { u32x2 w; w.x = cvt_pk_bf16(o[m][0], o[m][1]); w.y = cvt_pk_bf16(o[m][2], o[m][3]);
;                     *(u32x2*)(Aout + (size_t)(row0 + ai * 128 + m) * FH + hc0 + 4 * n) = w; } } }
	v_add_f32_e32 v153, 1.0, v193
	v_rcp_f32_e32 v140, v140
	v_rcp_f32_e32 v141, v141
	v_rcp_f32_e32 v132, v132
	v_rcp_f32_e32 v133, v133
	v_rcp_f32_e32 v152, v152
	v_rcp_f32_e32 v153, v153
	v_pk_fma_f32 v[142:143], v[150:151], v[170:171], v[174:175]
	v_pk_fma_f32 v[194:195], v[138:139], v[170:171], v[174:175]
	v_pk_fma_f32 v[136:137], v[136:137], v[164:165], v[148:149]
	v_pk_fma_f32 v[134:135], v[138:139], v[166:167], v[142:143]
	v_pk_fma_f32 v[194:195], v[146:147], v[166:167], v[194:195]
	v_pk_fma_f32 v[136:137], v[144:145], v[160:161], v[136:137]
	v_pk_mul_f32 v[128:129], v[128:129], v[140:141]
	v_pk_fma_f32 v[134:135], v[146:147], v[162:163], v[134:135]
	v_pk_mul_f32 v[130:131], v[130:131], v[132:133]
	v_pk_fma_f32 v[158:159], v[158:159], v[162:163], v[194:195]
	v_pk_mul_f32 v[152:153], v[154:155], v[152:153]
	v_pk_mul_f32 v[128:129], v[136:137], v[128:129]
	v_pk_mul_f32 v[130:131], v[134:135], v[130:131]
	v_pk_mul_f32 v[152:153], v[158:159], v[152:153]
	v_cvt_pk_bf16_f32 v128, v128, v129
	v_cvt_pk_bf16_f32 v129, v130, v131
	v_or_b32_e32 v130, 3, v246
	v_cvt_pk_bf16_f32 v157, v152, v153
	v_or_b32_e32 v152, 2, v246
	v_mad_i64_i32 v[130:131], s[42:43], v130, s82, v[206:207]
	v_mad_i64_i32 v[152:153], s[42:43], v152, s82, v[206:207]
	v_lshl_add_u64 v[140:141], v[130:131], 0, v[204:205]
	v_lshl_add_u64 v[152:153], v[152:153], 0, v[204:205]
	v_mov_b32_e32 v251, v128
	v_mov_b32_e32 v253, v129
	v_mov_b32_e32 v193, 0
	v_mov_b32_e32 v194, 0
	v_mov_b32_e32 v195, 0
	v_mov_b32_e32 v136, 0
	v_mov_b32_e32 v137, 0
	v_mov_b32_e32 v138, 0
	v_mov_b32_e32 v139, 0
	v_mov_b32_e32 v128, 0
	v_mov_b32_e32 v129, 0
	v_mov_b32_e32 v130, 0
	v_mov_b32_e32 v131, 0
	v_mov_b32_e32 v132, 0
	v_mov_b32_e32 v133, 0
	v_mov_b32_e32 v134, 0
	v_mov_b32_e32 v135, 0
	v_mov_b32_e32 v254, v156
	v_mov_b32_e32 v255, v157
	s_and_saveexec_b64 s[42:43], s[30:31]
	s_cbranch_execz .LBB0_1370
	ds_read_b128 v[132:135], v237 offset:2048
	ds_read_b128 v[136:139], v237 offset:2560
	ds_read_b128 v[128:131], v237 offset:3072
	ds_read_b128 v[192:195], v237 offset:3584
.LBB0_1370:
	s_or_b64 exec, exec, s[42:43]
	s_waitcnt lgkmcnt(0)
	v_mov_b32_dpp v192, v72 row_shr:1 row_mask:0xf bank_mask:0xf
	v_mov_b32_dpp v193, v73 row_shr:1 row_mask:0xf bank_mask:0xf
	v_pk_fma_f32 v[142:143], v[88:89], v[184:185], v[188:189]
	v_mov_b32_dpp v136, v64 row_shr:1 row_mask:0xf bank_mask:0xf
	v_mov_b32_dpp v137, v65 row_shr:1 row_mask:0xf bank_mask:0xf
	v_pk_fma_f32 v[142:143], v[180:181], v[192:193], v[142:143]
	v_mov_b32_dpp v128, v84 row_shr:1 row_mask:0xf bank_mask:0xf
	v_pk_fma_f32 v[136:137], v[176:177], v[136:137], v[142:143]
	v_mov_b32_dpp v129, v85 row_shr:1 row_mask:0xf bank_mask:0xf
	v_exp_f32_e32 v142, v136
	v_exp_f32_e32 v143, v137
	v_pk_fma_f32 v[144:145], v[92:93], v[168:169], v[172:173]
	v_mov_b32_dpp v132, v76 row_shr:1 row_mask:0xf bank_mask:0xf
	v_add_f32_e32 v142, 1.0, v142
	v_add_f32_e32 v143, 1.0, v143
	v_rcp_f32_e32 v142, v142
	v_rcp_f32_e32 v143, v143
	v_mov_b32_dpp v133, v77 row_shr:1 row_mask:0xf bank_mask:0xf
	v_pk_fma_f32 v[144:145], v[164:165], v[128:129], v[144:145]
	v_mov_b32_dpp v194, v74 row_shr:1 row_mask:0xf bank_mask:0xf
	v_pk_fma_f32 v[132:133], v[160:161], v[132:133], v[144:145]
	v_pk_mul_f32 v[136:137], v[136:137], v[142:143]
	v_mov_b32_dpp v195, v75 row_shr:1 row_mask:0xf bank_mask:0xf
	v_pk_mul_f32 v[132:133], v[132:133], v[136:137]
	v_pk_fma_f32 v[136:137], v[90:91], v[186:187], v[190:191]
	v_mov_b32_dpp v138, v66 row_shr:1 row_mask:0xf bank_mask:0xf
	v_mov_b32_dpp v139, v67 row_shr:1 row_mask:0xf bank_mask:0xf
	v_pk_fma_f32 v[136:137], v[182:183], v[194:195], v[136:137]
	v_mov_b32_dpp v130, v86 row_shr:1 row_mask:0xf bank_mask:0xf
	v_pk_fma_f32 v[136:137], v[178:179], v[138:139], v[136:137]
	v_mov_b32_dpp v131, v87 row_shr:1 row_mask:0xf bank_mask:0xf
	v_exp_f32_e32 v139, v136
	v_exp_f32_e32 v142, v137
	v_cvt_pk_bf16_f32 v138, v132, v133
	v_add_f32_e32 v132, 1.0, v139
	v_rcp_f32_e32 v132, v132
	v_add_f32_e32 v133, 1.0, v142
	v_rcp_f32_e32 v133, v133
	v_pk_fma_f32 v[142:143], v[94:95], v[170:171], v[174:175]
	v_mov_b32_dpp v134, v78 row_shr:1 row_mask:0xf bank_mask:0xf
	v_mov_b32_dpp v135, v79 row_shr:1 row_mask:0xf bank_mask:0xf
	v_pk_mul_f32 v[132:133], v[136:137], v[132:133]
	v_pk_fma_f32 v[136:137], v[68:69], v[184:185], v[188:189]
	v_pk_fma_f32 v[142:143], v[166:167], v[130:131], v[142:143]
	v_pk_fma_f32 v[136:137], v[88:89], v[180:181], v[136:137]
	v_pk_fma_f32 v[134:135], v[162:163], v[134:135], v[142:143]
	v_pk_fma_f32 v[136:137], v[176:177], v[192:193], v[136:137]
	v_add_u32_e32 v146, 0x80, v246
	v_exp_f32_e32 v142, v136
	v_exp_f32_e32 v143, v137
	v_pk_mul_f32 v[132:133], v[134:135], v[132:133]
	v_mov_b64_e32 v[134:135], s[60:61]
	v_cvt_pk_bf16_f32 v139, v132, v133
	v_mad_i64_i32 v[132:133], s[42:43], v146, s82, v[134:135]
	v_lshl_add_u64 v[132:133], v[132:133], 0, v[204:205]
	v_mov_b32_e32 v144, v138
	v_mov_b32_e32 v145, v139
	v_add_f32_e32 v138, 1.0, v142
	v_add_f32_e32 v139, 1.0, v143
	v_rcp_f32_e32 v138, v138
	v_rcp_f32_e32 v139, v139
	v_pk_fma_f32 v[142:143], v[80:81], v[168:169], v[172:173]
	v_pk_fma_f32 v[72:73], v[72:73], v[184:185], v[188:189]
	v_pk_fma_f32 v[142:143], v[92:93], v[164:165], v[142:143]
	v_pk_mul_f32 v[136:137], v[136:137], v[138:139]
	v_pk_fma_f32 v[128:129], v[160:161], v[128:129], v[142:143]
	v_pk_fma_f32 v[84:85], v[84:85], v[168:169], v[172:173]
	v_pk_mul_f32 v[128:129], v[128:129], v[136:137]
	v_pk_fma_f32 v[136:137], v[70:71], v[186:187], v[190:191]
	s_nop 0
	v_pk_fma_f32 v[136:137], v[90:91], v[182:183], v[136:137]
	s_nop 0
	v_pk_fma_f32 v[136:137], v[178:179], v[194:195], v[136:137]
	s_nop 0
	v_exp_f32_e32 v139, v136
; #define LAS __attribute__((address_space(3)))
; __device__ __forceinline__ float sigmoidf_(float x) { return __builtin_amdgcn_rcpf(1.0f + __expf(-x)); }
;     __device__ __forceinline__ void operator()(AccRef acc, const Unit& u, int wr, int wc, int fr, int fq) const {
;     ...
;                 f32x4 h2v = (f32x4){0.f, 0.f, 0.f, 0.f}, h3v = h2v, h2g = h2v, h3g = h2v;
;                 const int pb = ai * 2 + wr - 1;
;                 if (pb >= 0 && fr == 0) { const LAS float* xp = xch + (pb * 2) * 256 + clb + 4 * n;
;                     h2v = *(const LAS f32x4*)(xp); h3v = *(const LAS f32x4*)(xp + 256); h2g = *(const LAS f32x4*)(xp + 128); h3g = *(const LAS f32x4*)(xp + 256 + 128); }
;                 float o[4][4];
; #pragma unroll
;                 for (int j = 0; j < 4; ++j) {
;                     const float v0 = acc[ai][0][0][n][j], v1 = acc[ai][0][1][n][j], v2 = acc[ai][0][2][n][j], v3 = acc[ai][0][3][n][j];
;                     const float g0 = acc[ai][1][0][n][j], g1 = acc[ai][1][1][n][j], g2 = acc[ai][1][2][n][j], g3 = acc[ai][1][3][n][j];
;                     const float pv3 = dpp_upd<0x111>(h3v[j], v3), pv2 = dpp_upd<0x111>(h2v[j], v2), pg3 = dpp_upd<0x111>(h3g[j], g3), pg2 = dpp_upd<0x111>(h2g[j], g2);
;                     const float hv0 = bvv[j] + w2v[j] * v0 + w1v[j] * pv3 + w0v[j] * pv2, hv1 = bvv[j] + w2v[j] * v1 + w1v[j] * v0 + w0v[j] * pv3;
;                     const float hv2 = bvv[j] + w2v[j] * v2 + w1v[j] * v1 + w0v[j] * v0, hv3 = bvv[j] + w2v[j] * v3 + w1v[j] * v2 + w0v[j] * v1;
;                     const float hg0 = bvg[j] + w2g[j] * g0 + w1g[j] * pg3 + w0g[j] * pg2, hg1 = bvg[j] + w2g[j] * g1 + w1g[j] * g0 + w0g[j] * pg3;
;                     const float hg2 = bvg[j] + w2g[j] * g2 + w1g[j] * g1 + w0g[j] * g0, hg3 = bvg[j] + w2g[j] * g3 + w1g[j] * g2 + w0g[j] * g1;
;                     o[0][j] = hg0 * sigmoidf_(hg0) * hv0; o[1][j] = hg1 * sigmoidf_(hg1) * hv1; o[2][j] = hg2 * sigmoidf_(hg2) * hv2; o[3][j] = hg3 * sigmoidf_(hg3) * hv3; }
; #pragma unroll
;                 for (int m = 0; m < 4; ++m) { u32x2 w; w.x = cvt_pk_bf16(o[m][0], o[m][1]); w.y = cvt_pk_bf16(o[m][2], o[m][3]);
;                     *(u32x2*)(Aout + (size_t)(row0 + ai * 128 + m) * FH + hc0 + 4 * n) = w; } } }
	v_exp_f32_e32 v142, v137
	v_cvt_pk_bf16_f32 v138, v128, v129
	v_add_f32_e32 v128, 1.0, v139
	v_rcp_f32_e32 v128, v128
	v_add_f32_e32 v129, 1.0, v142
	v_rcp_f32_e32 v129, v129
	v_pk_fma_f32 v[142:143], v[82:83], v[170:171], v[174:175]
	v_pk_mul_f32 v[128:129], v[136:137], v[128:129]
	v_pk_fma_f32 v[142:143], v[94:95], v[166:167], v[142:143]
	v_pk_fma_f32 v[136:137], v[76:77], v[168:169], v[172:173]
	v_pk_fma_f32 v[130:131], v[162:163], v[130:131], v[142:143]
	v_pk_fma_f32 v[136:137], v[80:81], v[164:165], v[136:137]
	v_pk_mul_f32 v[128:129], v[130:131], v[128:129]
	v_pk_fma_f32 v[130:131], v[64:65], v[184:185], v[188:189]
	v_pk_fma_f32 v[64:65], v[64:65], v[180:181], v[72:73]
	v_pk_fma_f32 v[130:131], v[68:69], v[180:181], v[130:131]
	v_pk_fma_f32 v[64:65], v[68:69], v[176:177], v[64:65]
	v_pk_fma_f32 v[88:89], v[88:89], v[176:177], v[130:131]
	v_pk_fma_f32 v[92:93], v[92:93], v[160:161], v[136:137]
	v_exp_f32_e32 v130, v88
	v_exp_f32_e32 v131, v89
	v_exp_f32_e32 v72, v64
	v_add_f32_e32 v130, 1.0, v130
	v_add_f32_e32 v131, 1.0, v131
	v_rcp_f32_e32 v130, v130
	v_rcp_f32_e32 v131, v131
	v_pk_fma_f32 v[68:69], v[74:75], v[186:187], v[190:191]
	v_exp_f32_e32 v73, v65
	v_pk_mul_f32 v[88:89], v[88:89], v[130:131]
	v_add_f32_e32 v72, 1.0, v72
	v_pk_mul_f32 v[88:89], v[92:93], v[88:89]
	v_pk_fma_f32 v[92:93], v[66:67], v[186:187], v[190:191]
	v_pk_fma_f32 v[66:67], v[66:67], v[182:183], v[68:69]
	v_pk_fma_f32 v[92:93], v[70:71], v[182:183], v[92:93]
	v_pk_fma_f32 v[66:67], v[70:71], v[178:179], v[66:67]
	v_pk_fma_f32 v[90:91], v[90:91], v[178:179], v[92:93]
	v_exp_f32_e32 v93, v90
	v_exp_f32_e32 v68, v66
	v_exp_f32_e32 v69, v67
	v_exp_f32_e32 v130, v91
	v_add_f32_e32 v73, 1.0, v73
	v_add_f32_e32 v68, 1.0, v68
	v_add_f32_e32 v69, 1.0, v69
	v_cvt_pk_bf16_f32 v92, v88, v89
	v_add_f32_e32 v88, 1.0, v93
	v_add_f32_e32 v89, 1.0, v130
	v_rcp_f32_e32 v72, v72
	v_rcp_f32_e32 v73, v73
	v_rcp_f32_e32 v68, v68
	v_rcp_f32_e32 v69, v69
	v_rcp_f32_e32 v88, v88
	v_rcp_f32_e32 v89, v89
	v_pk_fma_f32 v[74:75], v[86:87], v[170:171], v[174:175]
	v_pk_fma_f32 v[130:131], v[78:79], v[170:171], v[174:175]
	v_pk_fma_f32 v[76:77], v[76:77], v[164:165], v[84:85]
	v_pk_fma_f32 v[70:71], v[78:79], v[166:167], v[74:75]
	v_pk_fma_f32 v[130:131], v[82:83], v[166:167], v[130:131]
	v_pk_fma_f32 v[76:77], v[80:81], v[160:161], v[76:77]
	v_pk_mul_f32 v[64:65], v[64:65], v[72:73]
	v_pk_fma_f32 v[70:71], v[82:83], v[162:163], v[70:71]
	v_pk_mul_f32 v[66:67], v[66:67], v[68:69]
	v_pk_fma_f32 v[94:95], v[94:95], v[162:163], v[130:131]
	v_pk_mul_f32 v[88:89], v[90:91], v[88:89]
	v_pk_mul_f32 v[64:65], v[76:77], v[64:65]
	v_pk_mul_f32 v[66:67], v[70:71], v[66:67]
	v_pk_mul_f32 v[88:89], v[94:95], v[88:89]
	v_cvt_pk_bf16_f32 v64, v64, v65
	v_cvt_pk_bf16_f32 v65, v66, v67
	v_add_u32_e32 v66, 0x83, v246
	v_cvt_pk_bf16_f32 v139, v128, v129
	v_add_u32_e32 v128, 0x81, v246
	v_cvt_pk_bf16_f32 v93, v88, v89
	v_add_u32_e32 v88, 0x82, v246
	v_mad_i64_i32 v[66:67], s[42:43], v66, s82, v[134:135]
	v_mad_i64_i32 v[128:129], s[42:43], v128, s82, v[134:135]
	v_mad_i64_i32 v[88:89], s[42:43], v88, s82, v[134:135]
	v_lshl_add_u64 v[82:83], v[66:67], 0, v[204:205]
	v_lshl_add_u64 v[128:129], v[128:129], 0, v[204:205]
	v_lshl_add_u64 v[88:89], v[88:89], 0, v[204:205]
	v_mov_b32_e32 v148, v64
	v_mov_b32_e32 v149, v65
	v_mov_b32_e32 v64, 0
	v_mov_b32_e32 v70, 0
	v_mov_b32_e32 v71, 0
	v_mov_b32_e32 v72, 0
	v_mov_b32_e32 v73, 0
	v_mov_b32_e32 v78, 0
	v_mov_b32_e32 v79, 0
	v_mov_b32_e32 v80, 0
	v_mov_b32_e32 v81, 0
	v_mov_b32_e32 v66, 0
	v_mov_b32_e32 v67, 0
	v_mov_b32_e32 v68, 0
	v_mov_b32_e32 v69, 0
	v_mov_b32_e32 v74, 0
	v_mov_b32_e32 v75, 0
	v_mov_b32_e32 v76, 0
	v_mov_b32_e32 v77, 0
	v_mov_b32_e32 v154, v138
	v_mov_b32_e32 v155, v139
	v_mov_b32_e32 v198, v92
	v_mov_b32_e32 v199, v93
	s_and_saveexec_b64 s[42:43], s[28:29]
	s_cbranch_execz .LBB0_1372
	ds_read_b128 v[74:77], v242
	ds_read_b128 v[66:69], v241
	ds_read_b128 v[78:81], v240
	ds_read_b128 v[70:73], v239
.LBB0_1372:
	s_or_b64 exec, exec, s[42:43]
	s_waitcnt lgkmcnt(0)
	v_mov_b32_dpp v70, v44 row_shr:1 row_mask:0xf bank_mask:0xf
	v_mov_b32_dpp v71, v45 row_shr:1 row_mask:0xf bank_mask:0xf
	s_waitcnt vmcnt(0)
; #define LAS __attribute__((address_space(3)))
; __device__ __forceinline__ float sigmoidf_(float x) { return __builtin_amdgcn_rcpf(1.0f + __expf(-x)); }
;     __device__ __forceinline__ void operator()(AccRef acc, const Unit& u, int wr, int wc, int fr, int fq) const {
;     ...
;                 f32x4 h2v = (f32x4){0.f, 0.f, 0.f, 0.f}, h3v = h2v, h2g = h2v, h3g = h2v;
;                 const int pb = ai * 2 + wr - 1;
;                 if (pb >= 0 && fr == 0) { const LAS float* xp = xch + (pb * 2) * 256 + clb + 4 * n;
;                     h2v = *(const LAS f32x4*)(xp); h3v = *(const LAS f32x4*)(xp + 256); h2g = *(const LAS f32x4*)(xp + 128); h3g = *(const LAS f32x4*)(xp + 256 + 128); }
;                 float o[4][4];
; #pragma unroll
;                 for (int j = 0; j < 4; ++j) {
;                     const float v0 = acc[ai][0][0][n][j], v1 = acc[ai][0][1][n][j], v2 = acc[ai][0][2][n][j], v3 = acc[ai][0][3][n][j];
;                     const float g0 = acc[ai][1][0][n][j], g1 = acc[ai][1][1][n][j], g2 = acc[ai][1][2][n][j], g3 = acc[ai][1][3][n][j];
;                     const float pv3 = dpp_upd<0x111>(h3v[j], v3), pv2 = dpp_upd<0x111>(h2v[j], v2), pg3 = dpp_upd<0x111>(h3g[j], g3), pg2 = dpp_upd<0x111>(h2g[j], g2);
;                     const float hv0 = bvv[j] + w2v[j] * v0 + w1v[j] * pv3 + w0v[j] * pv2, hv1 = bvv[j] + w2v[j] * v1 + w1v[j] * v0 + w0v[j] * pv3;
;                     const float hv2 = bvv[j] + w2v[j] * v2 + w1v[j] * v1 + w0v[j] * v0, hv3 = bvv[j] + w2v[j] * v3 + w1v[j] * v2 + w0v[j] * v1;
;                     const float hg0 = bvg[j] + w2g[j] * g0 + w1g[j] * pg3 + w0g[j] * pg2, hg1 = bvg[j] + w2g[j] * g1 + w1g[j] * g0 + w0g[j] * pg3;
;                     const float hg2 = bvg[j] + w2g[j] * g2 + w1g[j] * g1 + w0g[j] * g0, hg3 = bvg[j] + w2g[j] * g3 + w1g[j] * g2 + w0g[j] * g1;
;                     o[0][j] = hg0 * sigmoidf_(hg0) * hv0; o[1][j] = hg1 * sigmoidf_(hg1) * hv1; o[2][j] = hg2 * sigmoidf_(hg2) * hv2; o[3][j] = hg3 * sigmoidf_(hg3) * hv3; }
; #pragma unroll
;                 for (int m = 0; m < 4; ++m) { u32x2 w; w.x = cvt_pk_bf16(o[m][0], o[m][1]); w.y = cvt_pk_bf16(o[m][2], o[m][3]);
;                     *(u32x2*)(Aout + (size_t)(row0 + ai * 128 + m) * FH + hc0 + 4 * n) = w; } } }
	v_pk_fma_f32 v[84:85], v[56:57], v[120:121], v[124:125]
	v_mov_b32_dpp v78, v32 row_shr:1 row_mask:0xf bank_mask:0xf
	v_mov_b32_dpp v79, v33 row_shr:1 row_mask:0xf bank_mask:0xf
	v_pk_fma_f32 v[84:85], v[116:117], v[70:71], v[84:85]
	v_mov_b32_dpp v66, v52 row_shr:1 row_mask:0xf bank_mask:0xf
	v_pk_fma_f32 v[78:79], v[112:113], v[78:79], v[84:85]
	v_mov_b32_dpp v67, v53 row_shr:1 row_mask:0xf bank_mask:0xf
	v_exp_f32_e32 v65, v78
	v_exp_f32_e32 v85, v79
	v_pk_fma_f32 v[86:87], v[60:61], v[104:105], v[108:109]
	v_add_f32_e32 v65, 1.0, v65
	v_rcp_f32_e32 v84, v65
	v_add_f32_e32 v65, 1.0, v85
	v_rcp_f32_e32 v85, v65
	v_mov_b32_dpp v74, v40 row_shr:1 row_mask:0xf bank_mask:0xf
	v_mov_b32_dpp v75, v41 row_shr:1 row_mask:0xf bank_mask:0xf
	v_pk_fma_f32 v[86:87], v[100:101], v[66:67], v[86:87]
	v_pk_mul_f32 v[78:79], v[78:79], v[84:85]
	v_pk_fma_f32 v[74:75], v[96:97], v[74:75], v[86:87]
	v_mov_b32_dpp v72, v46 row_shr:1 row_mask:0xf bank_mask:0xf
	v_mov_b32_dpp v73, v47 row_shr:1 row_mask:0xf bank_mask:0xf
	v_pk_mul_f32 v[74:75], v[74:75], v[78:79]
	v_pk_fma_f32 v[78:79], v[58:59], v[122:123], v[126:127]
	v_mov_b32_dpp v80, v34 row_shr:1 row_mask:0xf bank_mask:0xf
	v_mov_b32_dpp v81, v35 row_shr:1 row_mask:0xf bank_mask:0xf
	v_pk_fma_f32 v[78:79], v[118:119], v[72:73], v[78:79]
	v_mov_b32_dpp v68, v54 row_shr:1 row_mask:0xf bank_mask:0xf
	v_pk_fma_f32 v[78:79], v[114:115], v[80:81], v[78:79]
	v_mov_b32_dpp v69, v55 row_shr:1 row_mask:0xf bank_mask:0xf
	v_exp_f32_e32 v65, v78
	v_exp_f32_e32 v81, v79
	v_pk_fma_f32 v[84:85], v[62:63], v[106:107], v[110:111]
	v_add_f32_e32 v65, 1.0, v65
	v_rcp_f32_e32 v80, v65
	v_add_f32_e32 v65, 1.0, v81
	v_rcp_f32_e32 v81, v65
	v_mov_b32_dpp v76, v42 row_shr:1 row_mask:0xf bank_mask:0xf
	v_mov_b32_dpp v77, v43 row_shr:1 row_mask:0xf bank_mask:0xf
	v_pk_fma_f32 v[84:85], v[102:103], v[68:69], v[84:85]
	v_pk_mul_f32 v[78:79], v[78:79], v[80:81]
	v_pk_fma_f32 v[76:77], v[98:99], v[76:77], v[84:85]
	v_cvt_pk_bf16_f32 v74, v74, v75
	v_pk_mul_f32 v[76:77], v[76:77], v[78:79]
	v_pk_fma_f32 v[44:45], v[44:45], v[120:121], v[124:125]
	v_cvt_pk_bf16_f32 v75, v76, v77
	v_pk_fma_f32 v[76:77], v[36:37], v[120:121], v[124:125]
	v_mov_b32_e32 v90, v247
	v_mov_b32_e32 v91, v248
	v_mov_b32_e32 v92, v74
	v_mov_b32_e32 v93, v75
	global_store_dwordx4 v[202:203], v[90:93], off
	v_pk_fma_f32 v[76:77], v[56:57], v[116:117], v[76:77]
	v_pk_fma_f32 v[52:53], v[52:53], v[104:105], v[108:109]
	v_pk_fma_f32 v[70:71], v[112:113], v[70:71], v[76:77]
	s_nop 0
	v_exp_f32_e32 v65, v70
	v_exp_f32_e32 v76, v71
	v_add_f32_e32 v65, 1.0, v65
	v_rcp_f32_e32 v74, v65
	v_add_f32_e32 v65, 1.0, v76
	v_rcp_f32_e32 v75, v65
	v_pk_fma_f32 v[76:77], v[48:49], v[104:105], v[108:109]
	v_pk_mul_f32 v[70:71], v[70:71], v[74:75]
	v_pk_fma_f32 v[76:77], v[60:61], v[100:101], v[76:77]
	v_pk_fma_f32 v[74:75], v[50:51], v[106:107], v[110:111]
	v_pk_fma_f32 v[66:67], v[96:97], v[66:67], v[76:77]
	v_pk_fma_f32 v[74:75], v[62:63], v[102:103], v[74:75]
	v_pk_mul_f32 v[66:67], v[66:67], v[70:71]
	v_pk_fma_f32 v[70:71], v[38:39], v[122:123], v[126:127]
	v_pk_fma_f32 v[68:69], v[98:99], v[68:69], v[74:75]
	v_pk_fma_f32 v[70:71], v[58:59], v[118:119], v[70:71]
	v_cvt_pk_bf16_f32 v66, v66, v67
	v_pk_fma_f32 v[70:71], v[114:115], v[72:73], v[70:71]
	s_nop 0
	v_exp_f32_e32 v65, v70
	v_exp_f32_e32 v73, v71
	v_add_f32_e32 v65, 1.0, v65
	v_rcp_f32_e32 v72, v65
	v_add_f32_e32 v65, 1.0, v73
	v_rcp_f32_e32 v73, v65
	s_nop 0
	v_pk_mul_f32 v[70:71], v[70:71], v[72:73]
	s_nop 0
	v_pk_mul_f32 v[68:69], v[68:69], v[70:71]
	s_nop 0
	v_cvt_pk_bf16_f32 v67, v68, v69
	v_pk_fma_f32 v[68:69], v[32:33], v[120:121], v[124:125]
	v_mov_b32_e32 v134, v249
	v_mov_b32_e32 v135, v250
	v_mov_b32_e32 v136, v66
	v_mov_b32_e32 v137, v67
	global_store_dwordx4 v[196:197], v[134:137], off
	v_pk_fma_f32 v[68:69], v[36:37], v[116:117], v[68:69]
	v_pk_fma_f32 v[32:33], v[32:33], v[116:117], v[44:45]
	v_pk_fma_f32 v[56:57], v[56:57], v[112:113], v[68:69]
	v_pk_fma_f32 v[32:33], v[36:37], v[112:113], v[32:33]
	v_exp_f32_e32 v65, v56
	v_exp_f32_e32 v68, v57
	v_add_f32_e32 v65, 1.0, v65
	v_rcp_f32_e32 v66, v65
	v_add_f32_e32 v65, 1.0, v68
	v_rcp_f32_e32 v67, v65
	v_pk_fma_f32 v[68:69], v[40:41], v[104:105], v[108:109]
	v_exp_f32_e32 v44, v32
	v_pk_fma_f32 v[68:69], v[48:49], v[100:101], v[68:69]
	v_pk_mul_f32 v[56:57], v[56:57], v[66:67]
	v_pk_fma_f32 v[60:61], v[60:61], v[96:97], v[68:69]
	v_pk_fma_f32 v[36:37], v[46:47], v[122:123], v[126:127]
	v_pk_mul_f32 v[56:57], v[60:61], v[56:57]
	v_pk_fma_f32 v[60:61], v[34:35], v[122:123], v[126:127]
	v_pk_fma_f32 v[34:35], v[34:35], v[118:119], v[36:37]
	v_pk_fma_f32 v[60:61], v[38:39], v[118:119], v[60:61]
	v_pk_fma_f32 v[34:35], v[38:39], v[114:115], v[34:35]
	v_pk_fma_f32 v[58:59], v[58:59], v[114:115], v[60:61]
	v_exp_f32_e32 v60, v58
	v_exp_f32_e32 v45, v33
	v_exp_f32_e32 v36, v34
	v_exp_f32_e32 v37, v35
	v_exp_f32_e32 v61, v59
	v_cvt_pk_bf16_f32 v56, v56, v57
	v_add_f32_e32 v57, 1.0, v60
	v_add_f32_e32 v44, 1.0, v44
	v_add_f32_e32 v45, 1.0, v45
	v_add_f32_e32 v36, 1.0, v36
	v_add_f32_e32 v37, 1.0, v37
	v_rcp_f32_e32 v60, v57
	v_add_f32_e32 v57, 1.0, v61
	v_rcp_f32_e32 v44, v44
	v_rcp_f32_e32 v45, v45
	v_rcp_f32_e32 v36, v36
	v_rcp_f32_e32 v37, v37
	v_rcp_f32_e32 v61, v57
	v_pk_fma_f32 v[46:47], v[54:55], v[106:107], v[110:111]
	v_pk_fma_f32 v[66:67], v[42:43], v[106:107], v[110:111]
	v_pk_fma_f32 v[40:41], v[40:41], v[100:101], v[52:53]
	v_pk_fma_f32 v[38:39], v[42:43], v[102:103], v[46:47]
	v_pk_fma_f32 v[66:67], v[50:51], v[102:103], v[66:67]
	v_pk_fma_f32 v[40:41], v[48:49], v[96:97], v[40:41]
	v_pk_mul_f32 v[32:33], v[32:33], v[44:45]
	v_pk_fma_f32 v[38:39], v[50:51], v[98:99], v[38:39]
	v_pk_mul_f32 v[34:35], v[34:35], v[36:37]
	v_pk_fma_f32 v[62:63], v[62:63], v[98:99], v[66:67]
	v_pk_mul_f32 v[58:59], v[58:59], v[60:61]
	v_pk_mul_f32 v[32:33], v[40:41], v[32:33]
	v_pk_mul_f32 v[34:35], v[38:39], v[34:35]
	v_pk_mul_f32 v[58:59], v[62:63], v[58:59]
	v_cvt_pk_bf16_f32 v32, v32, v33
	v_cvt_pk_bf16_f32 v33, v34, v35
	v_cvt_pk_bf16_f32 v57, v58, v59
	v_mov_b32_e32 v158, v251
	v_mov_b32_e32 v159, v253
	v_mov_b32_e32 v160, v32
	v_mov_b32_e32 v161, v33
	global_store_dwordx4 v[140:141], v[158:161], off
	v_mov_b32_e32 v65, 0
	v_mov_b32_e32 v66, 0
	v_mov_b32_e32 v67, 0
	v_mov_b32_e32 v40, 0
	v_mov_b32_e32 v41, 0
	v_mov_b32_e32 v42, 0
	v_mov_b32_e32 v43, 0
	v_mov_b32_e32 v32, 0
	v_mov_b32_e32 v33, 0
	v_mov_b32_e32 v34, 0
	v_mov_b32_e32 v35, 0
	v_mov_b32_e32 v36, 0
	v_mov_b32_e32 v37, 0
	v_mov_b32_e32 v38, 0
	v_mov_b32_e32 v39, 0
	v_mov_b32_e32 v162, v254
	v_mov_b32_e32 v163, v255
	v_mov_b32_e32 v164, v56
	v_mov_b32_e32 v165, v57
	global_store_dwordx4 v[152:153], v[162:165], off
	s_and_saveexec_b64 s[42:43], s[30:31]
	s_cbranch_execz .LBB0_1355
	ds_read_b128 v[36:39], v237 offset:2064
	ds_read_b128 v[40:43], v237 offset:2576
	ds_read_b128 v[32:35], v237 offset:3088
	ds_read_b128 v[64:67], v237 offset:3600
	s_branch .LBB0_1355

; #define LAS __attribute__((address_space(3)))
; __device__ __forceinline__ float sigmoidf_(float x) { return __builtin_amdgcn_rcpf(1.0f + __expf(-x)); }
;     __device__ __forceinline__ void operator()(AccRef acc, const Unit& u, int wr, int wc, int fr, int fq) const {
;     ...
;                 f32x4 h2v = (f32x4){0.f, 0.f, 0.f, 0.f}, h3v = h2v, h2g = h2v, h3g = h2v;
;                 const int pb = ai * 2 + wr - 1;
;                 if (pb >= 0 && fr == 0) { const LAS float* xp = xch + (pb * 2) * 256 + clb + 4 * n;
;                     h2v = *(const LAS f32x4*)(xp); h3v = *(const LAS f32x4*)(xp + 256); h2g = *(const LAS f32x4*)(xp + 128); h3g = *(const LAS f32x4*)(xp + 256 + 128); }
;                 float o[4][4];
; #pragma unroll
;                 for (int j = 0; j < 4; ++j) {
;                     const float v0 = acc[ai][0][0][n][j], v1 = acc[ai][0][1][n][j], v2 = acc[ai][0][2][n][j], v3 = acc[ai][0][3][n][j];
;                     const float g0 = acc[ai][1][0][n][j], g1 = acc[ai][1][1][n][j], g2 = acc[ai][1][2][n][j], g3 = acc[ai][1][3][n][j];
;                     const float pv3 = dpp_upd<0x111>(h3v[j], v3), pv2 = dpp_upd<0x111>(h2v[j], v2), pg3 = dpp_upd<0x111>(h3g[j], g3), pg2 = dpp_upd<0x111>(h2g[j], g2);
;                     const float hv0 = bvv[j] + w2v[j] * v0 + w1v[j] * pv3 + w0v[j] * pv2, hv1 = bvv[j] + w2v[j] * v1 + w1v[j] * v0 + w0v[j] * pv3;
;                     const float hv2 = bvv[j] + w2v[j] * v2 + w1v[j] * v1 + w0v[j] * v0, hv3 = bvv[j] + w2v[j] * v3 + w1v[j] * v2 + w0v[j] * v1;
;                     const float hg0 = bvg[j] + w2g[j] * g0 + w1g[j] * pg3 + w0g[j] * pg2, hg1 = bvg[j] + w2g[j] * g1 + w1g[j] * g0 + w0g[j] * pg3;
;                     const float hg2 = bvg[j] + w2g[j] * g2 + w1g[j] * g1 + w0g[j] * g0, hg3 = bvg[j] + w2g[j] * g3 + w1g[j] * g2 + w0g[j] * g1;
;                     o[0][j] = hg0 * sigmoidf_(hg0) * hv0; o[1][j] = hg1 * sigmoidf_(hg1) * hv1; o[2][j] = hg2 * sigmoidf_(hg2) * hv2; o[3][j] = hg3 * sigmoidf_(hg3) * hv3; }
; #pragma unroll
;                 for (int m = 0; m < 4; ++m) { u32x2 w; w.x = cvt_pk_bf16(o[m][0], o[m][1]); w.y = cvt_pk_bf16(o[m][2], o[m][3]);
;                     *(u32x2*)(Aout + (size_t)(row0 + ai * 128 + m) * FH + hc0 + 4 * n) = w; } } }
.LBB0_1936:
	s_or_b64 exec, exec, s[34:35]
	s_waitcnt lgkmcnt(0)
	v_mov_b32_dpp v64, v8 row_shr:1 row_mask:0xf bank_mask:0xf
	v_mov_b32_dpp v65, v9 row_shr:1 row_mask:0xf bank_mask:0xf
	v_pk_fma_f32 v[44:45], v[24:25], v[120:121], v[124:125]
	v_mov_b32_dpp v40, v0 row_shr:1 row_mask:0xf bank_mask:0xf
	v_mov_b32_dpp v41, v1 row_shr:1 row_mask:0xf bank_mask:0xf
	v_pk_fma_f32 v[44:45], v[116:117], v[64:65], v[44:45]
	v_mov_b32_dpp v32, v20 row_shr:1 row_mask:0xf bank_mask:0xf
	v_pk_fma_f32 v[40:41], v[112:113], v[40:41], v[44:45]
	v_mov_b32_dpp v33, v21 row_shr:1 row_mask:0xf bank_mask:0xf
	v_exp_f32_e32 v44, v40
	v_exp_f32_e32 v45, v41
	v_pk_fma_f32 v[46:47], v[28:29], v[104:105], v[108:109]
	v_mov_b32_dpp v36, v12 row_shr:1 row_mask:0xf bank_mask:0xf
	v_add_f32_e32 v44, 1.0, v44
	v_add_f32_e32 v45, 1.0, v45
	v_rcp_f32_e32 v44, v44
	v_rcp_f32_e32 v45, v45
	v_mov_b32_dpp v37, v13 row_shr:1 row_mask:0xf bank_mask:0xf
	v_pk_fma_f32 v[46:47], v[100:101], v[32:33], v[46:47]
	v_mov_b32_dpp v66, v10 row_shr:1 row_mask:0xf bank_mask:0xf
	v_pk_fma_f32 v[36:37], v[96:97], v[36:37], v[46:47]
	v_pk_mul_f32 v[40:41], v[40:41], v[44:45]
	v_mov_b32_dpp v67, v11 row_shr:1 row_mask:0xf bank_mask:0xf
	v_pk_mul_f32 v[36:37], v[36:37], v[40:41]
	v_pk_fma_f32 v[40:41], v[26:27], v[122:123], v[126:127]
	v_mov_b32_dpp v42, v2 row_shr:1 row_mask:0xf bank_mask:0xf
	v_mov_b32_dpp v43, v3 row_shr:1 row_mask:0xf bank_mask:0xf
	v_pk_fma_f32 v[40:41], v[118:119], v[66:67], v[40:41]
	v_cvt_pk_bf16_f32 v36, v36, v37
	v_pk_fma_f32 v[40:41], v[114:115], v[42:43], v[40:41]
	v_mov_b32_dpp v34, v22 row_shr:1 row_mask:0xf bank_mask:0xf
	v_exp_f32_e32 v42, v40
	v_exp_f32_e32 v43, v41
	v_mov_b32_dpp v35, v23 row_shr:1 row_mask:0xf bank_mask:0xf
	v_add_f32_e32 v37, 1.0, v42
	v_rcp_f32_e32 v42, v37
	v_add_f32_e32 v37, 1.0, v43
	v_rcp_f32_e32 v43, v37
	v_pk_fma_f32 v[44:45], v[30:31], v[106:107], v[110:111]
	v_mov_b32_dpp v38, v14 row_shr:1 row_mask:0xf bank_mask:0xf
	v_mov_b32_dpp v39, v15 row_shr:1 row_mask:0xf bank_mask:0xf
	v_pk_fma_f32 v[44:45], v[102:103], v[34:35], v[44:45]
	v_pk_mul_f32 v[40:41], v[40:41], v[42:43]
	v_pk_fma_f32 v[38:39], v[98:99], v[38:39], v[44:45]
	v_pk_fma_f32 v[8:9], v[8:9], v[120:121], v[124:125]
	v_pk_mul_f32 v[38:39], v[38:39], v[40:41]
	v_pk_fma_f32 v[20:21], v[20:21], v[104:105], v[108:109]
	v_cvt_pk_bf16_f32 v37, v38, v39
	v_pk_fma_f32 v[38:39], v[4:5], v[120:121], v[124:125]
	v_mov_b32_e32 v146, v36
	v_mov_b32_e32 v147, v37
	global_store_dwordx4 v[132:133], v[144:147], off
	v_pk_fma_f32 v[38:39], v[24:25], v[116:117], v[38:39]
	s_and_b64 vcc, exec, s[10:11]
	v_pk_fma_f32 v[38:39], v[112:113], v[64:65], v[38:39]
	s_mov_b32 s35, s24
	v_exp_f32_e32 v40, v38
	v_exp_f32_e32 v41, v39
	s_mov_b32 s34, s26
	s_mov_b64 s[38:39], s[30:31]
	v_add_f32_e32 v36, 1.0, v40
	v_add_f32_e32 v37, 1.0, v41
	v_rcp_f32_e32 v36, v36
	v_rcp_f32_e32 v37, v37
	v_pk_fma_f32 v[40:41], v[16:17], v[104:105], v[108:109]
	s_mov_b64 s[36:37], s[28:29]
	v_pk_fma_f32 v[40:41], v[28:29], v[100:101], v[40:41]
	v_pk_mul_f32 v[36:37], v[38:39], v[36:37]
	v_pk_fma_f32 v[32:33], v[96:97], v[32:33], v[40:41]
	v_pk_fma_f32 v[40:41], v[18:19], v[106:107], v[110:111]
	v_pk_mul_f32 v[32:33], v[32:33], v[36:37]
	v_pk_fma_f32 v[36:37], v[6:7], v[122:123], v[126:127]
	v_cvt_pk_bf16_f32 v32, v32, v33
	v_pk_fma_f32 v[36:37], v[26:27], v[118:119], v[36:37]
	v_pk_fma_f32 v[40:41], v[30:31], v[102:103], v[40:41]
	v_pk_fma_f32 v[36:37], v[114:115], v[66:67], v[36:37]
	v_pk_fma_f32 v[34:35], v[98:99], v[34:35], v[40:41]
	v_exp_f32_e32 v38, v36
	v_exp_f32_e32 v39, v37
	v_add_f32_e32 v33, 1.0, v38
	v_rcp_f32_e32 v38, v33
	v_add_f32_e32 v33, 1.0, v39
	v_rcp_f32_e32 v39, v33
	s_nop 0
	v_pk_mul_f32 v[36:37], v[36:37], v[38:39]
	s_nop 0
	v_pk_mul_f32 v[34:35], v[34:35], v[36:37]
	s_nop 0
	v_cvt_pk_bf16_f32 v33, v34, v35
	v_pk_fma_f32 v[34:35], v[0:1], v[120:121], v[124:125]
	v_mov_b32_e32 v156, v32
	v_mov_b32_e32 v157, v33
	global_store_dwordx4 v[128:129], v[154:157], off
	v_pk_fma_f32 v[34:35], v[4:5], v[116:117], v[34:35]
	v_pk_fma_f32 v[0:1], v[0:1], v[116:117], v[8:9]
	v_pk_fma_f32 v[24:25], v[24:25], v[112:113], v[34:35]
	v_pk_fma_f32 v[0:1], v[4:5], v[112:113], v[0:1]
	v_exp_f32_e32 v34, v24
	v_exp_f32_e32 v35, v25
	v_exp_f32_e32 v8, v0
	v_add_f32_e32 v32, 1.0, v34
	v_add_f32_e32 v33, 1.0, v35
	v_rcp_f32_e32 v32, v32
	v_rcp_f32_e32 v33, v33
	v_pk_fma_f32 v[34:35], v[12:13], v[104:105], v[108:109]
	v_pk_fma_f32 v[4:5], v[10:11], v[122:123], v[126:127]
	v_pk_fma_f32 v[34:35], v[16:17], v[100:101], v[34:35]
	v_pk_mul_f32 v[24:25], v[24:25], v[32:33]
	v_pk_fma_f32 v[28:29], v[28:29], v[96:97], v[34:35]
	v_pk_mul_f32 v[24:25], v[28:29], v[24:25]
	v_pk_fma_f32 v[28:29], v[2:3], v[122:123], v[126:127]
	v_pk_fma_f32 v[2:3], v[2:3], v[118:119], v[4:5]
	v_pk_fma_f32 v[28:29], v[6:7], v[118:119], v[28:29]
	v_pk_fma_f32 v[2:3], v[6:7], v[114:115], v[2:3]
	v_pk_fma_f32 v[26:27], v[26:27], v[114:115], v[28:29]
	v_exp_f32_e32 v28, v26
	v_exp_f32_e32 v29, v27
	v_exp_f32_e32 v9, v1
	v_exp_f32_e32 v4, v2
	v_exp_f32_e32 v5, v3
	v_cvt_pk_bf16_f32 v24, v24, v25
	v_add_f32_e32 v25, 1.0, v28
	v_rcp_f32_e32 v28, v25
	v_add_f32_e32 v25, 1.0, v29
	v_add_f32_e32 v8, 1.0, v8
	v_add_f32_e32 v9, 1.0, v9
	v_add_f32_e32 v4, 1.0, v4
	v_add_f32_e32 v5, 1.0, v5
	v_rcp_f32_e32 v29, v25
	v_rcp_f32_e32 v8, v8
	v_rcp_f32_e32 v9, v9
	v_rcp_f32_e32 v4, v4
	v_rcp_f32_e32 v5, v5
	v_pk_fma_f32 v[32:33], v[14:15], v[106:107], v[110:111]
	v_pk_fma_f32 v[10:11], v[22:23], v[106:107], v[110:111]
	v_pk_fma_f32 v[32:33], v[18:19], v[102:103], v[32:33]
	v_pk_fma_f32 v[12:13], v[12:13], v[100:101], v[20:21]
	v_pk_fma_f32 v[6:7], v[14:15], v[102:103], v[10:11]
	v_pk_fma_f32 v[30:31], v[30:31], v[98:99], v[32:33]
	v_pk_mul_f32 v[26:27], v[26:27], v[28:29]
	v_pk_fma_f32 v[12:13], v[16:17], v[96:97], v[12:13]
	v_pk_mul_f32 v[0:1], v[0:1], v[8:9]
	v_pk_fma_f32 v[6:7], v[18:19], v[98:99], v[6:7]
	v_pk_mul_f32 v[2:3], v[2:3], v[4:5]
	v_pk_mul_f32 v[26:27], v[30:31], v[26:27]
	v_pk_mul_f32 v[0:1], v[12:13], v[0:1]
	v_pk_mul_f32 v[2:3], v[6:7], v[2:3]
	v_cvt_pk_bf16_f32 v25, v26, v27
	v_cvt_pk_bf16_f32 v0, v0, v1
	v_cvt_pk_bf16_f32 v1, v2, v3
	v_mov_b32_e32 v200, v24
	v_mov_b32_e32 v201, v25
	global_store_dwordx4 v[88:89], v[198:201], off
	v_mov_b32_e32 v150, v0
	v_mov_b32_e32 v151, v1
	global_store_dwordx4 v[82:83], v[148:151], off
	s_cbranch_vccnz .LBB0_1955

; #define LAS __attribute__((address_space(3)))
; __device__ __forceinline__ float sigmoidf_(float x) { return __builtin_amdgcn_rcpf(1.0f + __expf(-x)); }
;     __device__ __forceinline__ void operator()(AccRef acc, const Unit& u, int wr, int wc, int fr, int fq) const {
;     ...
;                 f32x4 h2v = (f32x4){0.f, 0.f, 0.f, 0.f}, h3v = h2v, h2g = h2v, h3g = h2v;
;                 const int pb = ai * 2 + wr - 1;
;                 if (pb >= 0 && fr == 0) { const LAS float* xp = xch + (pb * 2) * 256 + clb + 4 * n;
;                     h2v = *(const LAS f32x4*)(xp); h3v = *(const LAS f32x4*)(xp + 256); h2g = *(const LAS f32x4*)(xp + 128); h3g = *(const LAS f32x4*)(xp + 256 + 128); }
;                 float o[4][4];
; #pragma unroll
;                 for (int j = 0; j < 4; ++j) {
;                     const float v0 = acc[ai][0][0][n][j], v1 = acc[ai][0][1][n][j], v2 = acc[ai][0][2][n][j], v3 = acc[ai][0][3][n][j];
;                     const float g0 = acc[ai][1][0][n][j], g1 = acc[ai][1][1][n][j], g2 = acc[ai][1][2][n][j], g3 = acc[ai][1][3][n][j];
;                     const float pv3 = dpp_upd<0x111>(h3v[j], v3), pv2 = dpp_upd<0x111>(h2v[j], v2), pg3 = dpp_upd<0x111>(h3g[j], g3), pg2 = dpp_upd<0x111>(h2g[j], g2);
;                     const float hv0 = bvv[j] + w2v[j] * v0 + w1v[j] * pv3 + w0v[j] * pv2, hv1 = bvv[j] + w2v[j] * v1 + w1v[j] * v0 + w0v[j] * pv3;
;                     const float hv2 = bvv[j] + w2v[j] * v2 + w1v[j] * v1 + w0v[j] * v0, hv3 = bvv[j] + w2v[j] * v3 + w1v[j] * v2 + w0v[j] * v1;
;                     const float hg0 = bvg[j] + w2g[j] * g0 + w1g[j] * pg3 + w0g[j] * pg2, hg1 = bvg[j] + w2g[j] * g1 + w1g[j] * g0 + w0g[j] * pg3;
;                     const float hg2 = bvg[j] + w2g[j] * g2 + w1g[j] * g1 + w0g[j] * g0, hg3 = bvg[j] + w2g[j] * g3 + w1g[j] * g2 + w0g[j] * g1;
;                     o[0][j] = hg0 * sigmoidf_(hg0) * hv0; o[1][j] = hg1 * sigmoidf_(hg1) * hv1; o[2][j] = hg2 * sigmoidf_(hg2) * hv2; o[3][j] = hg3 * sigmoidf_(hg3) * hv3; }
; #pragma unroll
;                 for (int m = 0; m < 4; ++m) { u32x2 w; w.x = cvt_pk_bf16(o[m][0], o[m][1]); w.y = cvt_pk_bf16(o[m][2], o[m][3]);
;                     *(u32x2*)(Aout + (size_t)(row0 + ai * 128 + m) * FH + hc0 + 4 * n) = w; } } }
.LBB0_1947:
	s_or_b64 exec, exec, s[40:41]
	v_pk_fma_f32 v[246:247], v[152:153], v[184:185], v[188:189]
	v_mov_b32_dpp v206, v128 row_shr:1 row_mask:0xf bank_mask:0xf
	v_mov_b32_dpp v207, v129 row_shr:1 row_mask:0xf bank_mask:0xf
	v_pk_fma_f32 v[246:247], v[180:181], v[198:199], v[246:247]
	v_mov_b32_dpp v194, v148 row_shr:1 row_mask:0xf bank_mask:0xf
	v_pk_fma_f32 v[206:207], v[176:177], v[206:207], v[246:247]
	v_mov_b32_dpp v195, v149 row_shr:1 row_mask:0xf bank_mask:0xf
	v_exp_f32_e32 v193, v206
	v_exp_f32_e32 v247, v207
	v_pk_fma_f32 v[248:249], v[156:157], v[168:169], v[172:173]
	v_add_f32_e32 v193, 1.0, v193
	v_rcp_f32_e32 v246, v193
	v_add_f32_e32 v193, 1.0, v247
	v_rcp_f32_e32 v247, v193
	v_mov_b32_dpp v202, v136 row_shr:1 row_mask:0xf bank_mask:0xf
	v_mov_b32_dpp v203, v137 row_shr:1 row_mask:0xf bank_mask:0xf
	v_pk_fma_f32 v[248:249], v[164:165], v[194:195], v[248:249]
	v_pk_mul_f32 v[206:207], v[206:207], v[246:247]
	v_pk_fma_f32 v[202:203], v[160:161], v[202:203], v[248:249]
	v_mov_b32_dpp v200, v142 row_shr:1 row_mask:0xf bank_mask:0xf
	v_mov_b32_dpp v201, v143 row_shr:1 row_mask:0xf bank_mask:0xf
	v_pk_mul_f32 v[202:203], v[202:203], v[206:207]
	v_pk_fma_f32 v[206:207], v[154:155], v[186:187], v[190:191]
	v_mov_b32_dpp v208, v130 row_shr:1 row_mask:0xf bank_mask:0xf
	v_mov_b32_dpp v209, v131 row_shr:1 row_mask:0xf bank_mask:0xf
	v_pk_fma_f32 v[206:207], v[182:183], v[200:201], v[206:207]
	v_mov_b32_dpp v196, v150 row_shr:1 row_mask:0xf bank_mask:0xf
	v_pk_fma_f32 v[206:207], v[178:179], v[208:209], v[206:207]
	v_mov_b32_dpp v197, v151 row_shr:1 row_mask:0xf bank_mask:0xf
	v_exp_f32_e32 v193, v206
	v_exp_f32_e32 v209, v207
	v_cvt_pk_bf16_f32 v208, v202, v203
	v_add_f32_e32 v193, 1.0, v193
	v_rcp_f32_e32 v202, v193
	v_add_f32_e32 v193, 1.0, v209
	v_rcp_f32_e32 v203, v193
	v_pk_fma_f32 v[246:247], v[158:159], v[170:171], v[174:175]
	v_mov_b32_dpp v204, v138 row_shr:1 row_mask:0xf bank_mask:0xf
	v_mov_b32_dpp v205, v139 row_shr:1 row_mask:0xf bank_mask:0xf
	v_pk_fma_f32 v[246:247], v[166:167], v[196:197], v[246:247]
	v_pk_mul_f32 v[202:203], v[206:207], v[202:203]
	v_pk_fma_f32 v[204:205], v[162:163], v[204:205], v[246:247]
	v_lshl_add_u32 v245, s34, 8, v235
	v_pk_mul_f32 v[202:203], v[204:205], v[202:203]
	v_lshlrev_b64 v[204:205], 1, v[232:233]
	v_pk_fma_f32 v[232:233], v[132:133], v[184:185], v[188:189]
	v_mov_b64_e32 v[206:207], s[60:61]
	v_pk_fma_f32 v[232:233], v[152:153], v[180:181], v[232:233]
	v_cvt_pk_bf16_f32 v209, v202, v203
	v_pk_fma_f32 v[198:199], v[176:177], v[198:199], v[232:233]
	v_mad_i64_i32 v[202:203], s[34:35], v245, s63, v[206:207]
	v_exp_f32_e32 v193, v198
	v_exp_f32_e32 v232, v199
	v_lshl_add_u64 v[202:203], v[202:203], 0, v[204:205]
	v_add_f32_e32 v193, 1.0, v193
	v_mov_b32_e32 v246, v208
	v_mov_b32_e32 v247, v209
	v_rcp_f32_e32 v208, v193
	v_add_f32_e32 v193, 1.0, v232
	v_rcp_f32_e32 v209, v193
	v_pk_fma_f32 v[232:233], v[144:145], v[168:169], v[172:173]
	v_pk_fma_f32 v[140:141], v[140:141], v[184:185], v[188:189]
	v_pk_fma_f32 v[232:233], v[156:157], v[164:165], v[232:233]
	v_pk_mul_f32 v[198:199], v[198:199], v[208:209]
	v_pk_fma_f32 v[194:195], v[160:161], v[194:195], v[232:233]
	v_pk_fma_f32 v[208:209], v[146:147], v[170:171], v[174:175]
	v_pk_mul_f32 v[194:195], v[194:195], v[198:199]
	v_pk_fma_f32 v[198:199], v[134:135], v[186:187], v[190:191]
	v_pk_fma_f32 v[208:209], v[158:159], v[166:167], v[208:209]
	v_pk_fma_f32 v[198:199], v[154:155], v[182:183], v[198:199]
	v_pk_fma_f32 v[196:197], v[162:163], v[196:197], v[208:209]
	v_pk_fma_f32 v[198:199], v[178:179], v[200:201], v[198:199]
	v_cvt_pk_bf16_f32 v194, v194, v195
	v_exp_f32_e32 v193, v198
	v_exp_f32_e32 v201, v199
	v_pk_fma_f32 v[148:149], v[148:149], v[168:169], v[172:173]
	v_add_f32_e32 v193, 1.0, v193
	v_rcp_f32_e32 v200, v193
	v_add_f32_e32 v193, 1.0, v201
	v_rcp_f32_e32 v201, v193
	v_or_b32_e32 v193, 1, v245
	v_pk_mul_f32 v[198:199], v[198:199], v[200:201]
	s_nop 0
	v_pk_mul_f32 v[196:197], v[196:197], v[198:199]
	v_pk_fma_f32 v[198:199], v[128:129], v[184:185], v[188:189]
	v_cvt_pk_bf16_f32 v195, v196, v197
	v_pk_fma_f32 v[198:199], v[132:133], v[180:181], v[198:199]
	v_mad_i64_i32 v[196:197], s[34:35], v193, s63, v[206:207]
	v_pk_fma_f32 v[152:153], v[152:153], v[176:177], v[198:199]
	v_lshl_add_u64 v[196:197], v[196:197], 0, v[204:205]
	v_exp_f32_e32 v193, v152
	v_exp_f32_e32 v198, v153
	v_mov_b32_e32 v248, v194
	v_mov_b32_e32 v249, v195
	v_add_f32_e32 v193, 1.0, v193
	v_rcp_f32_e32 v194, v193
	v_add_f32_e32 v193, 1.0, v198
	v_rcp_f32_e32 v195, v193
	v_pk_fma_f32 v[198:199], v[136:137], v[168:169], v[172:173]
	v_pk_fma_f32 v[128:129], v[128:129], v[180:181], v[140:141]
	v_pk_fma_f32 v[198:199], v[144:145], v[164:165], v[198:199]
	v_pk_fma_f32 v[128:129], v[132:133], v[176:177], v[128:129]
	v_pk_fma_f32 v[156:157], v[156:157], v[160:161], v[198:199]
	v_pk_mul_f32 v[152:153], v[152:153], v[194:195]
	v_pk_mul_f32 v[152:153], v[156:157], v[152:153]
	v_pk_fma_f32 v[156:157], v[130:131], v[186:187], v[190:191]
	v_exp_f32_e32 v140, v128
	v_pk_fma_f32 v[132:133], v[142:143], v[186:187], v[190:191]
	v_pk_fma_f32 v[156:157], v[134:135], v[182:183], v[156:157]
	v_pk_fma_f32 v[130:131], v[130:131], v[182:183], v[132:133]
	v_pk_fma_f32 v[154:155], v[154:155], v[178:179], v[156:157]
	v_pk_fma_f32 v[130:131], v[134:135], v[178:179], v[130:131]
	v_exp_f32_e32 v157, v154
	v_exp_f32_e32 v141, v129
	v_exp_f32_e32 v132, v130
	v_exp_f32_e32 v133, v131
	v_exp_f32_e32 v193, v155
	v_add_f32_e32 v140, 1.0, v140
	v_add_f32_e32 v141, 1.0, v141
	v_add_f32_e32 v132, 1.0, v132
	v_add_f32_e32 v133, 1.0, v133
	v_cvt_pk_bf16_f32 v156, v152, v153
	v_add_f32_e32 v152, 1.0, v157
; #define LAS __attribute__((address_space(3)))
; __device__ __forceinline__ float sigmoidf_(float x) { return __builtin_amdgcn_rcpf(1.0f + __expf(-x)); }
;     __device__ __forceinline__ void operator()(AccRef acc, const Unit& u, int wr, int wc, int fr, int fq) const {
;     ...
;                 f32x4 h2v = (f32x4){0.f, 0.f, 0.f, 0.f}, h3v = h2v, h2g = h2v, h3g = h2v;
;                 const int pb = ai * 2 + wr - 1;
;                 if (pb >= 0 && fr == 0) { const LAS float* xp = xch + (pb * 2) * 256 + clb + 4 * n;
;                     h2v = *(const LAS f32x4*)(xp); h3v = *(const LAS f32x4*)(xp + 256); h2g = *(const LAS f32x4*)(xp + 128); h3g = *(const LAS f32x4*)(xp + 256 + 128); }
;                 float o[4][4];
; #pragma unroll
;                 for (int j = 0; j < 4; ++j) {
;                     const float v0 = acc[ai][0][0][n][j], v1 = acc[ai][0][1][n][j], v2 = acc[ai][0][2][n][j], v3 = acc[ai][0][3][n][j];
;                     const float g0 = acc[ai][1][0][n][j], g1 = acc[ai][1][1][n][j], g2 = acc[ai][1][2][n][j], g3 = acc[ai][1][3][n][j];
;                     const float pv3 = dpp_upd<0x111>(h3v[j], v3), pv2 = dpp_upd<0x111>(h2v[j], v2), pg3 = dpp_upd<0x111>(h3g[j], g3), pg2 = dpp_upd<0x111>(h2g[j], g2);
;                     const float hv0 = bvv[j] + w2v[j] * v0 + w1v[j] * pv3 + w0v[j] * pv2, hv1 = bvv[j] + w2v[j] * v1 + w1v[j] * v0 + w0v[j] * pv3;
;                     const float hv2 = bvv[j] + w2v[j] * v2 + w1v[j] * v1 + w0v[j] * v0, hv3 = bvv[j] + w2v[j] * v3 + w1v[j] * v2 + w0v[j] * v1;
;                     const float hg0 = bvg[j] + w2g[j] * g0 + w1g[j] * pg3 + w0g[j] * pg2, hg1 = bvg[j] + w2g[j] * g1 + w1g[j] * g0 + w0g[j] * pg3;
;                     const float hg2 = bvg[j] + w2g[j] * g2 + w1g[j] * g1 + w0g[j] * g0, hg3 = bvg[j] + w2g[j] * g3 + w1g[j] * g2 + w0g[j] * g1;
;                     o[0][j] = hg0 * sigmoidf_(hg0) * hv0; o[1][j] = hg1 * sigmoidf_(hg1) * hv1; o[2][j] = hg2 * sigmoidf_(hg2) * hv2; o[3][j] = hg3 * sigmoidf_(hg3) * hv3; }
; #pragma unroll
;                 for (int m = 0; m < 4; ++m) { u32x2 w; w.x = cvt_pk_bf16(o[m][0], o[m][1]); w.y = cvt_pk_bf16(o[m][2], o[m][3]);
;                     *(u32x2*)(Aout + (size_t)(row0 + ai * 128 + m) * FH + hc0 + 4 * n) = w; } } }
	v_add_f32_e32 v153, 1.0, v193
	v_rcp_f32_e32 v140, v140
	v_rcp_f32_e32 v141, v141
	v_rcp_f32_e32 v132, v132
	v_rcp_f32_e32 v133, v133
	v_rcp_f32_e32 v152, v152
	v_rcp_f32_e32 v153, v153
	v_pk_fma_f32 v[142:143], v[150:151], v[170:171], v[174:175]
	v_pk_fma_f32 v[194:195], v[138:139], v[170:171], v[174:175]
	v_pk_fma_f32 v[136:137], v[136:137], v[164:165], v[148:149]
	v_pk_fma_f32 v[134:135], v[138:139], v[166:167], v[142:143]
	v_pk_fma_f32 v[194:195], v[146:147], v[166:167], v[194:195]
	v_pk_fma_f32 v[136:137], v[144:145], v[160:161], v[136:137]
	v_pk_mul_f32 v[128:129], v[128:129], v[140:141]
	v_pk_fma_f32 v[134:135], v[146:147], v[162:163], v[134:135]
	v_pk_mul_f32 v[130:131], v[130:131], v[132:133]
	v_pk_fma_f32 v[158:159], v[158:159], v[162:163], v[194:195]
	v_pk_mul_f32 v[152:153], v[154:155], v[152:153]
	v_pk_mul_f32 v[128:129], v[136:137], v[128:129]
	v_pk_mul_f32 v[130:131], v[134:135], v[130:131]
	v_pk_mul_f32 v[152:153], v[158:159], v[152:153]
	v_cvt_pk_bf16_f32 v128, v128, v129
	v_cvt_pk_bf16_f32 v129, v130, v131
	v_or_b32_e32 v130, 3, v245
	v_cvt_pk_bf16_f32 v157, v152, v153
	v_or_b32_e32 v152, 2, v245
	v_mad_i64_i32 v[130:131], s[34:35], v130, s63, v[206:207]
	v_mad_i64_i32 v[152:153], s[34:35], v152, s63, v[206:207]
	v_lshl_add_u64 v[140:141], v[130:131], 0, v[204:205]
	v_lshl_add_u64 v[152:153], v[152:153], 0, v[204:205]
	v_mov_b32_e32 v250, v128
	v_mov_b32_e32 v251, v129
	v_mov_b32_e32 v193, 0
	v_mov_b32_e32 v194, 0
	v_mov_b32_e32 v195, 0
	v_mov_b32_e32 v136, 0
	v_mov_b32_e32 v137, 0
	v_mov_b32_e32 v138, 0
	v_mov_b32_e32 v139, 0
	v_mov_b32_e32 v128, 0
	v_mov_b32_e32 v129, 0
	v_mov_b32_e32 v130, 0
	v_mov_b32_e32 v131, 0
	v_mov_b32_e32 v132, 0
	v_mov_b32_e32 v133, 0
	v_mov_b32_e32 v134, 0
	v_mov_b32_e32 v135, 0
	v_mov_b32_e32 v253, v156
	v_mov_b32_e32 v254, v157
	s_and_saveexec_b64 s[34:35], s[22:23]
	s_cbranch_execz .LBB0_1951
	ds_read_b128 v[132:135], v236 offset:2048
	ds_read_b128 v[136:139], v236 offset:2560
	ds_read_b128 v[128:131], v236 offset:3072
	ds_read_b128 v[192:195], v236 offset:3584
.LBB0_1951:
	s_or_b64 exec, exec, s[34:35]
	s_waitcnt lgkmcnt(0)
	v_mov_b32_dpp v192, v72 row_shr:1 row_mask:0xf bank_mask:0xf
	v_mov_b32_dpp v193, v73 row_shr:1 row_mask:0xf bank_mask:0xf
	v_pk_fma_f32 v[142:143], v[88:89], v[184:185], v[188:189]
	v_mov_b32_dpp v136, v64 row_shr:1 row_mask:0xf bank_mask:0xf
	v_mov_b32_dpp v137, v65 row_shr:1 row_mask:0xf bank_mask:0xf
	v_pk_fma_f32 v[142:143], v[180:181], v[192:193], v[142:143]
	v_mov_b32_dpp v128, v84 row_shr:1 row_mask:0xf bank_mask:0xf
	v_pk_fma_f32 v[136:137], v[176:177], v[136:137], v[142:143]
	v_mov_b32_dpp v129, v85 row_shr:1 row_mask:0xf bank_mask:0xf
	v_exp_f32_e32 v142, v136
	v_exp_f32_e32 v143, v137
	v_pk_fma_f32 v[144:145], v[92:93], v[168:169], v[172:173]
	v_mov_b32_dpp v132, v76 row_shr:1 row_mask:0xf bank_mask:0xf
	v_add_f32_e32 v142, 1.0, v142
	v_add_f32_e32 v143, 1.0, v143
	v_rcp_f32_e32 v142, v142
	v_rcp_f32_e32 v143, v143
	v_mov_b32_dpp v133, v77 row_shr:1 row_mask:0xf bank_mask:0xf
	v_pk_fma_f32 v[144:145], v[164:165], v[128:129], v[144:145]
	v_mov_b32_dpp v194, v74 row_shr:1 row_mask:0xf bank_mask:0xf
	v_pk_fma_f32 v[132:133], v[160:161], v[132:133], v[144:145]
	v_pk_mul_f32 v[136:137], v[136:137], v[142:143]
	v_mov_b32_dpp v195, v75 row_shr:1 row_mask:0xf bank_mask:0xf
	v_pk_mul_f32 v[132:133], v[132:133], v[136:137]
	v_pk_fma_f32 v[136:137], v[90:91], v[186:187], v[190:191]
	v_mov_b32_dpp v138, v66 row_shr:1 row_mask:0xf bank_mask:0xf
	v_mov_b32_dpp v139, v67 row_shr:1 row_mask:0xf bank_mask:0xf
	v_pk_fma_f32 v[136:137], v[182:183], v[194:195], v[136:137]
	v_mov_b32_dpp v130, v86 row_shr:1 row_mask:0xf bank_mask:0xf
	v_pk_fma_f32 v[136:137], v[178:179], v[138:139], v[136:137]
	v_mov_b32_dpp v131, v87 row_shr:1 row_mask:0xf bank_mask:0xf
	v_exp_f32_e32 v139, v136
	v_exp_f32_e32 v142, v137
	v_cvt_pk_bf16_f32 v138, v132, v133
	v_add_f32_e32 v132, 1.0, v139
	v_rcp_f32_e32 v132, v132
	v_add_f32_e32 v133, 1.0, v142
	v_rcp_f32_e32 v133, v133
	v_pk_fma_f32 v[142:143], v[94:95], v[170:171], v[174:175]
	v_mov_b32_dpp v134, v78 row_shr:1 row_mask:0xf bank_mask:0xf
	v_mov_b32_dpp v135, v79 row_shr:1 row_mask:0xf bank_mask:0xf
	v_pk_mul_f32 v[132:133], v[136:137], v[132:133]
	v_pk_fma_f32 v[136:137], v[68:69], v[184:185], v[188:189]
	v_pk_fma_f32 v[142:143], v[166:167], v[130:131], v[142:143]
	v_pk_fma_f32 v[136:137], v[88:89], v[180:181], v[136:137]
	v_pk_fma_f32 v[134:135], v[162:163], v[134:135], v[142:143]
	v_pk_fma_f32 v[136:137], v[176:177], v[192:193], v[136:137]
	v_add_u32_e32 v146, 0x80, v245
	v_exp_f32_e32 v142, v136
	v_exp_f32_e32 v143, v137
	v_pk_mul_f32 v[132:133], v[134:135], v[132:133]
	v_mov_b64_e32 v[134:135], s[60:61]
	v_cvt_pk_bf16_f32 v139, v132, v133
	v_mad_i64_i32 v[132:133], s[34:35], v146, s63, v[134:135]
	v_lshl_add_u64 v[132:133], v[132:133], 0, v[204:205]
	v_mov_b32_e32 v144, v138
	v_mov_b32_e32 v145, v139
	v_add_f32_e32 v138, 1.0, v142
	v_add_f32_e32 v139, 1.0, v143
	v_rcp_f32_e32 v138, v138
	v_rcp_f32_e32 v139, v139
	v_pk_fma_f32 v[142:143], v[80:81], v[168:169], v[172:173]
	v_pk_fma_f32 v[72:73], v[72:73], v[184:185], v[188:189]
	v_pk_fma_f32 v[142:143], v[92:93], v[164:165], v[142:143]
	v_pk_mul_f32 v[136:137], v[136:137], v[138:139]
	v_pk_fma_f32 v[128:129], v[160:161], v[128:129], v[142:143]
	v_pk_fma_f32 v[84:85], v[84:85], v[168:169], v[172:173]
	v_pk_mul_f32 v[128:129], v[128:129], v[136:137]
	v_pk_fma_f32 v[136:137], v[70:71], v[186:187], v[190:191]
	s_nop 0
	v_pk_fma_f32 v[136:137], v[90:91], v[182:183], v[136:137]
	s_nop 0
	v_pk_fma_f32 v[136:137], v[178:179], v[194:195], v[136:137]
	s_nop 0
	v_exp_f32_e32 v139, v136
; #define LAS __attribute__((address_space(3)))
; __device__ __forceinline__ float sigmoidf_(float x) { return __builtin_amdgcn_rcpf(1.0f + __expf(-x)); }
;     __device__ __forceinline__ void operator()(AccRef acc, const Unit& u, int wr, int wc, int fr, int fq) const {
;     ...
;                 f32x4 h2v = (f32x4){0.f, 0.f, 0.f, 0.f}, h3v = h2v, h2g = h2v, h3g = h2v;
;                 const int pb = ai * 2 + wr - 1;
;                 if (pb >= 0 && fr == 0) { const LAS float* xp = xch + (pb * 2) * 256 + clb + 4 * n;
;                     h2v = *(const LAS f32x4*)(xp); h3v = *(const LAS f32x4*)(xp + 256); h2g = *(const LAS f32x4*)(xp + 128); h3g = *(const LAS f32x4*)(xp + 256 + 128); }
;                 float o[4][4];
; #pragma unroll
;                 for (int j = 0; j < 4; ++j) {
;                     const float v0 = acc[ai][0][0][n][j], v1 = acc[ai][0][1][n][j], v2 = acc[ai][0][2][n][j], v3 = acc[ai][0][3][n][j];
;                     const float g0 = acc[ai][1][0][n][j], g1 = acc[ai][1][1][n][j], g2 = acc[ai][1][2][n][j], g3 = acc[ai][1][3][n][j];
;                     const float pv3 = dpp_upd<0x111>(h3v[j], v3), pv2 = dpp_upd<0x111>(h2v[j], v2), pg3 = dpp_upd<0x111>(h3g[j], g3), pg2 = dpp_upd<0x111>(h2g[j], g2);
;                     const float hv0 = bvv[j] + w2v[j] * v0 + w1v[j] * pv3 + w0v[j] * pv2, hv1 = bvv[j] + w2v[j] * v1 + w1v[j] * v0 + w0v[j] * pv3;
;                     const float hv2 = bvv[j] + w2v[j] * v2 + w1v[j] * v1 + w0v[j] * v0, hv3 = bvv[j] + w2v[j] * v3 + w1v[j] * v2 + w0v[j] * v1;
;                     const float hg0 = bvg[j] + w2g[j] * g0 + w1g[j] * pg3 + w0g[j] * pg2, hg1 = bvg[j] + w2g[j] * g1 + w1g[j] * g0 + w0g[j] * pg3;
;                     const float hg2 = bvg[j] + w2g[j] * g2 + w1g[j] * g1 + w0g[j] * g0, hg3 = bvg[j] + w2g[j] * g3 + w1g[j] * g2 + w0g[j] * g1;
;                     o[0][j] = hg0 * sigmoidf_(hg0) * hv0; o[1][j] = hg1 * sigmoidf_(hg1) * hv1; o[2][j] = hg2 * sigmoidf_(hg2) * hv2; o[3][j] = hg3 * sigmoidf_(hg3) * hv3; }
; #pragma unroll
;                 for (int m = 0; m < 4; ++m) { u32x2 w; w.x = cvt_pk_bf16(o[m][0], o[m][1]); w.y = cvt_pk_bf16(o[m][2], o[m][3]);
;                     *(u32x2*)(Aout + (size_t)(row0 + ai * 128 + m) * FH + hc0 + 4 * n) = w; } } }
	v_exp_f32_e32 v142, v137
	v_cvt_pk_bf16_f32 v138, v128, v129
	v_add_f32_e32 v128, 1.0, v139
	v_rcp_f32_e32 v128, v128
	v_add_f32_e32 v129, 1.0, v142
	v_rcp_f32_e32 v129, v129
	v_pk_fma_f32 v[142:143], v[82:83], v[170:171], v[174:175]
	v_pk_mul_f32 v[128:129], v[136:137], v[128:129]
	v_pk_fma_f32 v[142:143], v[94:95], v[166:167], v[142:143]
	v_pk_fma_f32 v[136:137], v[76:77], v[168:169], v[172:173]
	v_pk_fma_f32 v[130:131], v[162:163], v[130:131], v[142:143]
	v_pk_fma_f32 v[136:137], v[80:81], v[164:165], v[136:137]
	v_pk_mul_f32 v[128:129], v[130:131], v[128:129]
	v_pk_fma_f32 v[130:131], v[64:65], v[184:185], v[188:189]
	v_pk_fma_f32 v[64:65], v[64:65], v[180:181], v[72:73]
	v_pk_fma_f32 v[130:131], v[68:69], v[180:181], v[130:131]
	v_pk_fma_f32 v[64:65], v[68:69], v[176:177], v[64:65]
	v_pk_fma_f32 v[88:89], v[88:89], v[176:177], v[130:131]
	v_pk_fma_f32 v[92:93], v[92:93], v[160:161], v[136:137]
	v_exp_f32_e32 v130, v88
	v_exp_f32_e32 v131, v89
	v_exp_f32_e32 v72, v64
	v_add_f32_e32 v130, 1.0, v130
	v_add_f32_e32 v131, 1.0, v131
	v_rcp_f32_e32 v130, v130
	v_rcp_f32_e32 v131, v131
	v_pk_fma_f32 v[68:69], v[74:75], v[186:187], v[190:191]
	v_exp_f32_e32 v73, v65
	v_pk_mul_f32 v[88:89], v[88:89], v[130:131]
	v_add_f32_e32 v72, 1.0, v72
	v_pk_mul_f32 v[88:89], v[92:93], v[88:89]
	v_pk_fma_f32 v[92:93], v[66:67], v[186:187], v[190:191]
	v_pk_fma_f32 v[66:67], v[66:67], v[182:183], v[68:69]
	v_pk_fma_f32 v[92:93], v[70:71], v[182:183], v[92:93]
	v_pk_fma_f32 v[66:67], v[70:71], v[178:179], v[66:67]
	v_pk_fma_f32 v[90:91], v[90:91], v[178:179], v[92:93]
	v_exp_f32_e32 v93, v90
	v_exp_f32_e32 v68, v66
	v_exp_f32_e32 v69, v67
	v_exp_f32_e32 v130, v91
	v_add_f32_e32 v73, 1.0, v73
	v_add_f32_e32 v68, 1.0, v68
	v_add_f32_e32 v69, 1.0, v69
	v_cvt_pk_bf16_f32 v92, v88, v89
	v_add_f32_e32 v88, 1.0, v93
	v_add_f32_e32 v89, 1.0, v130
	v_rcp_f32_e32 v72, v72
	v_rcp_f32_e32 v73, v73
	v_rcp_f32_e32 v68, v68
	v_rcp_f32_e32 v69, v69
	v_rcp_f32_e32 v88, v88
	v_rcp_f32_e32 v89, v89
	v_pk_fma_f32 v[74:75], v[86:87], v[170:171], v[174:175]
	v_pk_fma_f32 v[130:131], v[78:79], v[170:171], v[174:175]
	v_pk_fma_f32 v[76:77], v[76:77], v[164:165], v[84:85]
	v_pk_fma_f32 v[70:71], v[78:79], v[166:167], v[74:75]
	v_pk_fma_f32 v[130:131], v[82:83], v[166:167], v[130:131]
	v_pk_fma_f32 v[76:77], v[80:81], v[160:161], v[76:77]
	v_pk_mul_f32 v[64:65], v[64:65], v[72:73]
	v_pk_fma_f32 v[70:71], v[82:83], v[162:163], v[70:71]
	v_pk_mul_f32 v[66:67], v[66:67], v[68:69]
	v_pk_fma_f32 v[94:95], v[94:95], v[162:163], v[130:131]
	v_pk_mul_f32 v[88:89], v[90:91], v[88:89]
	v_pk_mul_f32 v[64:65], v[76:77], v[64:65]
	v_pk_mul_f32 v[66:67], v[70:71], v[66:67]
	v_pk_mul_f32 v[88:89], v[94:95], v[88:89]
	v_cvt_pk_bf16_f32 v64, v64, v65
	v_cvt_pk_bf16_f32 v65, v66, v67
	v_add_u32_e32 v66, 0x83, v245
	v_cvt_pk_bf16_f32 v139, v128, v129
	v_add_u32_e32 v128, 0x81, v245
	v_cvt_pk_bf16_f32 v93, v88, v89
	v_add_u32_e32 v88, 0x82, v245
	v_mad_i64_i32 v[66:67], s[34:35], v66, s63, v[134:135]
	v_mad_i64_i32 v[128:129], s[34:35], v128, s63, v[134:135]
	v_mad_i64_i32 v[88:89], s[34:35], v88, s63, v[134:135]
	v_lshl_add_u64 v[82:83], v[66:67], 0, v[204:205]
	v_lshl_add_u64 v[128:129], v[128:129], 0, v[204:205]
	v_lshl_add_u64 v[88:89], v[88:89], 0, v[204:205]
	v_mov_b32_e32 v148, v64
	v_mov_b32_e32 v149, v65
	v_mov_b32_e32 v64, 0
	v_mov_b32_e32 v70, 0
	v_mov_b32_e32 v71, 0
	v_mov_b32_e32 v72, 0
	v_mov_b32_e32 v73, 0
	v_mov_b32_e32 v78, 0
	v_mov_b32_e32 v79, 0
	v_mov_b32_e32 v80, 0
	v_mov_b32_e32 v81, 0
	v_mov_b32_e32 v66, 0
	v_mov_b32_e32 v67, 0
	v_mov_b32_e32 v68, 0
	v_mov_b32_e32 v69, 0
	v_mov_b32_e32 v74, 0
	v_mov_b32_e32 v75, 0
	v_mov_b32_e32 v76, 0
	v_mov_b32_e32 v77, 0
	v_mov_b32_e32 v154, v138
	v_mov_b32_e32 v155, v139
	v_mov_b32_e32 v198, v92
	v_mov_b32_e32 v199, v93
	s_and_saveexec_b64 s[34:35], s[20:21]
	s_cbranch_execz .LBB0_1953
	ds_read_b128 v[74:77], v241
	ds_read_b128 v[66:69], v240
	ds_read_b128 v[78:81], v239
	ds_read_b128 v[70:73], v238
.LBB0_1953:
	s_or_b64 exec, exec, s[34:35]
	s_waitcnt lgkmcnt(0)
	v_mov_b32_dpp v70, v44 row_shr:1 row_mask:0xf bank_mask:0xf
	v_mov_b32_dpp v71, v45 row_shr:1 row_mask:0xf bank_mask:0xf
	s_waitcnt vmcnt(0)
; #define LAS __attribute__((address_space(3)))
; __device__ __forceinline__ float sigmoidf_(float x) { return __builtin_amdgcn_rcpf(1.0f + __expf(-x)); }
;     __device__ __forceinline__ void operator()(AccRef acc, const Unit& u, int wr, int wc, int fr, int fq) const {
;     ...
;                 f32x4 h2v = (f32x4){0.f, 0.f, 0.f, 0.f}, h3v = h2v, h2g = h2v, h3g = h2v;
;                 const int pb = ai * 2 + wr - 1;
;                 if (pb >= 0 && fr == 0) { const LAS float* xp = xch + (pb * 2) * 256 + clb + 4 * n;
;                     h2v = *(const LAS f32x4*)(xp); h3v = *(const LAS f32x4*)(xp + 256); h2g = *(const LAS f32x4*)(xp + 128); h3g = *(const LAS f32x4*)(xp + 256 + 128); }
;                 float o[4][4];
; #pragma unroll
;                 for (int j = 0; j < 4; ++j) {
;                     const float v0 = acc[ai][0][0][n][j], v1 = acc[ai][0][1][n][j], v2 = acc[ai][0][2][n][j], v3 = acc[ai][0][3][n][j];
;                     const float g0 = acc[ai][1][0][n][j], g1 = acc[ai][1][1][n][j], g2 = acc[ai][1][2][n][j], g3 = acc[ai][1][3][n][j];
;                     const float pv3 = dpp_upd<0x111>(h3v[j], v3), pv2 = dpp_upd<0x111>(h2v[j], v2), pg3 = dpp_upd<0x111>(h3g[j], g3), pg2 = dpp_upd<0x111>(h2g[j], g2);
;                     const float hv0 = bvv[j] + w2v[j] * v0 + w1v[j] * pv3 + w0v[j] * pv2, hv1 = bvv[j] + w2v[j] * v1 + w1v[j] * v0 + w0v[j] * pv3;
;                     const float hv2 = bvv[j] + w2v[j] * v2 + w1v[j] * v1 + w0v[j] * v0, hv3 = bvv[j] + w2v[j] * v3 + w1v[j] * v2 + w0v[j] * v1;
;                     const float hg0 = bvg[j] + w2g[j] * g0 + w1g[j] * pg3 + w0g[j] * pg2, hg1 = bvg[j] + w2g[j] * g1 + w1g[j] * g0 + w0g[j] * pg3;
;                     const float hg2 = bvg[j] + w2g[j] * g2 + w1g[j] * g1 + w0g[j] * g0, hg3 = bvg[j] + w2g[j] * g3 + w1g[j] * g2 + w0g[j] * g1;
;                     o[0][j] = hg0 * sigmoidf_(hg0) * hv0; o[1][j] = hg1 * sigmoidf_(hg1) * hv1; o[2][j] = hg2 * sigmoidf_(hg2) * hv2; o[3][j] = hg3 * sigmoidf_(hg3) * hv3; }
; #pragma unroll
;                 for (int m = 0; m < 4; ++m) { u32x2 w; w.x = cvt_pk_bf16(o[m][0], o[m][1]); w.y = cvt_pk_bf16(o[m][2], o[m][3]);
;                     *(u32x2*)(Aout + (size_t)(row0 + ai * 128 + m) * FH + hc0 + 4 * n) = w; } } }
	v_pk_fma_f32 v[84:85], v[56:57], v[120:121], v[124:125]
	v_mov_b32_dpp v78, v32 row_shr:1 row_mask:0xf bank_mask:0xf
	v_mov_b32_dpp v79, v33 row_shr:1 row_mask:0xf bank_mask:0xf
	v_pk_fma_f32 v[84:85], v[116:117], v[70:71], v[84:85]
	v_mov_b32_dpp v66, v52 row_shr:1 row_mask:0xf bank_mask:0xf
	v_pk_fma_f32 v[78:79], v[112:113], v[78:79], v[84:85]
	v_mov_b32_dpp v67, v53 row_shr:1 row_mask:0xf bank_mask:0xf
	v_exp_f32_e32 v65, v78
	v_exp_f32_e32 v85, v79
	v_pk_fma_f32 v[86:87], v[60:61], v[104:105], v[108:109]
	v_add_f32_e32 v65, 1.0, v65
	v_rcp_f32_e32 v84, v65
	v_add_f32_e32 v65, 1.0, v85
	v_rcp_f32_e32 v85, v65
	v_mov_b32_dpp v74, v40 row_shr:1 row_mask:0xf bank_mask:0xf
	v_mov_b32_dpp v75, v41 row_shr:1 row_mask:0xf bank_mask:0xf
	v_pk_fma_f32 v[86:87], v[100:101], v[66:67], v[86:87]
	v_pk_mul_f32 v[78:79], v[78:79], v[84:85]
	v_pk_fma_f32 v[74:75], v[96:97], v[74:75], v[86:87]
	v_mov_b32_dpp v72, v46 row_shr:1 row_mask:0xf bank_mask:0xf
	v_mov_b32_dpp v73, v47 row_shr:1 row_mask:0xf bank_mask:0xf
	v_pk_mul_f32 v[74:75], v[74:75], v[78:79]
	v_pk_fma_f32 v[78:79], v[58:59], v[122:123], v[126:127]
	v_mov_b32_dpp v80, v34 row_shr:1 row_mask:0xf bank_mask:0xf
	v_mov_b32_dpp v81, v35 row_shr:1 row_mask:0xf bank_mask:0xf
	v_pk_fma_f32 v[78:79], v[118:119], v[72:73], v[78:79]
	v_mov_b32_dpp v68, v54 row_shr:1 row_mask:0xf bank_mask:0xf
	v_pk_fma_f32 v[78:79], v[114:115], v[80:81], v[78:79]
	v_mov_b32_dpp v69, v55 row_shr:1 row_mask:0xf bank_mask:0xf
	v_exp_f32_e32 v65, v78
	v_exp_f32_e32 v81, v79
	v_pk_fma_f32 v[84:85], v[62:63], v[106:107], v[110:111]
	v_add_f32_e32 v65, 1.0, v65
	v_rcp_f32_e32 v80, v65
	v_add_f32_e32 v65, 1.0, v81
	v_rcp_f32_e32 v81, v65
	v_mov_b32_dpp v76, v42 row_shr:1 row_mask:0xf bank_mask:0xf
	v_mov_b32_dpp v77, v43 row_shr:1 row_mask:0xf bank_mask:0xf
	v_pk_fma_f32 v[84:85], v[102:103], v[68:69], v[84:85]
	v_pk_mul_f32 v[78:79], v[78:79], v[80:81]
	v_pk_fma_f32 v[76:77], v[98:99], v[76:77], v[84:85]
	v_cvt_pk_bf16_f32 v74, v74, v75
	v_pk_mul_f32 v[76:77], v[76:77], v[78:79]
	v_pk_fma_f32 v[44:45], v[44:45], v[120:121], v[124:125]
	v_cvt_pk_bf16_f32 v75, v76, v77
	v_pk_fma_f32 v[76:77], v[36:37], v[120:121], v[124:125]
	v_mov_b32_e32 v90, v246
	v_mov_b32_e32 v91, v247
	v_mov_b32_e32 v92, v74
	v_mov_b32_e32 v93, v75
	global_store_dwordx4 v[202:203], v[90:93], off
	v_pk_fma_f32 v[76:77], v[56:57], v[116:117], v[76:77]
	v_pk_fma_f32 v[52:53], v[52:53], v[104:105], v[108:109]
	v_pk_fma_f32 v[70:71], v[112:113], v[70:71], v[76:77]
	s_nop 0
	v_exp_f32_e32 v65, v70
	v_exp_f32_e32 v76, v71
	v_add_f32_e32 v65, 1.0, v65
	v_rcp_f32_e32 v74, v65
	v_add_f32_e32 v65, 1.0, v76
	v_rcp_f32_e32 v75, v65
	v_pk_fma_f32 v[76:77], v[48:49], v[104:105], v[108:109]
	v_pk_mul_f32 v[70:71], v[70:71], v[74:75]
	v_pk_fma_f32 v[76:77], v[60:61], v[100:101], v[76:77]
	v_pk_fma_f32 v[74:75], v[50:51], v[106:107], v[110:111]
	v_pk_fma_f32 v[66:67], v[96:97], v[66:67], v[76:77]
	v_pk_fma_f32 v[74:75], v[62:63], v[102:103], v[74:75]
	v_pk_mul_f32 v[66:67], v[66:67], v[70:71]
	v_pk_fma_f32 v[70:71], v[38:39], v[122:123], v[126:127]
	v_pk_fma_f32 v[68:69], v[98:99], v[68:69], v[74:75]
	v_pk_fma_f32 v[70:71], v[58:59], v[118:119], v[70:71]
	v_cvt_pk_bf16_f32 v66, v66, v67
	v_pk_fma_f32 v[70:71], v[114:115], v[72:73], v[70:71]
	s_nop 0
	v_exp_f32_e32 v65, v70
	v_exp_f32_e32 v73, v71
	v_add_f32_e32 v65, 1.0, v65
	v_rcp_f32_e32 v72, v65
	v_add_f32_e32 v65, 1.0, v73
	v_rcp_f32_e32 v73, v65
	s_nop 0
	v_pk_mul_f32 v[70:71], v[70:71], v[72:73]
	s_nop 0
	v_pk_mul_f32 v[68:69], v[68:69], v[70:71]
	s_nop 0
	v_cvt_pk_bf16_f32 v67, v68, v69
	v_pk_fma_f32 v[68:69], v[32:33], v[120:121], v[124:125]
	v_mov_b32_e32 v134, v248
	v_mov_b32_e32 v135, v249
	v_mov_b32_e32 v136, v66
	v_mov_b32_e32 v137, v67
	global_store_dwordx4 v[196:197], v[134:137], off
	v_pk_fma_f32 v[68:69], v[36:37], v[116:117], v[68:69]
	v_pk_fma_f32 v[32:33], v[32:33], v[116:117], v[44:45]
	v_pk_fma_f32 v[56:57], v[56:57], v[112:113], v[68:69]
	v_pk_fma_f32 v[32:33], v[36:37], v[112:113], v[32:33]
	v_exp_f32_e32 v65, v56
	v_exp_f32_e32 v68, v57
	v_add_f32_e32 v65, 1.0, v65
	v_rcp_f32_e32 v66, v65
	v_add_f32_e32 v65, 1.0, v68
	v_rcp_f32_e32 v67, v65
	v_pk_fma_f32 v[68:69], v[40:41], v[104:105], v[108:109]
	v_exp_f32_e32 v44, v32
	v_pk_fma_f32 v[68:69], v[48:49], v[100:101], v[68:69]
	v_pk_mul_f32 v[56:57], v[56:57], v[66:67]
	v_pk_fma_f32 v[60:61], v[60:61], v[96:97], v[68:69]
	v_pk_fma_f32 v[36:37], v[46:47], v[122:123], v[126:127]
	v_pk_mul_f32 v[56:57], v[60:61], v[56:57]
	v_pk_fma_f32 v[60:61], v[34:35], v[122:123], v[126:127]
	v_pk_fma_f32 v[34:35], v[34:35], v[118:119], v[36:37]
	v_pk_fma_f32 v[60:61], v[38:39], v[118:119], v[60:61]
	v_pk_fma_f32 v[34:35], v[38:39], v[114:115], v[34:35]
	v_pk_fma_f32 v[58:59], v[58:59], v[114:115], v[60:61]
	v_exp_f32_e32 v60, v58
	v_exp_f32_e32 v45, v33
	v_exp_f32_e32 v36, v34
	v_exp_f32_e32 v37, v35
	v_exp_f32_e32 v61, v59
	v_cvt_pk_bf16_f32 v56, v56, v57
	v_add_f32_e32 v57, 1.0, v60
	v_add_f32_e32 v44, 1.0, v44
	v_add_f32_e32 v45, 1.0, v45
	v_add_f32_e32 v36, 1.0, v36
	v_add_f32_e32 v37, 1.0, v37
	v_rcp_f32_e32 v60, v57
	v_add_f32_e32 v57, 1.0, v61
	v_rcp_f32_e32 v44, v44
	v_rcp_f32_e32 v45, v45
	v_rcp_f32_e32 v36, v36
	v_rcp_f32_e32 v37, v37
	v_rcp_f32_e32 v61, v57
	v_pk_fma_f32 v[46:47], v[54:55], v[106:107], v[110:111]
	v_pk_fma_f32 v[66:67], v[42:43], v[106:107], v[110:111]
	v_pk_fma_f32 v[40:41], v[40:41], v[100:101], v[52:53]
	v_pk_fma_f32 v[38:39], v[42:43], v[102:103], v[46:47]
	v_pk_fma_f32 v[66:67], v[50:51], v[102:103], v[66:67]
	v_pk_fma_f32 v[40:41], v[48:49], v[96:97], v[40:41]
	v_pk_mul_f32 v[32:33], v[32:33], v[44:45]
	v_pk_fma_f32 v[38:39], v[50:51], v[98:99], v[38:39]
	v_pk_mul_f32 v[34:35], v[34:35], v[36:37]
	v_pk_fma_f32 v[62:63], v[62:63], v[98:99], v[66:67]
	v_pk_mul_f32 v[58:59], v[58:59], v[60:61]
	v_pk_mul_f32 v[32:33], v[40:41], v[32:33]
	v_pk_mul_f32 v[34:35], v[38:39], v[34:35]
	v_pk_mul_f32 v[58:59], v[62:63], v[58:59]
	v_cvt_pk_bf16_f32 v32, v32, v33
	v_cvt_pk_bf16_f32 v33, v34, v35
	v_cvt_pk_bf16_f32 v57, v58, v59
	v_mov_b32_e32 v158, v250
	v_mov_b32_e32 v159, v251
	v_mov_b32_e32 v160, v32
	v_mov_b32_e32 v161, v33
	global_store_dwordx4 v[140:141], v[158:161], off
	v_mov_b32_e32 v65, 0
	v_mov_b32_e32 v66, 0
	v_mov_b32_e32 v67, 0
	v_mov_b32_e32 v40, 0
	v_mov_b32_e32 v41, 0
	v_mov_b32_e32 v42, 0
	v_mov_b32_e32 v43, 0
	v_mov_b32_e32 v32, 0
	v_mov_b32_e32 v33, 0
	v_mov_b32_e32 v34, 0
	v_mov_b32_e32 v35, 0
	v_mov_b32_e32 v36, 0
	v_mov_b32_e32 v37, 0
	v_mov_b32_e32 v38, 0
	v_mov_b32_e32 v39, 0
	v_mov_b32_e32 v162, v253
	v_mov_b32_e32 v163, v254
	v_mov_b32_e32 v164, v56
	v_mov_b32_e32 v165, v57
	global_store_dwordx4 v[152:153], v[162:165], off
	s_and_saveexec_b64 s[34:35], s[22:23]
	s_cbranch_execz .LBB0_1936
	ds_read_b128 v[36:39], v236 offset:2064
	ds_read_b128 v[40:43], v236 offset:2576
	ds_read_b128 v[32:35], v236 offset:3088
	ds_read_b128 v[64:67], v236 offset:3600
	s_branch .LBB0_1936
